# O9S with the two waits before every segment barrier merged into one s_waitcnt vmcnt(8) lgkmcnt(0) (40 sites)
# speedup vs baseline: 1.0060x; 1.0041x over previous
.LBB0_170:
	ds_read_b128 v[136:139], v191
	ds_read_b128 v[158:161], v191 offset:1024
	ds_read_b128 v[162:165], v191 offset:2048
	ds_read_b128 v[166:169], v191 offset:3072
	ds_read_b128 v[170:173], v192
	ds_read_b128 v[174:177], v192 offset:1024
	ds_read_b128 v[178:181], v192 offset:2048
	ds_read_b128 v[194:197], v192 offset:3072
	s_add_u32 s0, s42, 0xfff00080
	s_addc_u32 s50, s43, -1
	s_cmp_eq_u32 s70, 60
	s_cselect_b32 s53, s23, s50
	s_cselect_b32 s52, s41, s0
	s_cselect_b32 s51, s21, s68
	s_cselect_b32 s50, s66, s67
	s_add_i32 m0, s31, 0xc000
	ds_read_b128 v[198:201], v193
	ds_read_b128 v[202:205], v193 offset:1024
	ds_read_b128 v[206:209], v193 offset:2048
	ds_read_b128 v[210:213], v193 offset:3072
	ds_read_b128 v[214:217], v193 offset:4096
	ds_read_b128 v[218:221], v193 offset:5120
	ds_read_b128 v[222:225], v193 offset:6144
	ds_read_b128 v[226:229], v193 offset:7168
	global_load_lds_dwordx4 v152, s[42:43]
	s_add_i32 m0, s31, 0xe000
	s_nop 0
	global_load_lds_dwordx4 v154, s[42:43]
	s_waitcnt vmcnt(8) lgkmcnt(0)
	s_setprio 1
	s_barrier
	v_mfma_f32_16x16x32_bf16 v[132:135], v[136:139], v[198:201], v[132:135]
	v_mfma_f32_16x16x32_bf16 v[132:135], v[158:161], v[202:205], v[132:135]
	v_mfma_f32_16x16x32_bf16 v[128:131], v[162:165], v[198:201], v[128:131]
	v_mfma_f32_16x16x32_bf16 v[128:131], v[166:169], v[202:205], v[128:131]
	v_mfma_f32_16x16x32_bf16 v[124:127], v[170:173], v[198:201], v[124:127]
	v_mfma_f32_16x16x32_bf16 v[124:127], v[174:177], v[202:205], v[124:127]
	v_mfma_f32_16x16x32_bf16 v[120:123], v[178:181], v[198:201], v[120:123]
	v_mfma_f32_16x16x32_bf16 v[120:123], v[194:197], v[202:205], v[120:123]
	v_mfma_f32_16x16x32_bf16 v[104:107], v[178:181], v[206:209], v[104:107]
	v_mfma_f32_16x16x32_bf16 v[104:107], v[194:197], v[210:213], v[104:107]
	v_mfma_f32_16x16x32_bf16 v[108:111], v[170:173], v[206:209], v[108:111]
	v_mfma_f32_16x16x32_bf16 v[108:111], v[174:177], v[210:213], v[108:111]
	v_mfma_f32_16x16x32_bf16 v[112:115], v[162:165], v[206:209], v[112:115]
	v_mfma_f32_16x16x32_bf16 v[112:115], v[166:169], v[210:213], v[112:115]
	v_mfma_f32_16x16x32_bf16 v[116:119], v[136:139], v[206:209], v[116:119]
	v_mfma_f32_16x16x32_bf16 v[116:119], v[158:161], v[210:213], v[116:119]
	v_mfma_f32_16x16x32_bf16 v[100:103], v[136:139], v[214:217], v[100:103]
	v_mfma_f32_16x16x32_bf16 v[100:103], v[158:161], v[218:221], v[100:103]
	v_mfma_f32_16x16x32_bf16 v[96:99], v[162:165], v[214:217], v[96:99]
	v_mfma_f32_16x16x32_bf16 v[96:99], v[166:169], v[218:221], v[96:99]
	v_mfma_f32_16x16x32_bf16 v[92:95], v[170:173], v[214:217], v[92:95]
	v_mfma_f32_16x16x32_bf16 v[92:95], v[174:177], v[218:221], v[92:95]
	v_mfma_f32_16x16x32_bf16 v[88:91], v[178:181], v[214:217], v[88:91]
	v_mfma_f32_16x16x32_bf16 v[88:91], v[194:197], v[218:221], v[88:91]
	v_mfma_f32_16x16x32_bf16 v[72:75], v[178:181], v[222:225], v[72:75]
	v_mfma_f32_16x16x32_bf16 v[72:75], v[194:197], v[226:229], v[72:75]
	v_mfma_f32_16x16x32_bf16 v[76:79], v[170:173], v[222:225], v[76:79]
	v_mfma_f32_16x16x32_bf16 v[76:79], v[174:177], v[226:229], v[76:79]
	v_mfma_f32_16x16x32_bf16 v[80:83], v[162:165], v[222:225], v[80:83]
	v_mfma_f32_16x16x32_bf16 v[80:83], v[166:169], v[226:229], v[80:83]
	v_mfma_f32_16x16x32_bf16 v[84:87], v[136:139], v[222:225], v[84:87]
	v_mfma_f32_16x16x32_bf16 v[84:87], v[158:161], v[226:229], v[84:87]
	s_setprio 0
	s_barrier
	s_add_i32 s0, s61, s19
	s_mov_b32 m0, s0
	ds_read_b128 v[198:201], v193 offset:16384
	ds_read_b128 v[202:205], v193 offset:17408
	ds_read_b128 v[206:209], v193 offset:18432
	ds_read_b128 v[210:213], v193 offset:19456
	ds_read_b128 v[214:217], v193 offset:20480
	ds_read_b128 v[218:221], v193 offset:21504
	ds_read_b128 v[222:225], v193 offset:22528
	ds_read_b128 v[226:229], v193 offset:23552
	global_load_lds_dwordx4 v142, s[50:51]
	s_add_i32 m0, s0, 0x2000
	s_add_u32 s72, s50, 0x100000
	s_addc_u32 s73, s51, 0
	s_add_i32 s0, s62, s19
	global_load_lds_dwordx4 v146, s[50:51]
	s_mov_b32 m0, s0
	s_nop 0
	global_load_lds_dwordx4 v142, s[72:73]
	s_add_i32 m0, s0, 0x2000
	s_nop 0
	global_load_lds_dwordx4 v146, s[72:73]
	s_mov_b32 m0, s31
	s_nop 0
	global_load_lds_dwordx4 v140, s[52:53]
	s_mov_b32 m0, s35
	s_nop 0
	global_load_lds_dwordx4 v144, s[52:53]
	s_waitcnt vmcnt(8) lgkmcnt(0)
	s_setprio 1
	s_barrier
	v_mfma_f32_16x16x32_bf16 v[68:71], v[136:139], v[198:201], v[68:71]
	v_mfma_f32_16x16x32_bf16 v[68:71], v[158:161], v[202:205], v[68:71]
	v_mfma_f32_16x16x32_bf16 v[64:67], v[162:165], v[198:201], v[64:67]
	v_mfma_f32_16x16x32_bf16 v[64:67], v[166:169], v[202:205], v[64:67]
	v_mfma_f32_16x16x32_bf16 v[60:63], v[170:173], v[198:201], v[60:63]
	v_mfma_f32_16x16x32_bf16 v[60:63], v[174:177], v[202:205], v[60:63]
	v_mfma_f32_16x16x32_bf16 v[56:59], v[178:181], v[198:201], v[56:59]
	v_mfma_f32_16x16x32_bf16 v[56:59], v[194:197], v[202:205], v[56:59]
	v_mfma_f32_16x16x32_bf16 v[40:43], v[178:181], v[206:209], v[40:43]
	v_mfma_f32_16x16x32_bf16 v[40:43], v[194:197], v[210:213], v[40:43]
	v_mfma_f32_16x16x32_bf16 v[44:47], v[170:173], v[206:209], v[44:47]
	v_mfma_f32_16x16x32_bf16 v[44:47], v[174:177], v[210:213], v[44:47]
	v_mfma_f32_16x16x32_bf16 v[48:51], v[162:165], v[206:209], v[48:51]
	v_mfma_f32_16x16x32_bf16 v[48:51], v[166:169], v[210:213], v[48:51]
	v_mfma_f32_16x16x32_bf16 v[52:55], v[136:139], v[206:209], v[52:55]
	v_mfma_f32_16x16x32_bf16 v[52:55], v[158:161], v[210:213], v[52:55]
	v_mfma_f32_16x16x32_bf16 v[36:39], v[136:139], v[214:217], v[36:39]
	v_mfma_f32_16x16x32_bf16 v[36:39], v[158:161], v[218:221], v[36:39]
	v_mfma_f32_16x16x32_bf16 v[32:35], v[162:165], v[214:217], v[32:35]
	v_mfma_f32_16x16x32_bf16 v[32:35], v[166:169], v[218:221], v[32:35]
	v_mfma_f32_16x16x32_bf16 v[28:31], v[170:173], v[214:217], v[28:31]
	v_mfma_f32_16x16x32_bf16 v[28:31], v[174:177], v[218:221], v[28:31]
	v_mfma_f32_16x16x32_bf16 v[24:27], v[178:181], v[214:217], v[24:27]
	v_mfma_f32_16x16x32_bf16 v[24:27], v[194:197], v[218:221], v[24:27]
	v_mfma_f32_16x16x32_bf16 v[6:9], v[178:181], v[222:225], v[8:11]
	v_mfma_f32_16x16x32_bf16 v[6:9], v[194:197], v[226:229], v[6:9]
	v_mfma_f32_16x16x32_bf16 v[12:15], v[170:173], v[222:225], v[12:15]
	v_mfma_f32_16x16x32_bf16 v[12:15], v[174:177], v[226:229], v[12:15]
	v_mfma_f32_16x16x32_bf16 v[16:19], v[162:165], v[222:225], v[16:19]
	v_mfma_f32_16x16x32_bf16 v[16:19], v[166:169], v[226:229], v[16:19]
	v_mfma_f32_16x16x32_bf16 v[20:23], v[136:139], v[222:225], v[20:23]
	v_mfma_f32_16x16x32_bf16 v[20:23], v[158:161], v[226:229], v[20:23]
	s_setprio 0
	s_barrier
	s_add_i32 s0, 0, 0x18000
	v_add_u32_e32 v5, s0, v1
	s_add_i32 s71, 0, 0x1c000
	ds_read_b128 v[136:139], v5
	ds_read_b128 v[158:161], v5 offset:1024
	ds_read_b128 v[162:165], v5 offset:2048
	ds_read_b128 v[166:169], v5 offset:3072
	v_add_u32_e32 v5, s71, v1
	ds_read_b128 v[170:173], v5
	ds_read_b128 v[174:177], v5 offset:1024
	ds_read_b128 v[178:181], v5 offset:2048
	ds_read_b128 v[194:197], v5 offset:3072
	s_add_u32 s98, s52, 0x100000
	s_addc_u32 s99, s53, 0
	s_mov_b32 m0, s45
	ds_read_b128 v[198:201], v193 offset:32768
	ds_read_b128 v[202:205], v193 offset:33792
	ds_read_b128 v[206:209], v193 offset:34816
	ds_read_b128 v[210:213], v193 offset:35840
	ds_read_b128 v[214:217], v193 offset:36864
	ds_read_b128 v[218:221], v193 offset:37888
	ds_read_b128 v[222:225], v193 offset:38912
	ds_read_b128 v[226:229], v193 offset:39936
	global_load_lds_dwordx4 v140, s[98:99]
	s_mov_b32 m0, s46
	s_nop 0
	global_load_lds_dwordx4 v144, s[98:99]
	s_waitcnt vmcnt(8) lgkmcnt(0)
	s_setprio 1
	s_barrier
	v_mfma_f32_16x16x32_bf16 v[132:135], v[136:139], v[198:201], v[132:135]
	v_mfma_f32_16x16x32_bf16 v[132:135], v[158:161], v[202:205], v[132:135]
	v_mfma_f32_16x16x32_bf16 v[128:131], v[162:165], v[198:201], v[128:131]
	v_mfma_f32_16x16x32_bf16 v[128:131], v[166:169], v[202:205], v[128:131]
	v_mfma_f32_16x16x32_bf16 v[124:127], v[170:173], v[198:201], v[124:127]
	v_mfma_f32_16x16x32_bf16 v[124:127], v[174:177], v[202:205], v[124:127]
	v_mfma_f32_16x16x32_bf16 v[120:123], v[178:181], v[198:201], v[120:123]
	v_mfma_f32_16x16x32_bf16 v[120:123], v[194:197], v[202:205], v[120:123]
	v_mfma_f32_16x16x32_bf16 v[104:107], v[178:181], v[206:209], v[104:107]
	v_mfma_f32_16x16x32_bf16 v[104:107], v[194:197], v[210:213], v[104:107]
	v_mfma_f32_16x16x32_bf16 v[108:111], v[170:173], v[206:209], v[108:111]
	v_mfma_f32_16x16x32_bf16 v[108:111], v[174:177], v[210:213], v[108:111]
	v_mfma_f32_16x16x32_bf16 v[112:115], v[162:165], v[206:209], v[112:115]
	v_mfma_f32_16x16x32_bf16 v[112:115], v[166:169], v[210:213], v[112:115]
	v_mfma_f32_16x16x32_bf16 v[116:119], v[136:139], v[206:209], v[116:119]
	v_mfma_f32_16x16x32_bf16 v[116:119], v[158:161], v[210:213], v[116:119]
	v_mfma_f32_16x16x32_bf16 v[100:103], v[136:139], v[214:217], v[100:103]
	v_mfma_f32_16x16x32_bf16 v[100:103], v[158:161], v[218:221], v[100:103]
	v_mfma_f32_16x16x32_bf16 v[96:99], v[162:165], v[214:217], v[96:99]
	v_mfma_f32_16x16x32_bf16 v[96:99], v[166:169], v[218:221], v[96:99]
	v_mfma_f32_16x16x32_bf16 v[92:95], v[170:173], v[214:217], v[92:95]
	v_mfma_f32_16x16x32_bf16 v[92:95], v[174:177], v[218:221], v[92:95]
	v_mfma_f32_16x16x32_bf16 v[88:91], v[178:181], v[214:217], v[88:91]
	v_mfma_f32_16x16x32_bf16 v[88:91], v[194:197], v[218:221], v[88:91]
	v_mfma_f32_16x16x32_bf16 v[72:75], v[178:181], v[222:225], v[72:75]
	v_mfma_f32_16x16x32_bf16 v[72:75], v[194:197], v[226:229], v[72:75]
	v_mfma_f32_16x16x32_bf16 v[76:79], v[170:173], v[222:225], v[76:79]
	v_mfma_f32_16x16x32_bf16 v[76:79], v[174:177], v[226:229], v[76:79]
	v_mfma_f32_16x16x32_bf16 v[80:83], v[162:165], v[222:225], v[80:83]
	v_mfma_f32_16x16x32_bf16 v[80:83], v[166:169], v[226:229], v[80:83]
	v_mfma_f32_16x16x32_bf16 v[84:87], v[136:139], v[222:225], v[84:87]
	v_mfma_f32_16x16x32_bf16 v[84:87], v[158:161], v[226:229], v[84:87]
	s_setprio 0
	s_barrier
	s_add_i32 s0, s0, s19
	s_add_i32 m0, s0, 0xffffff80
	ds_read_b128 v[198:201], v193 offset:49152
	ds_read_b128 v[202:205], v193 offset:50176
	ds_read_b128 v[206:209], v193 offset:51200
	ds_read_b128 v[210:213], v193 offset:52224
	ds_read_b128 v[214:217], v193 offset:53248
	ds_read_b128 v[218:221], v193 offset:54272
	ds_read_b128 v[222:225], v193 offset:55296
	ds_read_b128 v[226:229], v193 offset:56320
	global_load_lds_dwordx4 v142, s[50:51] offset:128
	s_add_i32 m0, s0, 0x1f80
	s_add_i32 s0, s71, s19
	global_load_lds_dwordx4 v146, s[50:51] offset:128
	s_add_u32 s50, s50, 0x100080
	s_addc_u32 s51, s51, 0
	s_mov_b32 m0, s0
	s_nop 0
	global_load_lds_dwordx4 v142, s[50:51]
	s_add_i32 m0, s0, 0x2000
	s_nop 0
	global_load_lds_dwordx4 v146, s[50:51]
	s_add_i32 m0, s56, 0xffffff80
	s_nop 0
	global_load_lds_dwordx4 v140, s[52:53] offset:128
	s_add_i32 m0, s57, 0xffffff80
	s_nop 0
	global_load_lds_dwordx4 v144, s[52:53] offset:128
	s_waitcnt vmcnt(8) lgkmcnt(0)
	s_setprio 1
	s_barrier
	v_mfma_f32_16x16x32_bf16 v[68:71], v[136:139], v[198:201], v[68:71]
	v_mfma_f32_16x16x32_bf16 v[68:71], v[158:161], v[202:205], v[68:71]
	v_mfma_f32_16x16x32_bf16 v[64:67], v[162:165], v[198:201], v[64:67]
	v_mfma_f32_16x16x32_bf16 v[64:67], v[166:169], v[202:205], v[64:67]
	v_mfma_f32_16x16x32_bf16 v[60:63], v[170:173], v[198:201], v[60:63]
	v_mfma_f32_16x16x32_bf16 v[60:63], v[174:177], v[202:205], v[60:63]
	v_mfma_f32_16x16x32_bf16 v[56:59], v[178:181], v[198:201], v[56:59]
	v_mfma_f32_16x16x32_bf16 v[56:59], v[194:197], v[202:205], v[56:59]
	v_mfma_f32_16x16x32_bf16 v[52:55], v[136:139], v[206:209], v[52:55]
	v_mfma_f32_16x16x32_bf16 v[52:55], v[158:161], v[210:213], v[52:55]
	v_mfma_f32_16x16x32_bf16 v[48:51], v[162:165], v[206:209], v[48:51]
	v_mfma_f32_16x16x32_bf16 v[48:51], v[166:169], v[210:213], v[48:51]
	v_mfma_f32_16x16x32_bf16 v[44:47], v[170:173], v[206:209], v[44:47]
	v_mfma_f32_16x16x32_bf16 v[44:47], v[174:177], v[210:213], v[44:47]
	v_mfma_f32_16x16x32_bf16 v[40:43], v[178:181], v[206:209], v[40:43]
	v_mfma_f32_16x16x32_bf16 v[40:43], v[194:197], v[210:213], v[40:43]
	v_mfma_f32_16x16x32_bf16 v[36:39], v[136:139], v[214:217], v[36:39]
	v_mfma_f32_16x16x32_bf16 v[36:39], v[158:161], v[218:221], v[36:39]
	v_mfma_f32_16x16x32_bf16 v[32:35], v[162:165], v[214:217], v[32:35]
	v_mfma_f32_16x16x32_bf16 v[32:35], v[166:169], v[218:221], v[32:35]
	v_mfma_f32_16x16x32_bf16 v[28:31], v[170:173], v[214:217], v[28:31]
	v_mfma_f32_16x16x32_bf16 v[28:31], v[174:177], v[218:221], v[28:31]
	v_mfma_f32_16x16x32_bf16 v[24:27], v[178:181], v[214:217], v[24:27]
	v_mfma_f32_16x16x32_bf16 v[24:27], v[194:197], v[218:221], v[24:27]
	v_mfma_f32_16x16x32_bf16 v[20:23], v[136:139], v[222:225], v[20:23]
	v_mfma_f32_16x16x32_bf16 v[20:23], v[158:161], v[226:229], v[20:23]
	v_mfma_f32_16x16x32_bf16 v[16:19], v[162:165], v[222:225], v[16:19]
	v_mfma_f32_16x16x32_bf16 v[16:19], v[166:169], v[226:229], v[16:19]
	v_mfma_f32_16x16x32_bf16 v[10:13], v[170:173], v[222:225], v[12:15]
	v_mfma_f32_16x16x32_bf16 v[12:15], v[174:177], v[226:229], v[10:13]
	v_mfma_f32_16x16x32_bf16 v[6:9], v[178:181], v[222:225], v[6:9]
	v_mfma_f32_16x16x32_bf16 v[8:11], v[194:197], v[226:229], v[6:9]
	s_setprio 0
	s_barrier
	s_add_i32 s70, s70, 2
	s_add_u32 s42, s42, 0x100
	s_addc_u32 s43, s43, 0
	s_add_u32 s67, s67, 0x100
	s_addc_u32 s68, s68, 0
	s_cmp_gt_u32 s70, 61
	s_cbranch_scc0 .LBB0_170
	s_and_b64 vcc, exec, s[16:17]
	s_cbranch_vccz .LBB0_173
	s_barrier

.LBB0_342:
	ds_read_b128 v[132:135], v209
	ds_read_b128 v[136:139], v209 offset:1024
	ds_read_b128 v[140:143], v209 offset:2048
	ds_read_b128 v[144:147], v209 offset:3072
	ds_read_b128 v[148:151], v210
	ds_read_b128 v[152:155], v210 offset:1024
	ds_read_b128 v[156:159], v210 offset:2048
	ds_read_b128 v[160:163], v210 offset:3072
	s_add_u32 s0, s26, 0xffd50080
	s_addc_u32 s28, s27, -1
	s_cmpk_eq_i32 s62, 0xa8
	s_cselect_b32 s31, s7, s28
	s_cselect_b32 s30, s6, s0
	s_cselect_b32 s29, s25, s61
	s_cselect_b32 s28, s24, s60
	s_add_i32 m0, s43, 0xc000
	ds_read_b128 v[164:167], v211
	ds_read_b128 v[168:171], v211 offset:1024
	ds_read_b128 v[172:175], v211 offset:2048
	ds_read_b128 v[176:179], v211 offset:3072
	ds_read_b128 v[196:199], v211 offset:4096
	ds_read_b128 v[200:203], v211 offset:5120
	ds_read_b128 v[204:207], v211 offset:6144
	ds_read_b128 v[214:217], v211 offset:7168
	global_load_lds_dwordx4 v188, s[26:27]
	s_add_i32 m0, s43, 0xe000
	s_nop 0
	global_load_lds_dwordx4 v190, s[26:27]
	s_waitcnt vmcnt(8) lgkmcnt(0)
	s_setprio 1
	s_barrier
	v_mfma_f32_16x16x32_bf16 v[128:131], v[132:135], v[164:167], v[128:131]
	v_mfma_f32_16x16x32_bf16 v[128:131], v[136:139], v[168:171], v[128:131]
	v_mfma_f32_16x16x32_bf16 v[124:127], v[140:143], v[164:167], v[124:127]
	v_mfma_f32_16x16x32_bf16 v[124:127], v[144:147], v[168:171], v[124:127]
	v_mfma_f32_16x16x32_bf16 v[120:123], v[148:151], v[164:167], v[120:123]
	v_mfma_f32_16x16x32_bf16 v[120:123], v[152:155], v[168:171], v[120:123]
	v_mfma_f32_16x16x32_bf16 v[116:119], v[156:159], v[164:167], v[116:119]
	v_mfma_f32_16x16x32_bf16 v[116:119], v[160:163], v[168:171], v[116:119]
	v_mfma_f32_16x16x32_bf16 v[100:103], v[156:159], v[172:175], v[100:103]
	v_mfma_f32_16x16x32_bf16 v[100:103], v[160:163], v[176:179], v[100:103]
	v_mfma_f32_16x16x32_bf16 v[104:107], v[148:151], v[172:175], v[104:107]
	v_mfma_f32_16x16x32_bf16 v[104:107], v[152:155], v[176:179], v[104:107]
	v_mfma_f32_16x16x32_bf16 v[108:111], v[140:143], v[172:175], v[108:111]
	v_mfma_f32_16x16x32_bf16 v[108:111], v[144:147], v[176:179], v[108:111]
	v_mfma_f32_16x16x32_bf16 v[112:115], v[132:135], v[172:175], v[112:115]
	v_mfma_f32_16x16x32_bf16 v[112:115], v[136:139], v[176:179], v[112:115]
	v_mfma_f32_16x16x32_bf16 v[96:99], v[132:135], v[196:199], v[96:99]
	v_mfma_f32_16x16x32_bf16 v[96:99], v[136:139], v[200:203], v[96:99]
	v_mfma_f32_16x16x32_bf16 v[92:95], v[140:143], v[196:199], v[92:95]
	v_mfma_f32_16x16x32_bf16 v[92:95], v[144:147], v[200:203], v[92:95]
	v_mfma_f32_16x16x32_bf16 v[88:91], v[148:151], v[196:199], v[88:91]
	v_mfma_f32_16x16x32_bf16 v[88:91], v[152:155], v[200:203], v[88:91]
	v_mfma_f32_16x16x32_bf16 v[84:87], v[156:159], v[196:199], v[84:87]
	v_mfma_f32_16x16x32_bf16 v[84:87], v[160:163], v[200:203], v[84:87]
	v_mfma_f32_16x16x32_bf16 v[68:71], v[156:159], v[204:207], v[68:71]
	v_mfma_f32_16x16x32_bf16 v[68:71], v[160:163], v[214:217], v[68:71]
	v_mfma_f32_16x16x32_bf16 v[72:75], v[148:151], v[204:207], v[72:75]
	v_mfma_f32_16x16x32_bf16 v[72:75], v[152:155], v[214:217], v[72:75]
	v_mfma_f32_16x16x32_bf16 v[76:79], v[140:143], v[204:207], v[76:79]
	v_mfma_f32_16x16x32_bf16 v[76:79], v[144:147], v[214:217], v[76:79]
	v_mfma_f32_16x16x32_bf16 v[80:83], v[132:135], v[204:207], v[80:83]
	v_mfma_f32_16x16x32_bf16 v[80:83], v[136:139], v[214:217], v[80:83]
	s_setprio 0
	s_barrier
	s_add_i32 s0, s53, s42
	s_mov_b32 m0, s0
	ds_read_b128 v[164:167], v211 offset:16384
	ds_read_b128 v[168:171], v211 offset:17408
	ds_read_b128 v[172:175], v211 offset:18432
	ds_read_b128 v[176:179], v211 offset:19456
	ds_read_b128 v[196:199], v211 offset:20480
	ds_read_b128 v[200:203], v211 offset:21504
	ds_read_b128 v[204:207], v211 offset:22528
	ds_read_b128 v[214:217], v211 offset:23552
	global_load_lds_dwordx4 v182, s[28:29]
	s_add_i32 m0, s0, 0x2000
	s_add_u32 s64, s28, 0x2b0000
	s_addc_u32 s65, s29, 0
	s_add_i32 s0, s54, s42
	global_load_lds_dwordx4 v186, s[28:29]
	s_mov_b32 m0, s0
	s_nop 0
	global_load_lds_dwordx4 v182, s[64:65]
	s_add_i32 m0, s0, 0x2000
	s_nop 0
	global_load_lds_dwordx4 v186, s[64:65]
	s_mov_b32 m0, s43
	s_nop 0
	global_load_lds_dwordx4 v180, s[30:31]
	s_mov_b32 m0, s45
	s_nop 0
	global_load_lds_dwordx4 v184, s[30:31]
	s_waitcnt vmcnt(8) lgkmcnt(0)
	s_setprio 1
	s_barrier
	v_mfma_f32_16x16x32_bf16 v[64:67], v[132:135], v[164:167], v[64:67]
	v_mfma_f32_16x16x32_bf16 v[64:67], v[136:139], v[168:171], v[64:67]
	v_mfma_f32_16x16x32_bf16 v[60:63], v[140:143], v[164:167], v[60:63]
	v_mfma_f32_16x16x32_bf16 v[60:63], v[144:147], v[168:171], v[60:63]
	v_mfma_f32_16x16x32_bf16 v[56:59], v[148:151], v[164:167], v[56:59]
	v_mfma_f32_16x16x32_bf16 v[56:59], v[152:155], v[168:171], v[56:59]
	v_mfma_f32_16x16x32_bf16 v[52:55], v[156:159], v[164:167], v[52:55]
	v_mfma_f32_16x16x32_bf16 v[52:55], v[160:163], v[168:171], v[52:55]
	v_mfma_f32_16x16x32_bf16 v[36:39], v[156:159], v[172:175], v[36:39]
	v_mfma_f32_16x16x32_bf16 v[36:39], v[160:163], v[176:179], v[36:39]
	v_mfma_f32_16x16x32_bf16 v[40:43], v[148:151], v[172:175], v[40:43]
	v_mfma_f32_16x16x32_bf16 v[40:43], v[152:155], v[176:179], v[40:43]
	v_mfma_f32_16x16x32_bf16 v[44:47], v[140:143], v[172:175], v[44:47]
	v_mfma_f32_16x16x32_bf16 v[44:47], v[144:147], v[176:179], v[44:47]
	v_mfma_f32_16x16x32_bf16 v[48:51], v[132:135], v[172:175], v[48:51]
	v_mfma_f32_16x16x32_bf16 v[48:51], v[136:139], v[176:179], v[48:51]
	v_mfma_f32_16x16x32_bf16 v[32:35], v[132:135], v[196:199], v[32:35]
	v_mfma_f32_16x16x32_bf16 v[32:35], v[136:139], v[200:203], v[32:35]
	v_mfma_f32_16x16x32_bf16 v[28:31], v[140:143], v[196:199], v[28:31]
	v_mfma_f32_16x16x32_bf16 v[28:31], v[144:147], v[200:203], v[28:31]
	v_mfma_f32_16x16x32_bf16 v[24:27], v[148:151], v[196:199], v[24:27]
	v_mfma_f32_16x16x32_bf16 v[24:27], v[152:155], v[200:203], v[24:27]
	v_mfma_f32_16x16x32_bf16 v[20:23], v[156:159], v[196:199], v[20:23]
	v_mfma_f32_16x16x32_bf16 v[20:23], v[160:163], v[200:203], v[20:23]
	v_mfma_f32_16x16x32_bf16 v[4:7], v[156:159], v[204:207], v[4:7]
	v_mfma_f32_16x16x32_bf16 v[4:7], v[160:163], v[214:217], v[4:7]
	v_mfma_f32_16x16x32_bf16 v[8:11], v[148:151], v[204:207], v[8:11]
	v_mfma_f32_16x16x32_bf16 v[8:11], v[152:155], v[214:217], v[8:11]
	v_mfma_f32_16x16x32_bf16 v[12:15], v[140:143], v[204:207], v[12:15]
	v_mfma_f32_16x16x32_bf16 v[12:15], v[144:147], v[214:217], v[12:15]
	v_mfma_f32_16x16x32_bf16 v[16:19], v[132:135], v[204:207], v[16:19]
	v_mfma_f32_16x16x32_bf16 v[16:19], v[136:139], v[214:217], v[16:19]
	s_setprio 0
	s_barrier
	s_add_i32 s0, 0, 0x18000
	s_add_i32 s63, 0, 0x1c000
	v_add_u32_e32 v144, s0, v3
	v_add_u32_e32 v160, s63, v3
	ds_read_b128 v[132:135], v144
	ds_read_b128 v[136:139], v144 offset:1024
	ds_read_b128 v[140:143], v144 offset:2048
	ds_read_b128 v[144:147], v144 offset:3072
	ds_read_b128 v[148:151], v160
	ds_read_b128 v[152:155], v160 offset:1024
	ds_read_b128 v[156:159], v160 offset:2048
	ds_read_b128 v[160:163], v160 offset:3072
	s_add_u32 s98, s30, 0x2b0000
	s_addc_u32 s99, s31, 0
	s_mov_b32 m0, s46
	ds_read_b128 v[164:167], v211 offset:32768
	ds_read_b128 v[168:171], v211 offset:33792
	ds_read_b128 v[172:175], v211 offset:34816
	ds_read_b128 v[176:179], v211 offset:35840
	ds_read_b128 v[196:199], v211 offset:36864
	ds_read_b128 v[200:203], v211 offset:37888
	ds_read_b128 v[204:207], v211 offset:38912
	ds_read_b128 v[214:217], v211 offset:39936
	global_load_lds_dwordx4 v180, s[98:99]
	s_mov_b32 m0, s47
	s_nop 0
	global_load_lds_dwordx4 v184, s[98:99]
	s_waitcnt vmcnt(8) lgkmcnt(0)
	s_setprio 1
	s_barrier
	v_mfma_f32_16x16x32_bf16 v[128:131], v[132:135], v[164:167], v[128:131]
	v_mfma_f32_16x16x32_bf16 v[128:131], v[136:139], v[168:171], v[128:131]
	v_mfma_f32_16x16x32_bf16 v[124:127], v[140:143], v[164:167], v[124:127]
	v_mfma_f32_16x16x32_bf16 v[124:127], v[144:147], v[168:171], v[124:127]
	v_mfma_f32_16x16x32_bf16 v[120:123], v[148:151], v[164:167], v[120:123]
	v_mfma_f32_16x16x32_bf16 v[120:123], v[152:155], v[168:171], v[120:123]
	v_mfma_f32_16x16x32_bf16 v[116:119], v[156:159], v[164:167], v[116:119]
	v_mfma_f32_16x16x32_bf16 v[116:119], v[160:163], v[168:171], v[116:119]
	v_mfma_f32_16x16x32_bf16 v[100:103], v[156:159], v[172:175], v[100:103]
	v_mfma_f32_16x16x32_bf16 v[100:103], v[160:163], v[176:179], v[100:103]
	v_mfma_f32_16x16x32_bf16 v[104:107], v[148:151], v[172:175], v[104:107]
	v_mfma_f32_16x16x32_bf16 v[104:107], v[152:155], v[176:179], v[104:107]
	v_mfma_f32_16x16x32_bf16 v[108:111], v[140:143], v[172:175], v[108:111]
	v_mfma_f32_16x16x32_bf16 v[108:111], v[144:147], v[176:179], v[108:111]
	v_mfma_f32_16x16x32_bf16 v[112:115], v[132:135], v[172:175], v[112:115]
	v_mfma_f32_16x16x32_bf16 v[112:115], v[136:139], v[176:179], v[112:115]
	v_mfma_f32_16x16x32_bf16 v[96:99], v[132:135], v[196:199], v[96:99]
	v_mfma_f32_16x16x32_bf16 v[96:99], v[136:139], v[200:203], v[96:99]
	v_mfma_f32_16x16x32_bf16 v[92:95], v[140:143], v[196:199], v[92:95]
	v_mfma_f32_16x16x32_bf16 v[92:95], v[144:147], v[200:203], v[92:95]
	v_mfma_f32_16x16x32_bf16 v[88:91], v[148:151], v[196:199], v[88:91]
	v_mfma_f32_16x16x32_bf16 v[88:91], v[152:155], v[200:203], v[88:91]
	v_mfma_f32_16x16x32_bf16 v[84:87], v[156:159], v[196:199], v[84:87]
	v_mfma_f32_16x16x32_bf16 v[84:87], v[160:163], v[200:203], v[84:87]
	v_mfma_f32_16x16x32_bf16 v[68:71], v[156:159], v[204:207], v[68:71]
	v_mfma_f32_16x16x32_bf16 v[68:71], v[160:163], v[214:217], v[68:71]
	v_mfma_f32_16x16x32_bf16 v[72:75], v[148:151], v[204:207], v[72:75]
	v_mfma_f32_16x16x32_bf16 v[72:75], v[152:155], v[214:217], v[72:75]
	v_mfma_f32_16x16x32_bf16 v[76:79], v[140:143], v[204:207], v[76:79]
	v_mfma_f32_16x16x32_bf16 v[76:79], v[144:147], v[214:217], v[76:79]
	v_mfma_f32_16x16x32_bf16 v[80:83], v[132:135], v[204:207], v[80:83]
	v_mfma_f32_16x16x32_bf16 v[80:83], v[136:139], v[214:217], v[80:83]
	s_setprio 0
	s_barrier
	s_add_i32 s0, s0, s42
	s_add_i32 m0, s0, 0xffffff80
	ds_read_b128 v[164:167], v211 offset:49152
	ds_read_b128 v[168:171], v211 offset:50176
	ds_read_b128 v[172:175], v211 offset:51200
	ds_read_b128 v[176:179], v211 offset:52224
	ds_read_b128 v[196:199], v211 offset:53248
	ds_read_b128 v[200:203], v211 offset:54272
	ds_read_b128 v[204:207], v211 offset:55296
	ds_read_b128 v[214:217], v211 offset:56320
	global_load_lds_dwordx4 v182, s[28:29] offset:128
	s_add_i32 m0, s0, 0x1f80
	s_add_i32 s0, s63, s42
	global_load_lds_dwordx4 v186, s[28:29] offset:128
	s_add_u32 s28, s28, 0x2b0080
	s_addc_u32 s29, s29, 0
	s_mov_b32 m0, s0
	s_nop 0
	global_load_lds_dwordx4 v182, s[28:29]
	s_add_i32 m0, s0, 0x2000
	s_nop 0
	global_load_lds_dwordx4 v186, s[28:29]
	s_add_i32 m0, s51, 0xffffff80
	s_nop 0
	global_load_lds_dwordx4 v180, s[30:31] offset:128
	s_add_i32 m0, s52, 0xffffff80
	s_nop 0
	global_load_lds_dwordx4 v184, s[30:31] offset:128
	s_waitcnt vmcnt(8) lgkmcnt(0)
	s_setprio 1
	s_barrier
	v_mfma_f32_16x16x32_bf16 v[64:67], v[132:135], v[164:167], v[64:67]
	v_mfma_f32_16x16x32_bf16 v[64:67], v[136:139], v[168:171], v[64:67]
	v_mfma_f32_16x16x32_bf16 v[60:63], v[140:143], v[164:167], v[60:63]
	v_mfma_f32_16x16x32_bf16 v[60:63], v[144:147], v[168:171], v[60:63]
	v_mfma_f32_16x16x32_bf16 v[56:59], v[148:151], v[164:167], v[56:59]
	v_mfma_f32_16x16x32_bf16 v[56:59], v[152:155], v[168:171], v[56:59]
	v_mfma_f32_16x16x32_bf16 v[52:55], v[156:159], v[164:167], v[52:55]
	v_mfma_f32_16x16x32_bf16 v[52:55], v[160:163], v[168:171], v[52:55]
	v_mfma_f32_16x16x32_bf16 v[36:39], v[156:159], v[172:175], v[36:39]
	v_mfma_f32_16x16x32_bf16 v[36:39], v[160:163], v[176:179], v[36:39]
	v_mfma_f32_16x16x32_bf16 v[40:43], v[148:151], v[172:175], v[40:43]
	v_mfma_f32_16x16x32_bf16 v[40:43], v[152:155], v[176:179], v[40:43]
	v_mfma_f32_16x16x32_bf16 v[44:47], v[140:143], v[172:175], v[44:47]
	v_mfma_f32_16x16x32_bf16 v[44:47], v[144:147], v[176:179], v[44:47]
	v_mfma_f32_16x16x32_bf16 v[48:51], v[132:135], v[172:175], v[48:51]
	v_mfma_f32_16x16x32_bf16 v[48:51], v[136:139], v[176:179], v[48:51]
	v_mfma_f32_16x16x32_bf16 v[32:35], v[132:135], v[196:199], v[32:35]
	v_mfma_f32_16x16x32_bf16 v[32:35], v[136:139], v[200:203], v[32:35]
	v_mfma_f32_16x16x32_bf16 v[28:31], v[140:143], v[196:199], v[28:31]
	v_mfma_f32_16x16x32_bf16 v[28:31], v[144:147], v[200:203], v[28:31]
	v_mfma_f32_16x16x32_bf16 v[24:27], v[148:151], v[196:199], v[24:27]
	v_mfma_f32_16x16x32_bf16 v[24:27], v[152:155], v[200:203], v[24:27]
	v_mfma_f32_16x16x32_bf16 v[20:23], v[156:159], v[196:199], v[20:23]
	v_mfma_f32_16x16x32_bf16 v[20:23], v[160:163], v[200:203], v[20:23]
	v_mfma_f32_16x16x32_bf16 v[4:7], v[156:159], v[204:207], v[4:7]
	v_mfma_f32_16x16x32_bf16 v[4:7], v[160:163], v[214:217], v[4:7]
	v_mfma_f32_16x16x32_bf16 v[8:11], v[148:151], v[204:207], v[8:11]
	v_mfma_f32_16x16x32_bf16 v[8:11], v[152:155], v[214:217], v[8:11]
	v_mfma_f32_16x16x32_bf16 v[12:15], v[140:143], v[204:207], v[12:15]
	v_mfma_f32_16x16x32_bf16 v[12:15], v[144:147], v[214:217], v[12:15]
	v_mfma_f32_16x16x32_bf16 v[16:19], v[132:135], v[204:207], v[16:19]
	v_mfma_f32_16x16x32_bf16 v[16:19], v[136:139], v[214:217], v[16:19]
	s_setprio 0
	s_barrier
	s_add_i32 s62, s62, 2
	s_add_u32 s26, s26, 0x100
	s_addc_u32 s27, s27, 0
	s_add_u32 s60, s60, 0x100
	s_addc_u32 s61, s61, 0
	s_cmpk_gt_u32 s62, 0xa9
	s_cbranch_scc0 .LBB0_342
	s_and_b64 vcc, exec, s[22:23]
	s_cbranch_vccz .LBB0_345
	s_barrier

.LBB0_429:
	ds_read_b128 v[150:153], v156
	ds_read_b128 v[162:165], v156 offset:1024
	ds_read_b128 v[166:169], v156 offset:2048
	ds_read_b128 v[170:173], v156 offset:3072
	ds_read_b128 v[174:177], v157
	ds_read_b128 v[178:181], v157 offset:1024
	ds_read_b128 v[182:185], v157 offset:2048
	ds_read_b128 v[186:189], v157 offset:3072
	s_add_u32 s0, s50, 0xfff00080
	s_addc_u32 s52, s51, -1
	s_cmp_eq_u32 s72, 60
	s_cselect_b32 s55, s27, s52
	s_cselect_b32 s54, s67, s0
	s_cselect_b32 s53, s25, s71
	s_cselect_b32 s52, s68, s70
	s_add_i32 m0, s43, 0xc000
	ds_read_b128 v[190:193], v158
	ds_read_b128 v[194:197], v158 offset:1024
	ds_read_b128 v[198:201], v158 offset:2048
	ds_read_b128 v[202:205], v158 offset:3072
	ds_read_b128 v[206:209], v158 offset:4096
	ds_read_b128 v[210:213], v158 offset:5120
	ds_read_b128 v[214:217], v158 offset:6144
	ds_read_b128 v[218:221], v158 offset:7168
	global_load_lds_dwordx4 v142, s[50:51]
	s_add_i32 m0, s43, 0xe000
	s_nop 0
	global_load_lds_dwordx4 v144, s[50:51]
	s_waitcnt vmcnt(8) lgkmcnt(0)
	s_setprio 1
	s_barrier
	v_mfma_f32_16x16x32_bf16 v[128:131], v[150:153], v[190:193], v[128:131]
	v_mfma_f32_16x16x32_bf16 v[128:131], v[162:165], v[194:197], v[128:131]
	v_mfma_f32_16x16x32_bf16 v[124:127], v[166:169], v[190:193], v[124:127]
	v_mfma_f32_16x16x32_bf16 v[124:127], v[170:173], v[194:197], v[124:127]
	v_mfma_f32_16x16x32_bf16 v[120:123], v[174:177], v[190:193], v[120:123]
	v_mfma_f32_16x16x32_bf16 v[120:123], v[178:181], v[194:197], v[120:123]
	v_mfma_f32_16x16x32_bf16 v[116:119], v[182:185], v[190:193], v[116:119]
	v_mfma_f32_16x16x32_bf16 v[116:119], v[186:189], v[194:197], v[116:119]
	v_mfma_f32_16x16x32_bf16 v[100:103], v[182:185], v[198:201], v[100:103]
	v_mfma_f32_16x16x32_bf16 v[100:103], v[186:189], v[202:205], v[100:103]
	v_mfma_f32_16x16x32_bf16 v[104:107], v[174:177], v[198:201], v[104:107]
	v_mfma_f32_16x16x32_bf16 v[104:107], v[178:181], v[202:205], v[104:107]
	v_mfma_f32_16x16x32_bf16 v[108:111], v[166:169], v[198:201], v[108:111]
	v_mfma_f32_16x16x32_bf16 v[108:111], v[170:173], v[202:205], v[108:111]
	v_mfma_f32_16x16x32_bf16 v[112:115], v[150:153], v[198:201], v[112:115]
	v_mfma_f32_16x16x32_bf16 v[112:115], v[162:165], v[202:205], v[112:115]
	v_mfma_f32_16x16x32_bf16 v[96:99], v[150:153], v[206:209], v[96:99]
	v_mfma_f32_16x16x32_bf16 v[96:99], v[162:165], v[210:213], v[96:99]
	v_mfma_f32_16x16x32_bf16 v[92:95], v[166:169], v[206:209], v[92:95]
	v_mfma_f32_16x16x32_bf16 v[92:95], v[170:173], v[210:213], v[92:95]
	v_mfma_f32_16x16x32_bf16 v[88:91], v[174:177], v[206:209], v[88:91]
	v_mfma_f32_16x16x32_bf16 v[88:91], v[178:181], v[210:213], v[88:91]
	v_mfma_f32_16x16x32_bf16 v[84:87], v[182:185], v[206:209], v[84:87]
	v_mfma_f32_16x16x32_bf16 v[84:87], v[186:189], v[210:213], v[84:87]
	v_mfma_f32_16x16x32_bf16 v[68:71], v[182:185], v[214:217], v[68:71]
	v_mfma_f32_16x16x32_bf16 v[68:71], v[186:189], v[218:221], v[68:71]
	v_mfma_f32_16x16x32_bf16 v[72:75], v[174:177], v[214:217], v[72:75]
	v_mfma_f32_16x16x32_bf16 v[72:75], v[178:181], v[218:221], v[72:75]
	v_mfma_f32_16x16x32_bf16 v[76:79], v[166:169], v[214:217], v[76:79]
	v_mfma_f32_16x16x32_bf16 v[76:79], v[170:173], v[218:221], v[76:79]
	v_mfma_f32_16x16x32_bf16 v[80:83], v[150:153], v[214:217], v[80:83]
	v_mfma_f32_16x16x32_bf16 v[80:83], v[162:165], v[218:221], v[80:83]
	s_setprio 0
	s_barrier
	s_add_i32 s0, s62, s41
	s_mov_b32 m0, s0
	ds_read_b128 v[190:193], v158 offset:16384
	ds_read_b128 v[194:197], v158 offset:17408
	ds_read_b128 v[198:201], v158 offset:18432
	ds_read_b128 v[202:205], v158 offset:19456
	ds_read_b128 v[206:209], v158 offset:20480
	ds_read_b128 v[210:213], v158 offset:21504
	ds_read_b128 v[214:217], v158 offset:22528
	ds_read_b128 v[218:221], v158 offset:23552
	global_load_lds_dwordx4 v136, s[52:53]
	s_add_i32 m0, s0, 0x2000
	s_add_u32 s74, s52, 0x100000
	s_addc_u32 s75, s53, 0
	s_add_i32 s0, s63, s41
	global_load_lds_dwordx4 v140, s[52:53]
	s_mov_b32 m0, s0
	s_nop 0
	global_load_lds_dwordx4 v136, s[74:75]
	s_add_i32 m0, s0, 0x2000
	s_nop 0
	global_load_lds_dwordx4 v140, s[74:75]
	s_mov_b32 m0, s43
	s_nop 0
	global_load_lds_dwordx4 v134, s[54:55]
	s_mov_b32 m0, s48
	s_nop 0
	global_load_lds_dwordx4 v138, s[54:55]
	s_waitcnt vmcnt(8) lgkmcnt(0)
	s_setprio 1
	s_barrier
	v_mfma_f32_16x16x32_bf16 v[64:67], v[150:153], v[190:193], v[64:67]
	v_mfma_f32_16x16x32_bf16 v[64:67], v[162:165], v[194:197], v[64:67]
	v_mfma_f32_16x16x32_bf16 v[60:63], v[166:169], v[190:193], v[60:63]
	v_mfma_f32_16x16x32_bf16 v[60:63], v[170:173], v[194:197], v[60:63]
	v_mfma_f32_16x16x32_bf16 v[56:59], v[174:177], v[190:193], v[56:59]
	v_mfma_f32_16x16x32_bf16 v[56:59], v[178:181], v[194:197], v[56:59]
	v_mfma_f32_16x16x32_bf16 v[52:55], v[182:185], v[190:193], v[52:55]
	v_mfma_f32_16x16x32_bf16 v[52:55], v[186:189], v[194:197], v[52:55]
	v_mfma_f32_16x16x32_bf16 v[36:39], v[182:185], v[198:201], v[36:39]
	v_mfma_f32_16x16x32_bf16 v[36:39], v[186:189], v[202:205], v[36:39]
	v_mfma_f32_16x16x32_bf16 v[40:43], v[174:177], v[198:201], v[40:43]
	v_mfma_f32_16x16x32_bf16 v[40:43], v[178:181], v[202:205], v[40:43]
	v_mfma_f32_16x16x32_bf16 v[44:47], v[166:169], v[198:201], v[44:47]
	v_mfma_f32_16x16x32_bf16 v[44:47], v[170:173], v[202:205], v[44:47]
	v_mfma_f32_16x16x32_bf16 v[48:51], v[150:153], v[198:201], v[48:51]
	v_mfma_f32_16x16x32_bf16 v[48:51], v[162:165], v[202:205], v[48:51]
	v_mfma_f32_16x16x32_bf16 v[32:35], v[150:153], v[206:209], v[32:35]
	v_mfma_f32_16x16x32_bf16 v[32:35], v[162:165], v[210:213], v[32:35]
	v_mfma_f32_16x16x32_bf16 v[28:31], v[166:169], v[206:209], v[28:31]
	v_mfma_f32_16x16x32_bf16 v[28:31], v[170:173], v[210:213], v[28:31]
	v_mfma_f32_16x16x32_bf16 v[24:27], v[174:177], v[206:209], v[24:27]
	v_mfma_f32_16x16x32_bf16 v[24:27], v[178:181], v[210:213], v[24:27]
	v_mfma_f32_16x16x32_bf16 v[20:23], v[182:185], v[206:209], v[20:23]
	v_mfma_f32_16x16x32_bf16 v[20:23], v[186:189], v[210:213], v[20:23]
	v_mfma_f32_16x16x32_bf16 v[4:7], v[182:185], v[214:217], v[4:7]
	v_mfma_f32_16x16x32_bf16 v[4:7], v[186:189], v[218:221], v[4:7]
	v_mfma_f32_16x16x32_bf16 v[8:11], v[174:177], v[214:217], v[8:11]
	v_mfma_f32_16x16x32_bf16 v[8:11], v[178:181], v[218:221], v[8:11]
	v_mfma_f32_16x16x32_bf16 v[12:15], v[166:169], v[214:217], v[12:15]
	v_mfma_f32_16x16x32_bf16 v[12:15], v[170:173], v[218:221], v[12:15]
	v_mfma_f32_16x16x32_bf16 v[16:19], v[150:153], v[214:217], v[16:19]
	v_mfma_f32_16x16x32_bf16 v[16:19], v[162:165], v[218:221], v[16:19]
	s_setprio 0
	s_barrier
	s_add_i32 s0, 0, 0x18000
	v_add_u32_e32 v161, s0, v133
	s_add_i32 s73, 0, 0x1c000
	ds_read_b128 v[150:153], v161
	ds_read_b128 v[162:165], v161 offset:1024
	ds_read_b128 v[166:169], v161 offset:2048
	ds_read_b128 v[170:173], v161 offset:3072
	v_add_u32_e32 v161, s73, v133
	ds_read_b128 v[174:177], v161
	ds_read_b128 v[178:181], v161 offset:1024
	ds_read_b128 v[182:185], v161 offset:2048
	ds_read_b128 v[186:189], v161 offset:3072
	s_add_u32 s98, s54, 0x100000
	s_addc_u32 s99, s55, 0
	s_mov_b32 m0, s49
	ds_read_b128 v[190:193], v158 offset:32768
	ds_read_b128 v[194:197], v158 offset:33792
	ds_read_b128 v[198:201], v158 offset:34816
	ds_read_b128 v[202:205], v158 offset:35840
	ds_read_b128 v[206:209], v158 offset:36864
	ds_read_b128 v[210:213], v158 offset:37888
	ds_read_b128 v[214:217], v158 offset:38912
	ds_read_b128 v[218:221], v158 offset:39936
	global_load_lds_dwordx4 v134, s[98:99]
	s_mov_b32 m0, s56
	s_nop 0
	global_load_lds_dwordx4 v138, s[98:99]
	s_waitcnt vmcnt(8) lgkmcnt(0)
	s_setprio 1
	s_barrier
	v_mfma_f32_16x16x32_bf16 v[128:131], v[150:153], v[190:193], v[128:131]
	v_mfma_f32_16x16x32_bf16 v[128:131], v[162:165], v[194:197], v[128:131]
	v_mfma_f32_16x16x32_bf16 v[124:127], v[166:169], v[190:193], v[124:127]
	v_mfma_f32_16x16x32_bf16 v[124:127], v[170:173], v[194:197], v[124:127]
	v_mfma_f32_16x16x32_bf16 v[120:123], v[174:177], v[190:193], v[120:123]
	v_mfma_f32_16x16x32_bf16 v[120:123], v[178:181], v[194:197], v[120:123]
	v_mfma_f32_16x16x32_bf16 v[116:119], v[182:185], v[190:193], v[116:119]
	v_mfma_f32_16x16x32_bf16 v[116:119], v[186:189], v[194:197], v[116:119]
	v_mfma_f32_16x16x32_bf16 v[100:103], v[182:185], v[198:201], v[100:103]
	v_mfma_f32_16x16x32_bf16 v[100:103], v[186:189], v[202:205], v[100:103]
	v_mfma_f32_16x16x32_bf16 v[104:107], v[174:177], v[198:201], v[104:107]
	v_mfma_f32_16x16x32_bf16 v[104:107], v[178:181], v[202:205], v[104:107]
	v_mfma_f32_16x16x32_bf16 v[108:111], v[166:169], v[198:201], v[108:111]
	v_mfma_f32_16x16x32_bf16 v[108:111], v[170:173], v[202:205], v[108:111]
	v_mfma_f32_16x16x32_bf16 v[112:115], v[150:153], v[198:201], v[112:115]
	v_mfma_f32_16x16x32_bf16 v[112:115], v[162:165], v[202:205], v[112:115]
	v_mfma_f32_16x16x32_bf16 v[96:99], v[150:153], v[206:209], v[96:99]
	v_mfma_f32_16x16x32_bf16 v[96:99], v[162:165], v[210:213], v[96:99]
	v_mfma_f32_16x16x32_bf16 v[92:95], v[166:169], v[206:209], v[92:95]
	v_mfma_f32_16x16x32_bf16 v[92:95], v[170:173], v[210:213], v[92:95]
	v_mfma_f32_16x16x32_bf16 v[88:91], v[174:177], v[206:209], v[88:91]
	v_mfma_f32_16x16x32_bf16 v[88:91], v[178:181], v[210:213], v[88:91]
	v_mfma_f32_16x16x32_bf16 v[84:87], v[182:185], v[206:209], v[84:87]
	v_mfma_f32_16x16x32_bf16 v[84:87], v[186:189], v[210:213], v[84:87]
	v_mfma_f32_16x16x32_bf16 v[68:71], v[182:185], v[214:217], v[68:71]
	v_mfma_f32_16x16x32_bf16 v[68:71], v[186:189], v[218:221], v[68:71]
	v_mfma_f32_16x16x32_bf16 v[72:75], v[174:177], v[214:217], v[72:75]
	v_mfma_f32_16x16x32_bf16 v[72:75], v[178:181], v[218:221], v[72:75]
	v_mfma_f32_16x16x32_bf16 v[76:79], v[166:169], v[214:217], v[76:79]
	v_mfma_f32_16x16x32_bf16 v[76:79], v[170:173], v[218:221], v[76:79]
	v_mfma_f32_16x16x32_bf16 v[80:83], v[150:153], v[214:217], v[80:83]
	v_mfma_f32_16x16x32_bf16 v[80:83], v[162:165], v[218:221], v[80:83]
	s_setprio 0
	s_barrier
	s_add_i32 s0, s0, s41
	s_add_i32 m0, s0, 0xffffff80
	ds_read_b128 v[190:193], v158 offset:49152
	ds_read_b128 v[194:197], v158 offset:50176
	ds_read_b128 v[198:201], v158 offset:51200
	ds_read_b128 v[202:205], v158 offset:52224
	ds_read_b128 v[206:209], v158 offset:53248
	ds_read_b128 v[210:213], v158 offset:54272
	ds_read_b128 v[214:217], v158 offset:55296
	ds_read_b128 v[218:221], v158 offset:56320
	global_load_lds_dwordx4 v136, s[52:53] offset:128
	s_add_i32 m0, s0, 0x1f80
	s_add_i32 s0, s73, s41
	global_load_lds_dwordx4 v140, s[52:53] offset:128
	s_add_u32 s52, s52, 0x100080
	s_addc_u32 s53, s53, 0
	s_mov_b32 m0, s0
	s_nop 0
	global_load_lds_dwordx4 v136, s[52:53]
	s_add_i32 m0, s0, 0x2000
	s_nop 0
	global_load_lds_dwordx4 v140, s[52:53]
	s_add_i32 m0, s59, 0xffffff80
	s_nop 0
	global_load_lds_dwordx4 v134, s[54:55] offset:128
	s_add_i32 m0, s60, 0xffffff80
	s_nop 0
	global_load_lds_dwordx4 v138, s[54:55] offset:128
	s_waitcnt vmcnt(8) lgkmcnt(0)
	s_setprio 1
	s_barrier
	v_mfma_f32_16x16x32_bf16 v[64:67], v[150:153], v[190:193], v[64:67]
	v_mfma_f32_16x16x32_bf16 v[64:67], v[162:165], v[194:197], v[64:67]
	v_mfma_f32_16x16x32_bf16 v[60:63], v[166:169], v[190:193], v[60:63]
	v_mfma_f32_16x16x32_bf16 v[60:63], v[170:173], v[194:197], v[60:63]
	v_mfma_f32_16x16x32_bf16 v[56:59], v[174:177], v[190:193], v[56:59]
	v_mfma_f32_16x16x32_bf16 v[56:59], v[178:181], v[194:197], v[56:59]
	v_mfma_f32_16x16x32_bf16 v[52:55], v[182:185], v[190:193], v[52:55]
	v_mfma_f32_16x16x32_bf16 v[52:55], v[186:189], v[194:197], v[52:55]
	v_mfma_f32_16x16x32_bf16 v[36:39], v[182:185], v[198:201], v[36:39]
	v_mfma_f32_16x16x32_bf16 v[36:39], v[186:189], v[202:205], v[36:39]
	v_mfma_f32_16x16x32_bf16 v[40:43], v[174:177], v[198:201], v[40:43]
	v_mfma_f32_16x16x32_bf16 v[40:43], v[178:181], v[202:205], v[40:43]
	v_mfma_f32_16x16x32_bf16 v[44:47], v[166:169], v[198:201], v[44:47]
	v_mfma_f32_16x16x32_bf16 v[44:47], v[170:173], v[202:205], v[44:47]
	v_mfma_f32_16x16x32_bf16 v[48:51], v[150:153], v[198:201], v[48:51]
	v_mfma_f32_16x16x32_bf16 v[48:51], v[162:165], v[202:205], v[48:51]
	v_mfma_f32_16x16x32_bf16 v[32:35], v[150:153], v[206:209], v[32:35]
	v_mfma_f32_16x16x32_bf16 v[32:35], v[162:165], v[210:213], v[32:35]
	v_mfma_f32_16x16x32_bf16 v[28:31], v[166:169], v[206:209], v[28:31]
	v_mfma_f32_16x16x32_bf16 v[28:31], v[170:173], v[210:213], v[28:31]
	v_mfma_f32_16x16x32_bf16 v[24:27], v[174:177], v[206:209], v[24:27]
	v_mfma_f32_16x16x32_bf16 v[24:27], v[178:181], v[210:213], v[24:27]
	v_mfma_f32_16x16x32_bf16 v[20:23], v[182:185], v[206:209], v[20:23]
	v_mfma_f32_16x16x32_bf16 v[20:23], v[186:189], v[210:213], v[20:23]
	v_mfma_f32_16x16x32_bf16 v[4:7], v[182:185], v[214:217], v[4:7]
	v_mfma_f32_16x16x32_bf16 v[4:7], v[186:189], v[218:221], v[4:7]
	v_mfma_f32_16x16x32_bf16 v[8:11], v[174:177], v[214:217], v[8:11]
	v_mfma_f32_16x16x32_bf16 v[8:11], v[178:181], v[218:221], v[8:11]
	v_mfma_f32_16x16x32_bf16 v[12:15], v[166:169], v[214:217], v[12:15]
	v_mfma_f32_16x16x32_bf16 v[12:15], v[170:173], v[218:221], v[12:15]
	v_mfma_f32_16x16x32_bf16 v[16:19], v[150:153], v[214:217], v[16:19]
	v_mfma_f32_16x16x32_bf16 v[16:19], v[162:165], v[218:221], v[16:19]
	s_setprio 0
	s_barrier
	s_add_i32 s72, s72, 2
	s_add_u32 s50, s50, 0x100
	s_addc_u32 s51, s51, 0
	s_add_u32 s70, s70, 0x100
	s_addc_u32 s71, s71, 0
	s_cmp_gt_u32 s72, 61
	s_cbranch_scc0 .LBB0_429
	s_and_b64 vcc, exec, s[22:23]
	s_cbranch_vccz .LBB0_432
	s_barrier

.LBB0_1032:
	v_add_u32_e32 v5, s60, v3
	ds_read_b128 v[140:143], v5
	ds_read_b128 v[144:147], v5 offset:1024
	ds_read_b128 v[148:151], v5 offset:2048
	ds_read_b128 v[152:155], v5 offset:3072
	v_add_u32_e32 v5, s61, v3
	ds_read_b128 v[156:159], v5
	ds_read_b128 v[160:163], v5 offset:1024
	ds_read_b128 v[164:167], v5 offset:2048
	ds_read_b128 v[168:171], v5 offset:3072
	s_add_u32 s42, s40, 0xfff80080
	s_addc_u32 s43, s41, -1
	s_cmp_eq_u32 s67, 28
	s_cselect_b32 s51, s5, s43
	s_cselect_b32 s50, s7, s42
	s_cselect_b32 s43, s25, s66
	s_cselect_b32 s42, s27, s65
	s_add_i32 m0, s47, 0xc000
	ds_read_b128 v[172:175], v246
	ds_read_b128 v[176:179], v246 offset:1024
	ds_read_b128 v[180:183], v246 offset:2048
	ds_read_b128 v[184:187], v246 offset:3072
	ds_read_b128 v[188:191], v246 offset:4096
	ds_read_b128 v[192:195], v246 offset:5120
	ds_read_b128 v[196:199], v246 offset:6144
	ds_read_b128 v[200:203], v246 offset:7168
	global_load_lds_dwordx4 v216, s[40:41]
	s_add_i32 m0, s47, 0xe000
	s_nop 0
	global_load_lds_dwordx4 v218, s[40:41]
	s_waitcnt vmcnt(8) lgkmcnt(0)
	s_setprio 1
	s_barrier
	v_mfma_f32_16x16x32_bf16 v[136:139], v[140:143], v[172:175], v[136:139]
	v_mfma_f32_16x16x32_bf16 v[136:139], v[144:147], v[176:179], v[136:139]
	v_mfma_f32_16x16x32_bf16 v[132:135], v[148:151], v[172:175], v[132:135]
	v_mfma_f32_16x16x32_bf16 v[132:135], v[152:155], v[176:179], v[132:135]
	v_mfma_f32_16x16x32_bf16 v[104:107], v[156:159], v[172:175], v[104:107]
	v_mfma_f32_16x16x32_bf16 v[104:107], v[160:163], v[176:179], v[104:107]
	v_mfma_f32_16x16x32_bf16 v[100:103], v[164:167], v[172:175], v[100:103]
	v_mfma_f32_16x16x32_bf16 v[100:103], v[168:171], v[176:179], v[100:103]
	v_mfma_f32_16x16x32_bf16 v[92:95], v[164:167], v[180:183], v[92:95]
	v_mfma_f32_16x16x32_bf16 v[92:95], v[168:171], v[184:187], v[92:95]
	v_mfma_f32_16x16x32_bf16 v[96:99], v[156:159], v[180:183], v[96:99]
	v_mfma_f32_16x16x32_bf16 v[96:99], v[160:163], v[184:187], v[96:99]
	v_mfma_f32_16x16x32_bf16 v[124:127], v[148:151], v[180:183], v[124:127]
	v_mfma_f32_16x16x32_bf16 v[124:127], v[152:155], v[184:187], v[124:127]
	v_mfma_f32_16x16x32_bf16 v[128:131], v[140:143], v[180:183], v[128:131]
	v_mfma_f32_16x16x32_bf16 v[128:131], v[144:147], v[184:187], v[128:131]
	v_mfma_f32_16x16x32_bf16 v[120:123], v[140:143], v[188:191], v[120:123]
	v_mfma_f32_16x16x32_bf16 v[120:123], v[144:147], v[192:195], v[120:123]
	v_mfma_f32_16x16x32_bf16 v[116:119], v[148:151], v[188:191], v[116:119]
	v_mfma_f32_16x16x32_bf16 v[116:119], v[152:155], v[192:195], v[116:119]
	v_mfma_f32_16x16x32_bf16 v[88:91], v[156:159], v[188:191], v[88:91]
	v_mfma_f32_16x16x32_bf16 v[88:91], v[160:163], v[192:195], v[88:91]
	v_mfma_f32_16x16x32_bf16 v[84:87], v[164:167], v[188:191], v[84:87]
	v_mfma_f32_16x16x32_bf16 v[84:87], v[168:171], v[192:195], v[84:87]
	v_mfma_f32_16x16x32_bf16 v[76:79], v[164:167], v[196:199], v[76:79]
	v_mfma_f32_16x16x32_bf16 v[76:79], v[168:171], v[200:203], v[76:79]
	v_mfma_f32_16x16x32_bf16 v[80:83], v[156:159], v[196:199], v[80:83]
	v_mfma_f32_16x16x32_bf16 v[80:83], v[160:163], v[200:203], v[80:83]
	v_mfma_f32_16x16x32_bf16 v[108:111], v[148:151], v[196:199], v[108:111]
	v_mfma_f32_16x16x32_bf16 v[108:111], v[152:155], v[200:203], v[108:111]
	v_mfma_f32_16x16x32_bf16 v[112:115], v[140:143], v[196:199], v[112:115]
	v_mfma_f32_16x16x32_bf16 v[112:115], v[144:147], v[200:203], v[112:115]
	s_setprio 0
	s_barrier
	s_add_i32 s68, s60, s46
	s_mov_b32 m0, s68
	ds_read_b128 v[172:175], v246 offset:16384
	ds_read_b128 v[176:179], v246 offset:17408
	ds_read_b128 v[180:183], v246 offset:18432
	ds_read_b128 v[184:187], v246 offset:19456
	ds_read_b128 v[188:191], v246 offset:20480
	ds_read_b128 v[192:195], v246 offset:21504
	ds_read_b128 v[196:199], v246 offset:22528
	ds_read_b128 v[200:203], v246 offset:23552
	global_load_lds_dwordx4 v210, s[42:43]
	s_add_i32 m0, s68, 0x2000
	s_add_u32 s70, s42, 0x80000
	s_addc_u32 s71, s43, 0
	s_add_i32 s68, s61, s46
	global_load_lds_dwordx4 v214, s[42:43]
	s_mov_b32 m0, s68
	s_nop 0
	global_load_lds_dwordx4 v210, s[70:71]
	s_add_i32 m0, s68, 0x2000
	s_nop 0
	global_load_lds_dwordx4 v214, s[70:71]
	s_mov_b32 m0, s47
	s_nop 0
	global_load_lds_dwordx4 v208, s[50:51]
	s_mov_b32 m0, s48
	s_nop 0
	global_load_lds_dwordx4 v212, s[50:51]
	s_waitcnt vmcnt(8) lgkmcnt(0)
	s_setprio 1
	s_barrier
	v_mfma_f32_16x16x32_bf16 v[72:75], v[140:143], v[172:175], v[72:75]
	v_mfma_f32_16x16x32_bf16 v[72:75], v[144:147], v[176:179], v[72:75]
	v_mfma_f32_16x16x32_bf16 v[68:71], v[148:151], v[172:175], v[68:71]
	v_mfma_f32_16x16x32_bf16 v[68:71], v[152:155], v[176:179], v[68:71]
	v_mfma_f32_16x16x32_bf16 v[40:43], v[156:159], v[172:175], v[40:43]
	v_mfma_f32_16x16x32_bf16 v[40:43], v[160:163], v[176:179], v[40:43]
	v_mfma_f32_16x16x32_bf16 v[36:39], v[164:167], v[172:175], v[36:39]
	v_mfma_f32_16x16x32_bf16 v[36:39], v[168:171], v[176:179], v[36:39]
	v_mfma_f32_16x16x32_bf16 v[28:31], v[164:167], v[180:183], v[28:31]
	v_mfma_f32_16x16x32_bf16 v[28:31], v[168:171], v[184:187], v[28:31]
	v_mfma_f32_16x16x32_bf16 v[32:35], v[156:159], v[180:183], v[32:35]
	v_mfma_f32_16x16x32_bf16 v[32:35], v[160:163], v[184:187], v[32:35]
	v_mfma_f32_16x16x32_bf16 v[60:63], v[148:151], v[180:183], v[60:63]
	v_mfma_f32_16x16x32_bf16 v[60:63], v[152:155], v[184:187], v[60:63]
	v_mfma_f32_16x16x32_bf16 v[64:67], v[140:143], v[180:183], v[64:67]
	v_mfma_f32_16x16x32_bf16 v[64:67], v[144:147], v[184:187], v[64:67]
	v_mfma_f32_16x16x32_bf16 v[56:59], v[140:143], v[188:191], v[56:59]
	v_mfma_f32_16x16x32_bf16 v[56:59], v[144:147], v[192:195], v[56:59]
	v_mfma_f32_16x16x32_bf16 v[52:55], v[148:151], v[188:191], v[52:55]
	v_mfma_f32_16x16x32_bf16 v[52:55], v[152:155], v[192:195], v[52:55]
	v_mfma_f32_16x16x32_bf16 v[24:27], v[156:159], v[188:191], v[24:27]
	v_mfma_f32_16x16x32_bf16 v[24:27], v[160:163], v[192:195], v[24:27]
	v_mfma_f32_16x16x32_bf16 v[20:23], v[164:167], v[188:191], v[20:23]
	v_mfma_f32_16x16x32_bf16 v[20:23], v[168:171], v[192:195], v[20:23]
	v_mfma_f32_16x16x32_bf16 v[12:15], v[164:167], v[196:199], v[12:15]
	v_mfma_f32_16x16x32_bf16 v[12:15], v[168:171], v[200:203], v[12:15]
	v_mfma_f32_16x16x32_bf16 v[16:19], v[156:159], v[196:199], v[16:19]
	v_mfma_f32_16x16x32_bf16 v[16:19], v[160:163], v[200:203], v[16:19]
	v_mfma_f32_16x16x32_bf16 v[44:47], v[148:151], v[196:199], v[44:47]
	v_mfma_f32_16x16x32_bf16 v[44:47], v[152:155], v[200:203], v[44:47]
	v_mfma_f32_16x16x32_bf16 v[48:51], v[140:143], v[196:199], v[48:51]
	v_mfma_f32_16x16x32_bf16 v[48:51], v[144:147], v[200:203], v[48:51]
	s_setprio 0
	s_barrier
	s_add_i32 s68, 0, 0x18000
	v_add_u32_e32 v5, s68, v3
	s_add_i32 s70, 0, 0x1c000
	ds_read_b128 v[140:143], v5
	ds_read_b128 v[144:147], v5 offset:1024
	ds_read_b128 v[148:151], v5 offset:2048
	ds_read_b128 v[152:155], v5 offset:3072
	v_add_u32_e32 v5, s70, v3
	ds_read_b128 v[156:159], v5
	ds_read_b128 v[160:163], v5 offset:1024
	ds_read_b128 v[164:167], v5 offset:2048
	ds_read_b128 v[168:171], v5 offset:3072
	s_add_u32 s98, s50, 0x80000
	s_addc_u32 s99, s51, 0
	s_mov_b64 s[100:101], s[50:51]
	s_mov_b32 m0, s49
	ds_read_b128 v[172:175], v246 offset:32768
	ds_read_b128 v[176:179], v246 offset:33792
	ds_read_b128 v[180:183], v246 offset:34816
	ds_read_b128 v[184:187], v246 offset:35840
	ds_read_b128 v[188:191], v246 offset:36864
	ds_read_b128 v[192:195], v246 offset:37888
	ds_read_b128 v[196:199], v246 offset:38912
	ds_read_b128 v[200:203], v246 offset:39936
	global_load_lds_dwordx4 v208, s[98:99]
	s_mov_b32 m0, s52
	s_nop 0
	global_load_lds_dwordx4 v212, s[98:99]
	s_waitcnt vmcnt(8) lgkmcnt(0)
	s_setprio 1
	s_barrier
	v_mfma_f32_16x16x32_bf16 v[136:139], v[140:143], v[172:175], v[136:139]
	v_mfma_f32_16x16x32_bf16 v[136:139], v[144:147], v[176:179], v[136:139]
	v_mfma_f32_16x16x32_bf16 v[132:135], v[148:151], v[172:175], v[132:135]
	v_mfma_f32_16x16x32_bf16 v[132:135], v[152:155], v[176:179], v[132:135]
	v_mfma_f32_16x16x32_bf16 v[104:107], v[156:159], v[172:175], v[104:107]
	v_mfma_f32_16x16x32_bf16 v[104:107], v[160:163], v[176:179], v[104:107]
	v_mfma_f32_16x16x32_bf16 v[100:103], v[164:167], v[172:175], v[100:103]
	v_mfma_f32_16x16x32_bf16 v[100:103], v[168:171], v[176:179], v[100:103]
	v_mfma_f32_16x16x32_bf16 v[92:95], v[164:167], v[180:183], v[92:95]
	v_mfma_f32_16x16x32_bf16 v[92:95], v[168:171], v[184:187], v[92:95]
	v_mfma_f32_16x16x32_bf16 v[96:99], v[156:159], v[180:183], v[96:99]
	v_mfma_f32_16x16x32_bf16 v[96:99], v[160:163], v[184:187], v[96:99]
	v_mfma_f32_16x16x32_bf16 v[124:127], v[148:151], v[180:183], v[124:127]
	v_mfma_f32_16x16x32_bf16 v[124:127], v[152:155], v[184:187], v[124:127]
	v_mfma_f32_16x16x32_bf16 v[128:131], v[140:143], v[180:183], v[128:131]
	v_mfma_f32_16x16x32_bf16 v[128:131], v[144:147], v[184:187], v[128:131]
	v_mfma_f32_16x16x32_bf16 v[120:123], v[140:143], v[188:191], v[120:123]
	v_mfma_f32_16x16x32_bf16 v[120:123], v[144:147], v[192:195], v[120:123]
	v_mfma_f32_16x16x32_bf16 v[116:119], v[148:151], v[188:191], v[116:119]
	v_mfma_f32_16x16x32_bf16 v[116:119], v[152:155], v[192:195], v[116:119]
	v_mfma_f32_16x16x32_bf16 v[88:91], v[156:159], v[188:191], v[88:91]
	v_mfma_f32_16x16x32_bf16 v[88:91], v[160:163], v[192:195], v[88:91]
	v_mfma_f32_16x16x32_bf16 v[84:87], v[164:167], v[188:191], v[84:87]
	v_mfma_f32_16x16x32_bf16 v[84:87], v[168:171], v[192:195], v[84:87]
	v_mfma_f32_16x16x32_bf16 v[76:79], v[164:167], v[196:199], v[76:79]
	v_mfma_f32_16x16x32_bf16 v[76:79], v[168:171], v[200:203], v[76:79]
	v_mfma_f32_16x16x32_bf16 v[80:83], v[156:159], v[196:199], v[80:83]
	v_mfma_f32_16x16x32_bf16 v[80:83], v[160:163], v[200:203], v[80:83]
	v_mfma_f32_16x16x32_bf16 v[108:111], v[148:151], v[196:199], v[108:111]
	v_mfma_f32_16x16x32_bf16 v[108:111], v[152:155], v[200:203], v[108:111]
	v_mfma_f32_16x16x32_bf16 v[112:115], v[140:143], v[196:199], v[112:115]
	v_mfma_f32_16x16x32_bf16 v[112:115], v[144:147], v[200:203], v[112:115]
	s_setprio 0
	s_barrier
	s_add_i32 s50, s68, s46
	s_add_i32 m0, s50, 0xffffff80
	ds_read_b128 v[172:175], v246 offset:49152
	ds_read_b128 v[176:179], v246 offset:50176
	ds_read_b128 v[180:183], v246 offset:51200
	ds_read_b128 v[184:187], v246 offset:52224
	ds_read_b128 v[188:191], v246 offset:53248
	ds_read_b128 v[192:195], v246 offset:54272
	ds_read_b128 v[196:199], v246 offset:55296
	ds_read_b128 v[200:203], v246 offset:56320
	global_load_lds_dwordx4 v210, s[42:43] offset:128
	s_add_i32 m0, s50, 0x1f80
	s_add_i32 s50, s70, s46
	global_load_lds_dwordx4 v214, s[42:43] offset:128
	s_add_u32 s42, s42, 0x80080
	s_addc_u32 s43, s43, 0
	s_mov_b32 m0, s50
	s_nop 0
	global_load_lds_dwordx4 v210, s[42:43]
	s_add_i32 m0, s50, 0x2000
	s_nop 0
	global_load_lds_dwordx4 v214, s[42:43]
	s_add_i32 m0, s58, 0xffffff80
	s_nop 0
	global_load_lds_dwordx4 v208, s[100:101] offset:128
	s_add_i32 m0, s59, 0xffffff80
	s_nop 0
	global_load_lds_dwordx4 v212, s[100:101] offset:128
	s_waitcnt vmcnt(8) lgkmcnt(0)
	s_setprio 1
	s_barrier
	v_mfma_f32_16x16x32_bf16 v[72:75], v[140:143], v[172:175], v[72:75]
	v_mfma_f32_16x16x32_bf16 v[72:75], v[144:147], v[176:179], v[72:75]
	v_mfma_f32_16x16x32_bf16 v[68:71], v[148:151], v[172:175], v[68:71]
	v_mfma_f32_16x16x32_bf16 v[68:71], v[152:155], v[176:179], v[68:71]
	v_mfma_f32_16x16x32_bf16 v[40:43], v[156:159], v[172:175], v[40:43]
	v_mfma_f32_16x16x32_bf16 v[40:43], v[160:163], v[176:179], v[40:43]
	v_mfma_f32_16x16x32_bf16 v[36:39], v[164:167], v[172:175], v[36:39]
	v_mfma_f32_16x16x32_bf16 v[36:39], v[168:171], v[176:179], v[36:39]
	v_mfma_f32_16x16x32_bf16 v[28:31], v[164:167], v[180:183], v[28:31]
	v_mfma_f32_16x16x32_bf16 v[28:31], v[168:171], v[184:187], v[28:31]
	v_mfma_f32_16x16x32_bf16 v[32:35], v[156:159], v[180:183], v[32:35]
	v_mfma_f32_16x16x32_bf16 v[32:35], v[160:163], v[184:187], v[32:35]
	v_mfma_f32_16x16x32_bf16 v[60:63], v[148:151], v[180:183], v[60:63]
	v_mfma_f32_16x16x32_bf16 v[60:63], v[152:155], v[184:187], v[60:63]
	v_mfma_f32_16x16x32_bf16 v[64:67], v[140:143], v[180:183], v[64:67]
	v_mfma_f32_16x16x32_bf16 v[64:67], v[144:147], v[184:187], v[64:67]
	v_mfma_f32_16x16x32_bf16 v[56:59], v[140:143], v[188:191], v[56:59]
	v_mfma_f32_16x16x32_bf16 v[56:59], v[144:147], v[192:195], v[56:59]
	v_mfma_f32_16x16x32_bf16 v[52:55], v[148:151], v[188:191], v[52:55]
	v_mfma_f32_16x16x32_bf16 v[52:55], v[152:155], v[192:195], v[52:55]
	v_mfma_f32_16x16x32_bf16 v[24:27], v[156:159], v[188:191], v[24:27]
	v_mfma_f32_16x16x32_bf16 v[24:27], v[160:163], v[192:195], v[24:27]
	v_mfma_f32_16x16x32_bf16 v[20:23], v[164:167], v[188:191], v[20:23]
	v_mfma_f32_16x16x32_bf16 v[20:23], v[168:171], v[192:195], v[20:23]
	v_mfma_f32_16x16x32_bf16 v[12:15], v[164:167], v[196:199], v[12:15]
	v_mfma_f32_16x16x32_bf16 v[12:15], v[168:171], v[200:203], v[12:15]
	v_mfma_f32_16x16x32_bf16 v[16:19], v[156:159], v[196:199], v[16:19]
	v_mfma_f32_16x16x32_bf16 v[16:19], v[160:163], v[200:203], v[16:19]
	v_mfma_f32_16x16x32_bf16 v[44:47], v[148:151], v[196:199], v[44:47]
	v_mfma_f32_16x16x32_bf16 v[44:47], v[152:155], v[200:203], v[44:47]
	v_mfma_f32_16x16x32_bf16 v[48:51], v[140:143], v[196:199], v[48:51]
	v_mfma_f32_16x16x32_bf16 v[48:51], v[144:147], v[200:203], v[48:51]
	s_setprio 0
	s_barrier
	s_add_i32 s67, s67, 2
	s_add_u32 s40, s40, 0x100
	s_addc_u32 s41, s41, 0
	s_add_u32 s65, s65, 0x100
	s_addc_u32 s66, s66, 0
	s_cmp_gt_u32 s67, 29
	s_cbranch_scc0 .LBB0_1032
	s_and_b64 vcc, exec, s[22:23]
	s_cbranch_vccz .LBB0_1035
	s_barrier

.LBB0_1203:
	ds_read_b128 v[132:135], v187
	ds_read_b128 v[136:139], v187 offset:1024
	ds_read_b128 v[140:143], v187 offset:2048
	ds_read_b128 v[144:147], v187 offset:3072
	ds_read_b128 v[148:151], v188
	ds_read_b128 v[152:155], v188 offset:1024
	ds_read_b128 v[172:175], v188 offset:2048
	ds_read_b128 v[176:179], v188 offset:3072
	s_add_u32 s0, s42, 0xfff00080
	s_addc_u32 s50, s43, -1
	s_cmp_eq_u32 s65, 60
	s_cselect_b32 s53, s25, s50
	s_cselect_b32 s52, s31, s0
	s_cselect_b32 s51, s23, s64
	s_cselect_b32 s50, s62, s63
	s_add_i32 m0, s41, 0xc000
	ds_read_b128 v[180:183], v189
	ds_read_b128 v[192:195], v189 offset:1024
	ds_read_b128 v[196:199], v189 offset:2048
	ds_read_b128 v[200:203], v189 offset:3072
	ds_read_b128 v[204:207], v189 offset:4096
	ds_read_b128 v[208:211], v189 offset:5120
	ds_read_b128 v[212:215], v189 offset:6144
	ds_read_b128 v[216:219], v189 offset:7168
	global_load_lds_dwordx4 v164, s[42:43]
	s_add_i32 m0, s41, 0xe000
	s_nop 0
	global_load_lds_dwordx4 v166, s[42:43]
	s_waitcnt vmcnt(8) lgkmcnt(0)
	s_setprio 1
	s_barrier
	v_mfma_f32_16x16x32_bf16 v[128:131], v[132:135], v[180:183], v[128:131]
	v_mfma_f32_16x16x32_bf16 v[128:131], v[136:139], v[192:195], v[128:131]
	v_mfma_f32_16x16x32_bf16 v[124:127], v[140:143], v[180:183], v[124:127]
	v_mfma_f32_16x16x32_bf16 v[124:127], v[144:147], v[192:195], v[124:127]
	v_mfma_f32_16x16x32_bf16 v[120:123], v[148:151], v[180:183], v[120:123]
	v_mfma_f32_16x16x32_bf16 v[120:123], v[152:155], v[192:195], v[120:123]
	v_mfma_f32_16x16x32_bf16 v[116:119], v[172:175], v[180:183], v[116:119]
	v_mfma_f32_16x16x32_bf16 v[116:119], v[176:179], v[192:195], v[116:119]
	v_mfma_f32_16x16x32_bf16 v[100:103], v[172:175], v[196:199], v[100:103]
	v_mfma_f32_16x16x32_bf16 v[100:103], v[176:179], v[200:203], v[100:103]
	v_mfma_f32_16x16x32_bf16 v[104:107], v[148:151], v[196:199], v[104:107]
	v_mfma_f32_16x16x32_bf16 v[104:107], v[152:155], v[200:203], v[104:107]
	v_mfma_f32_16x16x32_bf16 v[108:111], v[140:143], v[196:199], v[108:111]
	v_mfma_f32_16x16x32_bf16 v[108:111], v[144:147], v[200:203], v[108:111]
	v_mfma_f32_16x16x32_bf16 v[112:115], v[132:135], v[196:199], v[112:115]
	v_mfma_f32_16x16x32_bf16 v[112:115], v[136:139], v[200:203], v[112:115]
	v_mfma_f32_16x16x32_bf16 v[96:99], v[132:135], v[204:207], v[96:99]
	v_mfma_f32_16x16x32_bf16 v[96:99], v[136:139], v[208:211], v[96:99]
	v_mfma_f32_16x16x32_bf16 v[92:95], v[140:143], v[204:207], v[92:95]
	v_mfma_f32_16x16x32_bf16 v[92:95], v[144:147], v[208:211], v[92:95]
	v_mfma_f32_16x16x32_bf16 v[88:91], v[148:151], v[204:207], v[88:91]
	v_mfma_f32_16x16x32_bf16 v[88:91], v[152:155], v[208:211], v[88:91]
	v_mfma_f32_16x16x32_bf16 v[84:87], v[172:175], v[204:207], v[84:87]
	v_mfma_f32_16x16x32_bf16 v[84:87], v[176:179], v[208:211], v[84:87]
	v_mfma_f32_16x16x32_bf16 v[68:71], v[172:175], v[212:215], v[68:71]
	v_mfma_f32_16x16x32_bf16 v[68:71], v[176:179], v[216:219], v[68:71]
	v_mfma_f32_16x16x32_bf16 v[72:75], v[148:151], v[212:215], v[72:75]
	v_mfma_f32_16x16x32_bf16 v[72:75], v[152:155], v[216:219], v[72:75]
	v_mfma_f32_16x16x32_bf16 v[76:79], v[140:143], v[212:215], v[76:79]
	v_mfma_f32_16x16x32_bf16 v[76:79], v[144:147], v[216:219], v[76:79]
	v_mfma_f32_16x16x32_bf16 v[80:83], v[132:135], v[212:215], v[80:83]
	v_mfma_f32_16x16x32_bf16 v[80:83], v[136:139], v[216:219], v[80:83]
	s_setprio 0
	s_barrier
	s_add_i32 s0, s59, s46
	s_mov_b32 m0, s0
	ds_read_b128 v[180:183], v189 offset:16384
	ds_read_b128 v[192:195], v189 offset:17408
	ds_read_b128 v[196:199], v189 offset:18432
	ds_read_b128 v[200:203], v189 offset:19456
	ds_read_b128 v[204:207], v189 offset:20480
	ds_read_b128 v[208:211], v189 offset:21504
	ds_read_b128 v[212:215], v189 offset:22528
	ds_read_b128 v[216:219], v189 offset:23552
	global_load_lds_dwordx4 v158, s[50:51]
	s_add_i32 m0, s0, 0x2000
	s_add_u32 s66, s50, 0x100000
	s_addc_u32 s67, s51, 0
	s_add_i32 s0, s60, s46
	global_load_lds_dwordx4 v162, s[50:51]
	s_mov_b32 m0, s0
	s_nop 0
	global_load_lds_dwordx4 v158, s[66:67]
	s_add_i32 m0, s0, 0x2000
	s_nop 0
	global_load_lds_dwordx4 v162, s[66:67]
	s_mov_b32 m0, s41
	s_nop 0
	global_load_lds_dwordx4 v156, s[52:53]
	s_mov_b32 m0, s47
	s_nop 0
	global_load_lds_dwordx4 v160, s[52:53]
	s_waitcnt vmcnt(8) lgkmcnt(0)
	s_setprio 1
	s_barrier
	v_mfma_f32_16x16x32_bf16 v[64:67], v[132:135], v[180:183], v[64:67]
	v_mfma_f32_16x16x32_bf16 v[64:67], v[136:139], v[192:195], v[64:67]
	v_mfma_f32_16x16x32_bf16 v[60:63], v[140:143], v[180:183], v[60:63]
	v_mfma_f32_16x16x32_bf16 v[60:63], v[144:147], v[192:195], v[60:63]
	v_mfma_f32_16x16x32_bf16 v[56:59], v[148:151], v[180:183], v[56:59]
	v_mfma_f32_16x16x32_bf16 v[56:59], v[152:155], v[192:195], v[56:59]
	v_mfma_f32_16x16x32_bf16 v[52:55], v[172:175], v[180:183], v[52:55]
	v_mfma_f32_16x16x32_bf16 v[52:55], v[176:179], v[192:195], v[52:55]
	v_mfma_f32_16x16x32_bf16 v[36:39], v[172:175], v[196:199], v[36:39]
	v_mfma_f32_16x16x32_bf16 v[36:39], v[176:179], v[200:203], v[36:39]
	v_mfma_f32_16x16x32_bf16 v[40:43], v[148:151], v[196:199], v[40:43]
	v_mfma_f32_16x16x32_bf16 v[40:43], v[152:155], v[200:203], v[40:43]
	v_mfma_f32_16x16x32_bf16 v[44:47], v[140:143], v[196:199], v[44:47]
	v_mfma_f32_16x16x32_bf16 v[44:47], v[144:147], v[200:203], v[44:47]
	v_mfma_f32_16x16x32_bf16 v[48:51], v[132:135], v[196:199], v[48:51]
	v_mfma_f32_16x16x32_bf16 v[48:51], v[136:139], v[200:203], v[48:51]
	v_mfma_f32_16x16x32_bf16 v[32:35], v[132:135], v[204:207], v[32:35]
	v_mfma_f32_16x16x32_bf16 v[32:35], v[136:139], v[208:211], v[32:35]
	v_mfma_f32_16x16x32_bf16 v[28:31], v[140:143], v[204:207], v[28:31]
	v_mfma_f32_16x16x32_bf16 v[28:31], v[144:147], v[208:211], v[28:31]
	v_mfma_f32_16x16x32_bf16 v[24:27], v[148:151], v[204:207], v[24:27]
	v_mfma_f32_16x16x32_bf16 v[24:27], v[152:155], v[208:211], v[24:27]
	v_mfma_f32_16x16x32_bf16 v[20:23], v[172:175], v[204:207], v[20:23]
	v_mfma_f32_16x16x32_bf16 v[20:23], v[176:179], v[208:211], v[20:23]
	v_mfma_f32_16x16x32_bf16 v[4:7], v[172:175], v[212:215], v[4:7]
	v_mfma_f32_16x16x32_bf16 v[4:7], v[176:179], v[216:219], v[4:7]
	v_mfma_f32_16x16x32_bf16 v[8:11], v[148:151], v[212:215], v[8:11]
	v_mfma_f32_16x16x32_bf16 v[8:11], v[152:155], v[216:219], v[8:11]
	v_mfma_f32_16x16x32_bf16 v[12:15], v[140:143], v[212:215], v[12:15]
	v_mfma_f32_16x16x32_bf16 v[12:15], v[144:147], v[216:219], v[12:15]
	v_mfma_f32_16x16x32_bf16 v[16:19], v[132:135], v[212:215], v[16:19]
	v_mfma_f32_16x16x32_bf16 v[16:19], v[136:139], v[216:219], v[16:19]
	s_setprio 0
	s_barrier
	s_add_i32 s0, 0, 0x18000
	s_add_i32 s66, 0, 0x1c000
	v_add_u32_e32 v144, s0, v3
	v_add_u32_e32 v176, s66, v3
	ds_read_b128 v[132:135], v144
	ds_read_b128 v[136:139], v144 offset:1024
	ds_read_b128 v[140:143], v144 offset:2048
	ds_read_b128 v[144:147], v144 offset:3072
	ds_read_b128 v[148:151], v176
	ds_read_b128 v[152:155], v176 offset:1024
	ds_read_b128 v[172:175], v176 offset:2048
	ds_read_b128 v[176:179], v176 offset:3072
	s_add_u32 s98, s52, 0x100000
	s_addc_u32 s99, s53, 0
	s_mov_b32 m0, s48
	ds_read_b128 v[180:183], v189 offset:32768
	ds_read_b128 v[192:195], v189 offset:33792
	ds_read_b128 v[196:199], v189 offset:34816
	ds_read_b128 v[200:203], v189 offset:35840
	ds_read_b128 v[204:207], v189 offset:36864
	ds_read_b128 v[208:211], v189 offset:37888
	ds_read_b128 v[212:215], v189 offset:38912
	ds_read_b128 v[216:219], v189 offset:39936
	global_load_lds_dwordx4 v156, s[98:99]
	s_mov_b32 m0, s49
	s_nop 0
	global_load_lds_dwordx4 v160, s[98:99]
	s_waitcnt vmcnt(8) lgkmcnt(0)
	s_setprio 1
	s_barrier
	v_mfma_f32_16x16x32_bf16 v[128:131], v[132:135], v[180:183], v[128:131]
	v_mfma_f32_16x16x32_bf16 v[128:131], v[136:139], v[192:195], v[128:131]
	v_mfma_f32_16x16x32_bf16 v[124:127], v[140:143], v[180:183], v[124:127]
	v_mfma_f32_16x16x32_bf16 v[124:127], v[144:147], v[192:195], v[124:127]
	v_mfma_f32_16x16x32_bf16 v[120:123], v[148:151], v[180:183], v[120:123]
	v_mfma_f32_16x16x32_bf16 v[120:123], v[152:155], v[192:195], v[120:123]
	v_mfma_f32_16x16x32_bf16 v[116:119], v[172:175], v[180:183], v[116:119]
	v_mfma_f32_16x16x32_bf16 v[116:119], v[176:179], v[192:195], v[116:119]
	v_mfma_f32_16x16x32_bf16 v[100:103], v[172:175], v[196:199], v[100:103]
	v_mfma_f32_16x16x32_bf16 v[100:103], v[176:179], v[200:203], v[100:103]
	v_mfma_f32_16x16x32_bf16 v[104:107], v[148:151], v[196:199], v[104:107]
	v_mfma_f32_16x16x32_bf16 v[104:107], v[152:155], v[200:203], v[104:107]
	v_mfma_f32_16x16x32_bf16 v[108:111], v[140:143], v[196:199], v[108:111]
	v_mfma_f32_16x16x32_bf16 v[108:111], v[144:147], v[200:203], v[108:111]
	v_mfma_f32_16x16x32_bf16 v[112:115], v[132:135], v[196:199], v[112:115]
	v_mfma_f32_16x16x32_bf16 v[112:115], v[136:139], v[200:203], v[112:115]
	v_mfma_f32_16x16x32_bf16 v[96:99], v[132:135], v[204:207], v[96:99]
	v_mfma_f32_16x16x32_bf16 v[96:99], v[136:139], v[208:211], v[96:99]
	v_mfma_f32_16x16x32_bf16 v[92:95], v[140:143], v[204:207], v[92:95]
	v_mfma_f32_16x16x32_bf16 v[92:95], v[144:147], v[208:211], v[92:95]
	v_mfma_f32_16x16x32_bf16 v[88:91], v[148:151], v[204:207], v[88:91]
	v_mfma_f32_16x16x32_bf16 v[88:91], v[152:155], v[208:211], v[88:91]
	v_mfma_f32_16x16x32_bf16 v[84:87], v[172:175], v[204:207], v[84:87]
	v_mfma_f32_16x16x32_bf16 v[84:87], v[176:179], v[208:211], v[84:87]
	v_mfma_f32_16x16x32_bf16 v[68:71], v[172:175], v[212:215], v[68:71]
	v_mfma_f32_16x16x32_bf16 v[68:71], v[176:179], v[216:219], v[68:71]
	v_mfma_f32_16x16x32_bf16 v[72:75], v[148:151], v[212:215], v[72:75]
	v_mfma_f32_16x16x32_bf16 v[72:75], v[152:155], v[216:219], v[72:75]
	v_mfma_f32_16x16x32_bf16 v[76:79], v[140:143], v[212:215], v[76:79]
	v_mfma_f32_16x16x32_bf16 v[76:79], v[144:147], v[216:219], v[76:79]
	v_mfma_f32_16x16x32_bf16 v[80:83], v[132:135], v[212:215], v[80:83]
	v_mfma_f32_16x16x32_bf16 v[80:83], v[136:139], v[216:219], v[80:83]
	s_setprio 0
	s_barrier
	s_add_i32 s0, s0, s46
	s_add_i32 m0, s0, 0xffffff80
	ds_read_b128 v[180:183], v189 offset:49152
	ds_read_b128 v[192:195], v189 offset:50176
	ds_read_b128 v[196:199], v189 offset:51200
	ds_read_b128 v[200:203], v189 offset:52224
	ds_read_b128 v[204:207], v189 offset:53248
	ds_read_b128 v[208:211], v189 offset:54272
	ds_read_b128 v[212:215], v189 offset:55296
	ds_read_b128 v[216:219], v189 offset:56320
	global_load_lds_dwordx4 v158, s[50:51] offset:128
	s_add_i32 m0, s0, 0x1f80
	s_add_i32 s0, s66, s46
	global_load_lds_dwordx4 v162, s[50:51] offset:128
	s_add_u32 s50, s50, 0x100080
	s_addc_u32 s51, s51, 0
	s_mov_b32 m0, s0
	s_nop 0
	global_load_lds_dwordx4 v158, s[50:51]
	s_add_i32 m0, s0, 0x2000
	s_nop 0
	global_load_lds_dwordx4 v162, s[50:51]
	s_add_i32 m0, s57, 0xffffff80
	s_nop 0
	global_load_lds_dwordx4 v156, s[52:53] offset:128
	s_add_i32 m0, s58, 0xffffff80
	s_nop 0
	global_load_lds_dwordx4 v160, s[52:53] offset:128
	s_waitcnt vmcnt(8) lgkmcnt(0)
	s_setprio 1
	s_barrier
	v_mfma_f32_16x16x32_bf16 v[64:67], v[132:135], v[180:183], v[64:67]
	v_mfma_f32_16x16x32_bf16 v[64:67], v[136:139], v[192:195], v[64:67]
	v_mfma_f32_16x16x32_bf16 v[60:63], v[140:143], v[180:183], v[60:63]
	v_mfma_f32_16x16x32_bf16 v[60:63], v[144:147], v[192:195], v[60:63]
	v_mfma_f32_16x16x32_bf16 v[56:59], v[148:151], v[180:183], v[56:59]
	v_mfma_f32_16x16x32_bf16 v[56:59], v[152:155], v[192:195], v[56:59]
	v_mfma_f32_16x16x32_bf16 v[52:55], v[172:175], v[180:183], v[52:55]
	v_mfma_f32_16x16x32_bf16 v[52:55], v[176:179], v[192:195], v[52:55]
	v_mfma_f32_16x16x32_bf16 v[36:39], v[172:175], v[196:199], v[36:39]
	v_mfma_f32_16x16x32_bf16 v[36:39], v[176:179], v[200:203], v[36:39]
	v_mfma_f32_16x16x32_bf16 v[40:43], v[148:151], v[196:199], v[40:43]
	v_mfma_f32_16x16x32_bf16 v[40:43], v[152:155], v[200:203], v[40:43]
	v_mfma_f32_16x16x32_bf16 v[44:47], v[140:143], v[196:199], v[44:47]
	v_mfma_f32_16x16x32_bf16 v[44:47], v[144:147], v[200:203], v[44:47]
	v_mfma_f32_16x16x32_bf16 v[48:51], v[132:135], v[196:199], v[48:51]
	v_mfma_f32_16x16x32_bf16 v[48:51], v[136:139], v[200:203], v[48:51]
	v_mfma_f32_16x16x32_bf16 v[32:35], v[132:135], v[204:207], v[32:35]
	v_mfma_f32_16x16x32_bf16 v[32:35], v[136:139], v[208:211], v[32:35]
	v_mfma_f32_16x16x32_bf16 v[28:31], v[140:143], v[204:207], v[28:31]
	v_mfma_f32_16x16x32_bf16 v[28:31], v[144:147], v[208:211], v[28:31]
	v_mfma_f32_16x16x32_bf16 v[24:27], v[148:151], v[204:207], v[24:27]
	v_mfma_f32_16x16x32_bf16 v[24:27], v[152:155], v[208:211], v[24:27]
	v_mfma_f32_16x16x32_bf16 v[20:23], v[172:175], v[204:207], v[20:23]
	v_mfma_f32_16x16x32_bf16 v[20:23], v[176:179], v[208:211], v[20:23]
	v_mfma_f32_16x16x32_bf16 v[4:7], v[172:175], v[212:215], v[4:7]
	v_mfma_f32_16x16x32_bf16 v[4:7], v[176:179], v[216:219], v[4:7]
	v_mfma_f32_16x16x32_bf16 v[8:11], v[148:151], v[212:215], v[8:11]
	v_mfma_f32_16x16x32_bf16 v[8:11], v[152:155], v[216:219], v[8:11]
	v_mfma_f32_16x16x32_bf16 v[12:15], v[140:143], v[212:215], v[12:15]
	v_mfma_f32_16x16x32_bf16 v[12:15], v[144:147], v[216:219], v[12:15]
	v_mfma_f32_16x16x32_bf16 v[16:19], v[132:135], v[212:215], v[16:19]
	v_mfma_f32_16x16x32_bf16 v[16:19], v[136:139], v[216:219], v[16:19]
	s_setprio 0
	s_barrier
	s_add_i32 s65, s65, 2
	s_add_u32 s42, s42, 0x100
	s_addc_u32 s43, s43, 0
	s_add_u32 s63, s63, 0x100
	s_addc_u32 s64, s64, 0
	s_cmp_gt_u32 s65, 61
	s_cbranch_scc0 .LBB0_1203
	s_and_b64 vcc, exec, s[20:21]
	s_cbranch_vccz .LBB0_1206
	s_barrier

.LBB0_1288:
	ds_read_b128 v[154:157], v150
	ds_read_b128 v[158:161], v150 offset:1024
	ds_read_b128 v[162:165], v150 offset:2048
	ds_read_b128 v[166:169], v150 offset:3072
	ds_read_b128 v[170:173], v151
	ds_read_b128 v[174:177], v151 offset:1024
	ds_read_b128 v[178:181], v151 offset:2048
	ds_read_b128 v[182:185], v151 offset:3072
	s_add_u32 s0, s42, 0xfff00080
	s_addc_u32 s50, s43, -1
	s_cmp_eq_u32 s70, 12
	s_cselect_b32 s53, s29, s50
	s_cselect_b32 s52, s28, s0
	s_cselect_b32 s51, s5, s41
	s_cselect_b32 s50, s4, s31
	s_add_i32 m0, s17, 0xc000
	ds_read_b128 v[186:189], v152
	ds_read_b128 v[190:193], v152 offset:1024
	ds_read_b128 v[194:197], v152 offset:2048
	ds_read_b128 v[198:201], v152 offset:3072
	ds_read_b128 v[202:205], v152 offset:4096
	ds_read_b128 v[206:209], v152 offset:5120
	ds_read_b128 v[210:213], v152 offset:6144
	ds_read_b128 v[214:217], v152 offset:7168
	global_load_lds_dwordx4 v142, s[42:43]
	s_add_i32 m0, s17, 0xe000
	s_nop 0
	global_load_lds_dwordx4 v144, s[42:43]
	s_waitcnt vmcnt(8) lgkmcnt(0)
	s_setprio 1
	s_barrier
	v_mfma_f32_16x16x32_bf16 v[128:131], v[154:157], v[186:189], v[128:131]
	v_mfma_f32_16x16x32_bf16 v[128:131], v[158:161], v[190:193], v[128:131]
	v_mfma_f32_16x16x32_bf16 v[124:127], v[162:165], v[186:189], v[124:127]
	v_mfma_f32_16x16x32_bf16 v[124:127], v[166:169], v[190:193], v[124:127]
	v_mfma_f32_16x16x32_bf16 v[112:115], v[170:173], v[186:189], v[112:115]
	v_mfma_f32_16x16x32_bf16 v[112:115], v[174:177], v[190:193], v[112:115]
	v_mfma_f32_16x16x32_bf16 v[108:111], v[178:181], v[186:189], v[108:111]
	v_mfma_f32_16x16x32_bf16 v[108:111], v[182:185], v[190:193], v[108:111]
	v_mfma_f32_16x16x32_bf16 v[92:95], v[178:181], v[194:197], v[92:95]
	v_mfma_f32_16x16x32_bf16 v[92:95], v[182:185], v[198:201], v[92:95]
	v_mfma_f32_16x16x32_bf16 v[96:99], v[170:173], v[194:197], v[96:99]
	v_mfma_f32_16x16x32_bf16 v[96:99], v[174:177], v[198:201], v[96:99]
	v_mfma_f32_16x16x32_bf16 v[116:119], v[162:165], v[194:197], v[116:119]
	v_mfma_f32_16x16x32_bf16 v[116:119], v[166:169], v[198:201], v[116:119]
	v_mfma_f32_16x16x32_bf16 v[120:123], v[154:157], v[194:197], v[120:123]
	v_mfma_f32_16x16x32_bf16 v[120:123], v[158:161], v[198:201], v[120:123]
	v_mfma_f32_16x16x32_bf16 v[104:107], v[154:157], v[202:205], v[104:107]
	v_mfma_f32_16x16x32_bf16 v[104:107], v[158:161], v[206:209], v[104:107]
	v_mfma_f32_16x16x32_bf16 v[100:103], v[162:165], v[202:205], v[100:103]
	v_mfma_f32_16x16x32_bf16 v[100:103], v[166:169], v[206:209], v[100:103]
	v_mfma_f32_16x16x32_bf16 v[80:83], v[170:173], v[202:205], v[80:83]
	v_mfma_f32_16x16x32_bf16 v[80:83], v[174:177], v[206:209], v[80:83]
	v_mfma_f32_16x16x32_bf16 v[76:79], v[178:181], v[202:205], v[76:79]
	v_mfma_f32_16x16x32_bf16 v[76:79], v[182:185], v[206:209], v[76:79]
	v_mfma_f32_16x16x32_bf16 v[68:71], v[178:181], v[210:213], v[68:71]
	v_mfma_f32_16x16x32_bf16 v[68:71], v[182:185], v[214:217], v[68:71]
	v_mfma_f32_16x16x32_bf16 v[72:75], v[170:173], v[210:213], v[72:75]
	v_mfma_f32_16x16x32_bf16 v[72:75], v[174:177], v[214:217], v[72:75]
	v_mfma_f32_16x16x32_bf16 v[84:87], v[162:165], v[210:213], v[84:87]
	v_mfma_f32_16x16x32_bf16 v[84:87], v[166:169], v[214:217], v[84:87]
	v_mfma_f32_16x16x32_bf16 v[88:91], v[154:157], v[210:213], v[88:91]
	v_mfma_f32_16x16x32_bf16 v[88:91], v[158:161], v[214:217], v[88:91]
	s_setprio 0
	s_barrier
	s_add_i32 s0, s60, s46
	s_mov_b32 m0, s0
	ds_read_b128 v[186:189], v152 offset:16384
	ds_read_b128 v[190:193], v152 offset:17408
	ds_read_b128 v[194:197], v152 offset:18432
	ds_read_b128 v[198:201], v152 offset:19456
	ds_read_b128 v[202:205], v152 offset:20480
	ds_read_b128 v[206:209], v152 offset:21504
	ds_read_b128 v[210:213], v152 offset:22528
	ds_read_b128 v[214:217], v152 offset:23552
	global_load_lds_dwordx4 v136, s[50:51]
	s_add_i32 m0, s0, 0x2000
	s_add_u32 s72, s50, 0x100000
	s_addc_u32 s73, s51, 0
	s_add_i32 s0, s61, s46
	global_load_lds_dwordx4 v132, s[50:51]
	s_mov_b32 m0, s0
	s_nop 0
	global_load_lds_dwordx4 v136, s[72:73]
	s_add_i32 m0, s0, 0x2000
	s_nop 0
	global_load_lds_dwordx4 v132, s[72:73]
	s_mov_b32 m0, s17
	s_nop 0
	global_load_lds_dwordx4 v138, s[52:53]
	s_mov_b32 m0, s47
	s_nop 0
	global_load_lds_dwordx4 v134, s[52:53]
	s_waitcnt vmcnt(8) lgkmcnt(0)
	s_setprio 1
	s_barrier
	v_mfma_f32_16x16x32_bf16 v[64:67], v[154:157], v[186:189], v[64:67]
	v_mfma_f32_16x16x32_bf16 v[64:67], v[158:161], v[190:193], v[64:67]
	v_mfma_f32_16x16x32_bf16 v[60:63], v[162:165], v[186:189], v[60:63]
	v_mfma_f32_16x16x32_bf16 v[60:63], v[166:169], v[190:193], v[60:63]
	v_mfma_f32_16x16x32_bf16 v[48:51], v[170:173], v[186:189], v[48:51]
	v_mfma_f32_16x16x32_bf16 v[48:51], v[174:177], v[190:193], v[48:51]
	v_mfma_f32_16x16x32_bf16 v[44:47], v[178:181], v[186:189], v[44:47]
	v_mfma_f32_16x16x32_bf16 v[44:47], v[182:185], v[190:193], v[44:47]
	v_mfma_f32_16x16x32_bf16 v[28:31], v[178:181], v[194:197], v[28:31]
	v_mfma_f32_16x16x32_bf16 v[28:31], v[182:185], v[198:201], v[28:31]
	v_mfma_f32_16x16x32_bf16 v[32:35], v[170:173], v[194:197], v[32:35]
	v_mfma_f32_16x16x32_bf16 v[32:35], v[174:177], v[198:201], v[32:35]
	v_mfma_f32_16x16x32_bf16 v[52:55], v[162:165], v[194:197], v[52:55]
	v_mfma_f32_16x16x32_bf16 v[52:55], v[166:169], v[198:201], v[52:55]
	v_mfma_f32_16x16x32_bf16 v[56:59], v[154:157], v[194:197], v[56:59]
	v_mfma_f32_16x16x32_bf16 v[56:59], v[158:161], v[198:201], v[56:59]
	v_mfma_f32_16x16x32_bf16 v[40:43], v[154:157], v[202:205], v[40:43]
	v_mfma_f32_16x16x32_bf16 v[40:43], v[158:161], v[206:209], v[40:43]
	v_mfma_f32_16x16x32_bf16 v[36:39], v[162:165], v[202:205], v[36:39]
	v_mfma_f32_16x16x32_bf16 v[36:39], v[166:169], v[206:209], v[36:39]
	v_mfma_f32_16x16x32_bf16 v[16:19], v[170:173], v[202:205], v[16:19]
	v_mfma_f32_16x16x32_bf16 v[16:19], v[174:177], v[206:209], v[16:19]
	v_mfma_f32_16x16x32_bf16 v[12:15], v[178:181], v[202:205], v[12:15]
	v_mfma_f32_16x16x32_bf16 v[12:15], v[182:185], v[206:209], v[12:15]
	v_mfma_f32_16x16x32_bf16 v[4:7], v[178:181], v[210:213], v[4:7]
	v_mfma_f32_16x16x32_bf16 v[4:7], v[182:185], v[214:217], v[4:7]
	v_mfma_f32_16x16x32_bf16 v[8:11], v[170:173], v[210:213], v[8:11]
	v_mfma_f32_16x16x32_bf16 v[8:11], v[174:177], v[214:217], v[8:11]
	v_mfma_f32_16x16x32_bf16 v[20:23], v[162:165], v[210:213], v[20:23]
	v_mfma_f32_16x16x32_bf16 v[20:23], v[166:169], v[214:217], v[20:23]
	v_mfma_f32_16x16x32_bf16 v[24:27], v[154:157], v[210:213], v[24:27]
	v_mfma_f32_16x16x32_bf16 v[24:27], v[158:161], v[214:217], v[24:27]
	s_setprio 0
	s_barrier
	s_add_i32 s0, 0, 0x18000
	v_add_u32_e32 v140, s0, v3
	s_add_i32 s71, 0, 0x1c000
	ds_read_b128 v[154:157], v140
	ds_read_b128 v[158:161], v140 offset:1024
	ds_read_b128 v[162:165], v140 offset:2048
	ds_read_b128 v[166:169], v140 offset:3072
	v_add_u32_e32 v140, s71, v3
	ds_read_b128 v[170:173], v140
	ds_read_b128 v[174:177], v140 offset:1024
	ds_read_b128 v[178:181], v140 offset:2048
	ds_read_b128 v[182:185], v140 offset:3072
	s_add_u32 s98, s52, 0x100000
	s_addc_u32 s99, s53, 0
	s_mov_b32 m0, s48
	ds_read_b128 v[186:189], v152 offset:32768
	ds_read_b128 v[190:193], v152 offset:33792
	ds_read_b128 v[194:197], v152 offset:34816
	ds_read_b128 v[198:201], v152 offset:35840
	ds_read_b128 v[202:205], v152 offset:36864
	ds_read_b128 v[206:209], v152 offset:37888
	ds_read_b128 v[210:213], v152 offset:38912
	ds_read_b128 v[214:217], v152 offset:39936
	global_load_lds_dwordx4 v138, s[98:99]
	s_mov_b32 m0, s49
	s_nop 0
	global_load_lds_dwordx4 v134, s[98:99]
	s_waitcnt vmcnt(8) lgkmcnt(0)
	s_setprio 1
	s_barrier
	v_mfma_f32_16x16x32_bf16 v[128:131], v[154:157], v[186:189], v[128:131]
	v_mfma_f32_16x16x32_bf16 v[128:131], v[158:161], v[190:193], v[128:131]
	v_mfma_f32_16x16x32_bf16 v[124:127], v[162:165], v[186:189], v[124:127]
	v_mfma_f32_16x16x32_bf16 v[124:127], v[166:169], v[190:193], v[124:127]
	v_mfma_f32_16x16x32_bf16 v[112:115], v[170:173], v[186:189], v[112:115]
	v_mfma_f32_16x16x32_bf16 v[112:115], v[174:177], v[190:193], v[112:115]
	v_mfma_f32_16x16x32_bf16 v[108:111], v[178:181], v[186:189], v[108:111]
	v_mfma_f32_16x16x32_bf16 v[108:111], v[182:185], v[190:193], v[108:111]
	v_mfma_f32_16x16x32_bf16 v[92:95], v[178:181], v[194:197], v[92:95]
	v_mfma_f32_16x16x32_bf16 v[92:95], v[182:185], v[198:201], v[92:95]
	v_mfma_f32_16x16x32_bf16 v[96:99], v[170:173], v[194:197], v[96:99]
	v_mfma_f32_16x16x32_bf16 v[96:99], v[174:177], v[198:201], v[96:99]
	v_mfma_f32_16x16x32_bf16 v[116:119], v[162:165], v[194:197], v[116:119]
	v_mfma_f32_16x16x32_bf16 v[116:119], v[166:169], v[198:201], v[116:119]
	v_mfma_f32_16x16x32_bf16 v[120:123], v[154:157], v[194:197], v[120:123]
	v_mfma_f32_16x16x32_bf16 v[120:123], v[158:161], v[198:201], v[120:123]
	v_mfma_f32_16x16x32_bf16 v[104:107], v[154:157], v[202:205], v[104:107]
	v_mfma_f32_16x16x32_bf16 v[104:107], v[158:161], v[206:209], v[104:107]
	v_mfma_f32_16x16x32_bf16 v[100:103], v[162:165], v[202:205], v[100:103]
	v_mfma_f32_16x16x32_bf16 v[100:103], v[166:169], v[206:209], v[100:103]
	v_mfma_f32_16x16x32_bf16 v[80:83], v[170:173], v[202:205], v[80:83]
	v_mfma_f32_16x16x32_bf16 v[80:83], v[174:177], v[206:209], v[80:83]
	v_mfma_f32_16x16x32_bf16 v[76:79], v[178:181], v[202:205], v[76:79]
	v_mfma_f32_16x16x32_bf16 v[76:79], v[182:185], v[206:209], v[76:79]
	v_mfma_f32_16x16x32_bf16 v[68:71], v[178:181], v[210:213], v[68:71]
	v_mfma_f32_16x16x32_bf16 v[68:71], v[182:185], v[214:217], v[68:71]
	v_mfma_f32_16x16x32_bf16 v[72:75], v[170:173], v[210:213], v[72:75]
	v_mfma_f32_16x16x32_bf16 v[72:75], v[174:177], v[214:217], v[72:75]
	v_mfma_f32_16x16x32_bf16 v[84:87], v[162:165], v[210:213], v[84:87]
	v_mfma_f32_16x16x32_bf16 v[84:87], v[166:169], v[214:217], v[84:87]
	v_mfma_f32_16x16x32_bf16 v[88:91], v[154:157], v[210:213], v[88:91]
	v_mfma_f32_16x16x32_bf16 v[88:91], v[158:161], v[214:217], v[88:91]
	s_setprio 0
	s_barrier
	s_add_i32 s0, s0, s46
	s_add_i32 m0, s0, 0xffffff80
	ds_read_b128 v[186:189], v152 offset:49152
	ds_read_b128 v[190:193], v152 offset:50176
	ds_read_b128 v[194:197], v152 offset:51200
	ds_read_b128 v[198:201], v152 offset:52224
	ds_read_b128 v[202:205], v152 offset:53248
	ds_read_b128 v[206:209], v152 offset:54272
	ds_read_b128 v[210:213], v152 offset:55296
	ds_read_b128 v[214:217], v152 offset:56320
	global_load_lds_dwordx4 v136, s[50:51] offset:128
	s_add_i32 m0, s0, 0x1f80
	s_add_i32 s0, s71, s46
	global_load_lds_dwordx4 v132, s[50:51] offset:128
	s_add_u32 s50, s50, 0x100080
	s_addc_u32 s51, s51, 0
	s_mov_b32 m0, s0
	s_nop 0
	global_load_lds_dwordx4 v136, s[50:51]
	s_add_i32 m0, s0, 0x2000
	s_nop 0
	global_load_lds_dwordx4 v132, s[50:51]
	s_add_i32 m0, s58, 0xffffff80
	s_nop 0
	global_load_lds_dwordx4 v138, s[52:53] offset:128
	s_add_i32 m0, s59, 0xffffff80
	s_nop 0
	global_load_lds_dwordx4 v134, s[52:53] offset:128
	s_waitcnt vmcnt(8) lgkmcnt(0)
	s_setprio 1
	s_barrier
	v_mfma_f32_16x16x32_bf16 v[64:67], v[154:157], v[186:189], v[64:67]
	v_mfma_f32_16x16x32_bf16 v[64:67], v[158:161], v[190:193], v[64:67]
	v_mfma_f32_16x16x32_bf16 v[60:63], v[162:165], v[186:189], v[60:63]
	v_mfma_f32_16x16x32_bf16 v[60:63], v[166:169], v[190:193], v[60:63]
	v_mfma_f32_16x16x32_bf16 v[48:51], v[170:173], v[186:189], v[48:51]
	v_mfma_f32_16x16x32_bf16 v[48:51], v[174:177], v[190:193], v[48:51]
	v_mfma_f32_16x16x32_bf16 v[44:47], v[178:181], v[186:189], v[44:47]
	v_mfma_f32_16x16x32_bf16 v[44:47], v[182:185], v[190:193], v[44:47]
	v_mfma_f32_16x16x32_bf16 v[28:31], v[178:181], v[194:197], v[28:31]
	v_mfma_f32_16x16x32_bf16 v[28:31], v[182:185], v[198:201], v[28:31]
	v_mfma_f32_16x16x32_bf16 v[32:35], v[170:173], v[194:197], v[32:35]
	v_mfma_f32_16x16x32_bf16 v[32:35], v[174:177], v[198:201], v[32:35]
	v_mfma_f32_16x16x32_bf16 v[52:55], v[162:165], v[194:197], v[52:55]
	v_mfma_f32_16x16x32_bf16 v[52:55], v[166:169], v[198:201], v[52:55]
	v_mfma_f32_16x16x32_bf16 v[56:59], v[154:157], v[194:197], v[56:59]
	v_mfma_f32_16x16x32_bf16 v[56:59], v[158:161], v[198:201], v[56:59]
	v_mfma_f32_16x16x32_bf16 v[40:43], v[154:157], v[202:205], v[40:43]
	v_mfma_f32_16x16x32_bf16 v[40:43], v[158:161], v[206:209], v[40:43]
	v_mfma_f32_16x16x32_bf16 v[36:39], v[162:165], v[202:205], v[36:39]
	v_mfma_f32_16x16x32_bf16 v[36:39], v[166:169], v[206:209], v[36:39]
	v_mfma_f32_16x16x32_bf16 v[16:19], v[170:173], v[202:205], v[16:19]
	v_mfma_f32_16x16x32_bf16 v[16:19], v[174:177], v[206:209], v[16:19]
	v_mfma_f32_16x16x32_bf16 v[12:15], v[178:181], v[202:205], v[12:15]
	v_mfma_f32_16x16x32_bf16 v[12:15], v[182:185], v[206:209], v[12:15]
	v_mfma_f32_16x16x32_bf16 v[4:7], v[178:181], v[210:213], v[4:7]
	v_mfma_f32_16x16x32_bf16 v[4:7], v[182:185], v[214:217], v[4:7]
	v_mfma_f32_16x16x32_bf16 v[8:11], v[170:173], v[210:213], v[8:11]
	v_mfma_f32_16x16x32_bf16 v[8:11], v[174:177], v[214:217], v[8:11]
	v_mfma_f32_16x16x32_bf16 v[20:23], v[162:165], v[210:213], v[20:23]
	v_mfma_f32_16x16x32_bf16 v[20:23], v[166:169], v[214:217], v[20:23]
	v_mfma_f32_16x16x32_bf16 v[24:27], v[154:157], v[210:213], v[24:27]
	v_mfma_f32_16x16x32_bf16 v[24:27], v[158:161], v[214:217], v[24:27]
	s_setprio 0
	s_barrier
	s_add_i32 s70, s70, 2
	s_add_u32 s42, s42, 0x100
	s_addc_u32 s43, s43, 0
	s_add_u32 s31, s31, 0x100
	s_addc_u32 s41, s41, 0
	s_cmp_gt_u32 s70, 13
	s_cbranch_scc0 .LBB0_1288
	s_and_b64 vcc, exec, s[14:15]
	s_cbranch_vccz .LBB0_1291
	s_barrier

.LBB0_1415:
	ds_read_b128 v[132:135], v187
	ds_read_b128 v[136:139], v187 offset:1024
	ds_read_b128 v[140:143], v187 offset:2048
	ds_read_b128 v[144:147], v187 offset:3072
	ds_read_b128 v[148:151], v188
	ds_read_b128 v[152:155], v188 offset:1024
	ds_read_b128 v[172:175], v188 offset:2048
	ds_read_b128 v[176:179], v188 offset:3072
	s_add_u32 s0, s42, 0xfffe0080
	s_addc_u32 s50, s43, -1
	s_cmp_eq_u32 s64, 4
	s_cselect_b32 s53, s25, s50
	s_cselect_b32 s52, s31, s0
	s_cselect_b32 s51, s23, s63
	s_cselect_b32 s50, s61, s62
	s_add_i32 m0, s41, 0xc000
	ds_read_b128 v[180:183], v189
	ds_read_b128 v[192:195], v189 offset:1024
	ds_read_b128 v[196:199], v189 offset:2048
	ds_read_b128 v[200:203], v189 offset:3072
	ds_read_b128 v[204:207], v189 offset:4096
	ds_read_b128 v[208:211], v189 offset:5120
	ds_read_b128 v[212:215], v189 offset:6144
	ds_read_b128 v[216:219], v189 offset:7168
	global_load_lds_dwordx4 v164, s[42:43]
	s_add_i32 m0, s41, 0xe000
	s_nop 0
	global_load_lds_dwordx4 v166, s[42:43]
	s_waitcnt vmcnt(8) lgkmcnt(0)
	s_setprio 1
	s_barrier
	v_mfma_f32_16x16x32_bf16 v[128:131], v[132:135], v[180:183], v[128:131]
	v_mfma_f32_16x16x32_bf16 v[128:131], v[136:139], v[192:195], v[128:131]
	v_mfma_f32_16x16x32_bf16 v[124:127], v[140:143], v[180:183], v[124:127]
	v_mfma_f32_16x16x32_bf16 v[124:127], v[144:147], v[192:195], v[124:127]
	v_mfma_f32_16x16x32_bf16 v[120:123], v[148:151], v[180:183], v[120:123]
	v_mfma_f32_16x16x32_bf16 v[120:123], v[152:155], v[192:195], v[120:123]
	v_mfma_f32_16x16x32_bf16 v[116:119], v[172:175], v[180:183], v[116:119]
	v_mfma_f32_16x16x32_bf16 v[116:119], v[176:179], v[192:195], v[116:119]
	v_mfma_f32_16x16x32_bf16 v[100:103], v[172:175], v[196:199], v[100:103]
	v_mfma_f32_16x16x32_bf16 v[100:103], v[176:179], v[200:203], v[100:103]
	v_mfma_f32_16x16x32_bf16 v[104:107], v[148:151], v[196:199], v[104:107]
	v_mfma_f32_16x16x32_bf16 v[104:107], v[152:155], v[200:203], v[104:107]
	v_mfma_f32_16x16x32_bf16 v[108:111], v[140:143], v[196:199], v[108:111]
	v_mfma_f32_16x16x32_bf16 v[108:111], v[144:147], v[200:203], v[108:111]
	v_mfma_f32_16x16x32_bf16 v[112:115], v[132:135], v[196:199], v[112:115]
	v_mfma_f32_16x16x32_bf16 v[112:115], v[136:139], v[200:203], v[112:115]
	v_mfma_f32_16x16x32_bf16 v[96:99], v[132:135], v[204:207], v[96:99]
	v_mfma_f32_16x16x32_bf16 v[96:99], v[136:139], v[208:211], v[96:99]
	v_mfma_f32_16x16x32_bf16 v[92:95], v[140:143], v[204:207], v[92:95]
	v_mfma_f32_16x16x32_bf16 v[92:95], v[144:147], v[208:211], v[92:95]
	v_mfma_f32_16x16x32_bf16 v[88:91], v[148:151], v[204:207], v[88:91]
	v_mfma_f32_16x16x32_bf16 v[88:91], v[152:155], v[208:211], v[88:91]
	v_mfma_f32_16x16x32_bf16 v[84:87], v[172:175], v[204:207], v[84:87]
	v_mfma_f32_16x16x32_bf16 v[84:87], v[176:179], v[208:211], v[84:87]
	v_mfma_f32_16x16x32_bf16 v[68:71], v[172:175], v[212:215], v[68:71]
	v_mfma_f32_16x16x32_bf16 v[68:71], v[176:179], v[216:219], v[68:71]
	v_mfma_f32_16x16x32_bf16 v[72:75], v[148:151], v[212:215], v[72:75]
	v_mfma_f32_16x16x32_bf16 v[72:75], v[152:155], v[216:219], v[72:75]
	v_mfma_f32_16x16x32_bf16 v[76:79], v[140:143], v[212:215], v[76:79]
	v_mfma_f32_16x16x32_bf16 v[76:79], v[144:147], v[216:219], v[76:79]
	v_mfma_f32_16x16x32_bf16 v[80:83], v[132:135], v[212:215], v[80:83]
	v_mfma_f32_16x16x32_bf16 v[80:83], v[136:139], v[216:219], v[80:83]
	s_setprio 0
	s_barrier
	s_add_i32 s0, s58, s45
	s_mov_b32 m0, s0
	ds_read_b128 v[180:183], v189 offset:16384
	ds_read_b128 v[192:195], v189 offset:17408
	ds_read_b128 v[196:199], v189 offset:18432
	ds_read_b128 v[200:203], v189 offset:19456
	ds_read_b128 v[204:207], v189 offset:20480
	ds_read_b128 v[208:211], v189 offset:21504
	ds_read_b128 v[212:215], v189 offset:22528
	ds_read_b128 v[216:219], v189 offset:23552
	global_load_lds_dwordx4 v158, s[50:51]
	s_add_i32 m0, s0, 0x2000
	s_add_u32 s66, s50, 0x20000
	s_addc_u32 s67, s51, 0
	s_add_i32 s0, s59, s45
	global_load_lds_dwordx4 v162, s[50:51]
	s_mov_b32 m0, s0
	s_nop 0
	global_load_lds_dwordx4 v158, s[66:67]
	s_add_i32 m0, s0, 0x2000
	s_nop 0
	global_load_lds_dwordx4 v162, s[66:67]
	s_mov_b32 m0, s41
	s_nop 0
	global_load_lds_dwordx4 v156, s[52:53]
	s_mov_b32 m0, s46
	s_nop 0
	global_load_lds_dwordx4 v160, s[52:53]
	s_waitcnt vmcnt(8) lgkmcnt(0)
	s_setprio 1
	s_barrier
	v_mfma_f32_16x16x32_bf16 v[64:67], v[132:135], v[180:183], v[64:67]
	v_mfma_f32_16x16x32_bf16 v[64:67], v[136:139], v[192:195], v[64:67]
	v_mfma_f32_16x16x32_bf16 v[60:63], v[140:143], v[180:183], v[60:63]
	v_mfma_f32_16x16x32_bf16 v[60:63], v[144:147], v[192:195], v[60:63]
	v_mfma_f32_16x16x32_bf16 v[56:59], v[148:151], v[180:183], v[56:59]
	v_mfma_f32_16x16x32_bf16 v[56:59], v[152:155], v[192:195], v[56:59]
	v_mfma_f32_16x16x32_bf16 v[52:55], v[172:175], v[180:183], v[52:55]
	v_mfma_f32_16x16x32_bf16 v[52:55], v[176:179], v[192:195], v[52:55]
	v_mfma_f32_16x16x32_bf16 v[36:39], v[172:175], v[196:199], v[36:39]
	v_mfma_f32_16x16x32_bf16 v[36:39], v[176:179], v[200:203], v[36:39]
	v_mfma_f32_16x16x32_bf16 v[40:43], v[148:151], v[196:199], v[40:43]
	v_mfma_f32_16x16x32_bf16 v[40:43], v[152:155], v[200:203], v[40:43]
	v_mfma_f32_16x16x32_bf16 v[44:47], v[140:143], v[196:199], v[44:47]
	v_mfma_f32_16x16x32_bf16 v[44:47], v[144:147], v[200:203], v[44:47]
	v_mfma_f32_16x16x32_bf16 v[48:51], v[132:135], v[196:199], v[48:51]
	v_mfma_f32_16x16x32_bf16 v[48:51], v[136:139], v[200:203], v[48:51]
	v_mfma_f32_16x16x32_bf16 v[32:35], v[132:135], v[204:207], v[32:35]
	v_mfma_f32_16x16x32_bf16 v[32:35], v[136:139], v[208:211], v[32:35]
	v_mfma_f32_16x16x32_bf16 v[28:31], v[140:143], v[204:207], v[28:31]
	v_mfma_f32_16x16x32_bf16 v[28:31], v[144:147], v[208:211], v[28:31]
	v_mfma_f32_16x16x32_bf16 v[24:27], v[148:151], v[204:207], v[24:27]
	v_mfma_f32_16x16x32_bf16 v[24:27], v[152:155], v[208:211], v[24:27]
	v_mfma_f32_16x16x32_bf16 v[20:23], v[172:175], v[204:207], v[20:23]
	v_mfma_f32_16x16x32_bf16 v[20:23], v[176:179], v[208:211], v[20:23]
	v_mfma_f32_16x16x32_bf16 v[4:7], v[172:175], v[212:215], v[4:7]
	v_mfma_f32_16x16x32_bf16 v[4:7], v[176:179], v[216:219], v[4:7]
	v_mfma_f32_16x16x32_bf16 v[8:11], v[148:151], v[212:215], v[8:11]
	v_mfma_f32_16x16x32_bf16 v[8:11], v[152:155], v[216:219], v[8:11]
	v_mfma_f32_16x16x32_bf16 v[12:15], v[140:143], v[212:215], v[12:15]
	v_mfma_f32_16x16x32_bf16 v[12:15], v[144:147], v[216:219], v[12:15]
	v_mfma_f32_16x16x32_bf16 v[16:19], v[132:135], v[212:215], v[16:19]
	v_mfma_f32_16x16x32_bf16 v[16:19], v[136:139], v[216:219], v[16:19]
	s_setprio 0
	s_barrier
	s_add_i32 s0, 0, 0x18000
	s_add_i32 s65, 0, 0x1c000
	v_add_u32_e32 v144, s0, v3
	v_add_u32_e32 v176, s65, v3
	ds_read_b128 v[132:135], v144
	ds_read_b128 v[136:139], v144 offset:1024
	ds_read_b128 v[140:143], v144 offset:2048
	ds_read_b128 v[144:147], v144 offset:3072
	ds_read_b128 v[148:151], v176
	ds_read_b128 v[152:155], v176 offset:1024
	ds_read_b128 v[172:175], v176 offset:2048
	ds_read_b128 v[176:179], v176 offset:3072
	s_add_u32 s98, s52, 0x20000
	s_addc_u32 s99, s53, 0
	s_mov_b32 m0, s47
	ds_read_b128 v[180:183], v189 offset:32768
	ds_read_b128 v[192:195], v189 offset:33792
	ds_read_b128 v[196:199], v189 offset:34816
	ds_read_b128 v[200:203], v189 offset:35840
	ds_read_b128 v[204:207], v189 offset:36864
	ds_read_b128 v[208:211], v189 offset:37888
	ds_read_b128 v[212:215], v189 offset:38912
	ds_read_b128 v[216:219], v189 offset:39936
	global_load_lds_dwordx4 v156, s[98:99]
	s_mov_b32 m0, s48
	s_nop 0
	global_load_lds_dwordx4 v160, s[98:99]
	s_waitcnt vmcnt(8) lgkmcnt(0)
	s_setprio 1
	s_barrier
	v_mfma_f32_16x16x32_bf16 v[128:131], v[132:135], v[180:183], v[128:131]
	v_mfma_f32_16x16x32_bf16 v[128:131], v[136:139], v[192:195], v[128:131]
	v_mfma_f32_16x16x32_bf16 v[124:127], v[140:143], v[180:183], v[124:127]
	v_mfma_f32_16x16x32_bf16 v[124:127], v[144:147], v[192:195], v[124:127]
	v_mfma_f32_16x16x32_bf16 v[120:123], v[148:151], v[180:183], v[120:123]
	v_mfma_f32_16x16x32_bf16 v[120:123], v[152:155], v[192:195], v[120:123]
	v_mfma_f32_16x16x32_bf16 v[116:119], v[172:175], v[180:183], v[116:119]
	v_mfma_f32_16x16x32_bf16 v[116:119], v[176:179], v[192:195], v[116:119]
	v_mfma_f32_16x16x32_bf16 v[100:103], v[172:175], v[196:199], v[100:103]
	v_mfma_f32_16x16x32_bf16 v[100:103], v[176:179], v[200:203], v[100:103]
	v_mfma_f32_16x16x32_bf16 v[104:107], v[148:151], v[196:199], v[104:107]
	v_mfma_f32_16x16x32_bf16 v[104:107], v[152:155], v[200:203], v[104:107]
	v_mfma_f32_16x16x32_bf16 v[108:111], v[140:143], v[196:199], v[108:111]
	v_mfma_f32_16x16x32_bf16 v[108:111], v[144:147], v[200:203], v[108:111]
	v_mfma_f32_16x16x32_bf16 v[112:115], v[132:135], v[196:199], v[112:115]
	v_mfma_f32_16x16x32_bf16 v[112:115], v[136:139], v[200:203], v[112:115]
	v_mfma_f32_16x16x32_bf16 v[96:99], v[132:135], v[204:207], v[96:99]
	v_mfma_f32_16x16x32_bf16 v[96:99], v[136:139], v[208:211], v[96:99]
	v_mfma_f32_16x16x32_bf16 v[92:95], v[140:143], v[204:207], v[92:95]
	v_mfma_f32_16x16x32_bf16 v[92:95], v[144:147], v[208:211], v[92:95]
	v_mfma_f32_16x16x32_bf16 v[88:91], v[148:151], v[204:207], v[88:91]
	v_mfma_f32_16x16x32_bf16 v[88:91], v[152:155], v[208:211], v[88:91]
	v_mfma_f32_16x16x32_bf16 v[84:87], v[172:175], v[204:207], v[84:87]
	v_mfma_f32_16x16x32_bf16 v[84:87], v[176:179], v[208:211], v[84:87]
	v_mfma_f32_16x16x32_bf16 v[68:71], v[172:175], v[212:215], v[68:71]
	v_mfma_f32_16x16x32_bf16 v[68:71], v[176:179], v[216:219], v[68:71]
	v_mfma_f32_16x16x32_bf16 v[72:75], v[148:151], v[212:215], v[72:75]
	v_mfma_f32_16x16x32_bf16 v[72:75], v[152:155], v[216:219], v[72:75]
	v_mfma_f32_16x16x32_bf16 v[76:79], v[140:143], v[212:215], v[76:79]
	v_mfma_f32_16x16x32_bf16 v[76:79], v[144:147], v[216:219], v[76:79]
	v_mfma_f32_16x16x32_bf16 v[80:83], v[132:135], v[212:215], v[80:83]
	v_mfma_f32_16x16x32_bf16 v[80:83], v[136:139], v[216:219], v[80:83]
	s_setprio 0
	s_barrier
	s_add_i32 s0, s0, s45
	s_add_i32 m0, s0, 0xffffff80
	ds_read_b128 v[180:183], v189 offset:49152
	ds_read_b128 v[192:195], v189 offset:50176
	ds_read_b128 v[196:199], v189 offset:51200
	ds_read_b128 v[200:203], v189 offset:52224
	ds_read_b128 v[204:207], v189 offset:53248
	ds_read_b128 v[208:211], v189 offset:54272
	ds_read_b128 v[212:215], v189 offset:55296
	ds_read_b128 v[216:219], v189 offset:56320
	global_load_lds_dwordx4 v158, s[50:51] offset:128
	s_add_i32 m0, s0, 0x1f80
	s_add_i32 s0, s65, s45
	global_load_lds_dwordx4 v162, s[50:51] offset:128
	s_add_u32 s50, s50, 0x20080
	s_addc_u32 s51, s51, 0
	s_mov_b32 m0, s0
	s_nop 0
	global_load_lds_dwordx4 v158, s[50:51]
	s_add_i32 m0, s0, 0x2000
	s_nop 0
	global_load_lds_dwordx4 v162, s[50:51]
	s_add_i32 m0, s56, 0xffffff80
	s_nop 0
	global_load_lds_dwordx4 v156, s[52:53] offset:128
	s_add_i32 m0, s57, 0xffffff80
	s_nop 0
	global_load_lds_dwordx4 v160, s[52:53] offset:128
	s_waitcnt vmcnt(8) lgkmcnt(0)
	s_setprio 1
	s_barrier
	v_mfma_f32_16x16x32_bf16 v[64:67], v[132:135], v[180:183], v[64:67]
	v_mfma_f32_16x16x32_bf16 v[64:67], v[136:139], v[192:195], v[64:67]
	v_mfma_f32_16x16x32_bf16 v[60:63], v[140:143], v[180:183], v[60:63]
	v_mfma_f32_16x16x32_bf16 v[60:63], v[144:147], v[192:195], v[60:63]
	v_mfma_f32_16x16x32_bf16 v[56:59], v[148:151], v[180:183], v[56:59]
	v_mfma_f32_16x16x32_bf16 v[56:59], v[152:155], v[192:195], v[56:59]
	v_mfma_f32_16x16x32_bf16 v[52:55], v[172:175], v[180:183], v[52:55]
	v_mfma_f32_16x16x32_bf16 v[52:55], v[176:179], v[192:195], v[52:55]
	v_mfma_f32_16x16x32_bf16 v[36:39], v[172:175], v[196:199], v[36:39]
	v_mfma_f32_16x16x32_bf16 v[36:39], v[176:179], v[200:203], v[36:39]
	v_mfma_f32_16x16x32_bf16 v[40:43], v[148:151], v[196:199], v[40:43]
	v_mfma_f32_16x16x32_bf16 v[40:43], v[152:155], v[200:203], v[40:43]
	v_mfma_f32_16x16x32_bf16 v[44:47], v[140:143], v[196:199], v[44:47]
	v_mfma_f32_16x16x32_bf16 v[44:47], v[144:147], v[200:203], v[44:47]
	v_mfma_f32_16x16x32_bf16 v[48:51], v[132:135], v[196:199], v[48:51]
	v_mfma_f32_16x16x32_bf16 v[48:51], v[136:139], v[200:203], v[48:51]
	v_mfma_f32_16x16x32_bf16 v[32:35], v[132:135], v[204:207], v[32:35]
	v_mfma_f32_16x16x32_bf16 v[32:35], v[136:139], v[208:211], v[32:35]
	v_mfma_f32_16x16x32_bf16 v[28:31], v[140:143], v[204:207], v[28:31]
	v_mfma_f32_16x16x32_bf16 v[28:31], v[144:147], v[208:211], v[28:31]
	v_mfma_f32_16x16x32_bf16 v[24:27], v[148:151], v[204:207], v[24:27]
	v_mfma_f32_16x16x32_bf16 v[24:27], v[152:155], v[208:211], v[24:27]
	v_mfma_f32_16x16x32_bf16 v[20:23], v[172:175], v[204:207], v[20:23]
	v_mfma_f32_16x16x32_bf16 v[20:23], v[176:179], v[208:211], v[20:23]
	v_mfma_f32_16x16x32_bf16 v[4:7], v[172:175], v[212:215], v[4:7]
	v_mfma_f32_16x16x32_bf16 v[4:7], v[176:179], v[216:219], v[4:7]
	v_mfma_f32_16x16x32_bf16 v[8:11], v[148:151], v[212:215], v[8:11]
	v_mfma_f32_16x16x32_bf16 v[8:11], v[152:155], v[216:219], v[8:11]
	v_mfma_f32_16x16x32_bf16 v[12:15], v[140:143], v[212:215], v[12:15]
	v_mfma_f32_16x16x32_bf16 v[12:15], v[144:147], v[216:219], v[12:15]
	v_mfma_f32_16x16x32_bf16 v[16:19], v[132:135], v[212:215], v[16:19]
	v_mfma_f32_16x16x32_bf16 v[16:19], v[136:139], v[216:219], v[16:19]
	s_setprio 0
	s_barrier
	s_add_i32 s64, s64, 2
	s_add_u32 s42, s42, 0x100
	s_addc_u32 s43, s43, 0
	s_add_u32 s62, s62, 0x100
	s_addc_u32 s63, s63, 0
	s_cmp_gt_u32 s64, 5
	s_cbranch_scc0 .LBB0_1415
	s_and_b64 vcc, exec, s[16:17]
	s_cbranch_vccz .LBB0_1418
	s_barrier

.LBB0_1503:
	ds_read_b128 v[132:135], v159
	ds_read_b128 v[164:167], v159 offset:1024
	ds_read_b128 v[168:171], v159 offset:2048
	ds_read_b128 v[172:175], v159 offset:3072
	ds_read_b128 v[176:179], v160
	ds_read_b128 v[180:183], v160 offset:1024
	ds_read_b128 v[184:187], v160 offset:2048
	ds_read_b128 v[188:191], v160 offset:3072
	s_add_u32 s0, s54, 0xfff00080
	s_addc_u32 s56, s55, -1
	s_cmp_eq_u32 s75, 60
	s_cselect_b32 s59, s31, s56
	s_cselect_b32 s58, s71, s0
	s_cselect_b32 s57, s29, s74
	s_cselect_b32 s56, s72, s73
	s_add_i32 m0, s48, 0xc000
	ds_read_b128 v[192:195], v161
	ds_read_b128 v[196:199], v161 offset:1024
	ds_read_b128 v[200:203], v161 offset:2048
	ds_read_b128 v[204:207], v161 offset:3072
	ds_read_b128 v[208:211], v161 offset:4096
	ds_read_b128 v[212:215], v161 offset:5120
	ds_read_b128 v[216:219], v161 offset:6144
	ds_read_b128 v[220:223], v161 offset:7168
	global_load_lds_dwordx4 v148, s[54:55]
	s_add_i32 m0, s48, 0xe000
	s_nop 0
	global_load_lds_dwordx4 v150, s[54:55]
	s_waitcnt vmcnt(8) lgkmcnt(0)
	s_setprio 1
	s_barrier
	v_mfma_f32_16x16x32_bf16 v[136:139], v[132:135], v[192:195], v[136:139]
	v_mfma_f32_16x16x32_bf16 v[136:139], v[164:167], v[196:199], v[136:139]
	v_mfma_f32_16x16x32_bf16 v[128:131], v[168:171], v[192:195], v[128:131]
	v_mfma_f32_16x16x32_bf16 v[128:131], v[172:175], v[196:199], v[128:131]
	v_mfma_f32_16x16x32_bf16 v[124:127], v[176:179], v[192:195], v[124:127]
	v_mfma_f32_16x16x32_bf16 v[124:127], v[180:183], v[196:199], v[124:127]
	v_mfma_f32_16x16x32_bf16 v[120:123], v[184:187], v[192:195], v[120:123]
	v_mfma_f32_16x16x32_bf16 v[120:123], v[188:191], v[196:199], v[120:123]
	v_mfma_f32_16x16x32_bf16 v[104:107], v[184:187], v[200:203], v[104:107]
	v_mfma_f32_16x16x32_bf16 v[104:107], v[188:191], v[204:207], v[104:107]
	v_mfma_f32_16x16x32_bf16 v[108:111], v[176:179], v[200:203], v[108:111]
	v_mfma_f32_16x16x32_bf16 v[108:111], v[180:183], v[204:207], v[108:111]
	v_mfma_f32_16x16x32_bf16 v[112:115], v[168:171], v[200:203], v[112:115]
	v_mfma_f32_16x16x32_bf16 v[112:115], v[172:175], v[204:207], v[112:115]
	v_mfma_f32_16x16x32_bf16 v[116:119], v[132:135], v[200:203], v[116:119]
	v_mfma_f32_16x16x32_bf16 v[116:119], v[164:167], v[204:207], v[116:119]
	v_mfma_f32_16x16x32_bf16 v[100:103], v[132:135], v[208:211], v[100:103]
	v_mfma_f32_16x16x32_bf16 v[100:103], v[164:167], v[212:215], v[100:103]
	v_mfma_f32_16x16x32_bf16 v[96:99], v[168:171], v[208:211], v[96:99]
	v_mfma_f32_16x16x32_bf16 v[96:99], v[172:175], v[212:215], v[96:99]
	v_mfma_f32_16x16x32_bf16 v[92:95], v[176:179], v[208:211], v[92:95]
	v_mfma_f32_16x16x32_bf16 v[92:95], v[180:183], v[212:215], v[92:95]
	v_mfma_f32_16x16x32_bf16 v[88:91], v[184:187], v[208:211], v[88:91]
	v_mfma_f32_16x16x32_bf16 v[88:91], v[188:191], v[212:215], v[88:91]
	v_mfma_f32_16x16x32_bf16 v[72:75], v[184:187], v[216:219], v[72:75]
	v_mfma_f32_16x16x32_bf16 v[72:75], v[188:191], v[220:223], v[72:75]
	v_mfma_f32_16x16x32_bf16 v[76:79], v[176:179], v[216:219], v[76:79]
	v_mfma_f32_16x16x32_bf16 v[76:79], v[180:183], v[220:223], v[76:79]
	v_mfma_f32_16x16x32_bf16 v[80:83], v[168:171], v[216:219], v[80:83]
	v_mfma_f32_16x16x32_bf16 v[80:83], v[172:175], v[220:223], v[80:83]
	v_mfma_f32_16x16x32_bf16 v[84:87], v[132:135], v[216:219], v[84:87]
	v_mfma_f32_16x16x32_bf16 v[84:87], v[164:167], v[220:223], v[84:87]
	s_setprio 0
	s_barrier
	s_add_i32 s0, s65, s47
	s_mov_b32 m0, s0
	ds_read_b128 v[192:195], v161 offset:16384
	ds_read_b128 v[196:199], v161 offset:17408
	ds_read_b128 v[200:203], v161 offset:18432
	ds_read_b128 v[204:207], v161 offset:19456
	ds_read_b128 v[208:211], v161 offset:20480
	ds_read_b128 v[212:215], v161 offset:21504
	ds_read_b128 v[216:219], v161 offset:22528
	ds_read_b128 v[220:223], v161 offset:23552
	global_load_lds_dwordx4 v142, s[56:57]
	s_add_i32 m0, s0, 0x2000
	s_add_u32 s76, s56, 0x100000
	s_addc_u32 s77, s57, 0
	s_add_i32 s0, s66, s47
	global_load_lds_dwordx4 v146, s[56:57]
	s_mov_b32 m0, s0
	s_nop 0
	global_load_lds_dwordx4 v142, s[76:77]
	s_add_i32 m0, s0, 0x2000
	s_nop 0
	global_load_lds_dwordx4 v146, s[76:77]
	s_mov_b32 m0, s48
	s_nop 0
	global_load_lds_dwordx4 v140, s[58:59]
	s_mov_b32 m0, s49
	s_nop 0
	global_load_lds_dwordx4 v144, s[58:59]
	s_waitcnt vmcnt(8) lgkmcnt(0)
	s_setprio 1
	s_barrier
	v_mfma_f32_16x16x32_bf16 v[68:71], v[132:135], v[192:195], v[68:71]
	v_mfma_f32_16x16x32_bf16 v[68:71], v[164:167], v[196:199], v[68:71]
	v_mfma_f32_16x16x32_bf16 v[64:67], v[168:171], v[192:195], v[64:67]
	v_mfma_f32_16x16x32_bf16 v[64:67], v[172:175], v[196:199], v[64:67]
	v_mfma_f32_16x16x32_bf16 v[60:63], v[176:179], v[192:195], v[60:63]
	v_mfma_f32_16x16x32_bf16 v[60:63], v[180:183], v[196:199], v[60:63]
	v_mfma_f32_16x16x32_bf16 v[56:59], v[184:187], v[192:195], v[56:59]
	v_mfma_f32_16x16x32_bf16 v[56:59], v[188:191], v[196:199], v[56:59]
	v_mfma_f32_16x16x32_bf16 v[40:43], v[184:187], v[200:203], v[40:43]
	v_mfma_f32_16x16x32_bf16 v[40:43], v[188:191], v[204:207], v[40:43]
	v_mfma_f32_16x16x32_bf16 v[44:47], v[176:179], v[200:203], v[44:47]
	v_mfma_f32_16x16x32_bf16 v[44:47], v[180:183], v[204:207], v[44:47]
	v_mfma_f32_16x16x32_bf16 v[48:51], v[168:171], v[200:203], v[48:51]
	v_mfma_f32_16x16x32_bf16 v[48:51], v[172:175], v[204:207], v[48:51]
	v_mfma_f32_16x16x32_bf16 v[52:55], v[132:135], v[200:203], v[52:55]
	v_mfma_f32_16x16x32_bf16 v[52:55], v[164:167], v[204:207], v[52:55]
	v_mfma_f32_16x16x32_bf16 v[36:39], v[132:135], v[208:211], v[36:39]
	v_mfma_f32_16x16x32_bf16 v[36:39], v[164:167], v[212:215], v[36:39]
	v_mfma_f32_16x16x32_bf16 v[32:35], v[168:171], v[208:211], v[32:35]
	v_mfma_f32_16x16x32_bf16 v[32:35], v[172:175], v[212:215], v[32:35]
	v_mfma_f32_16x16x32_bf16 v[28:31], v[176:179], v[208:211], v[28:31]
	v_mfma_f32_16x16x32_bf16 v[28:31], v[180:183], v[212:215], v[28:31]
	v_mfma_f32_16x16x32_bf16 v[24:27], v[184:187], v[208:211], v[24:27]
	v_mfma_f32_16x16x32_bf16 v[24:27], v[188:191], v[212:215], v[24:27]
	v_mfma_f32_16x16x32_bf16 v[8:11], v[184:187], v[216:219], v[8:11]
	v_mfma_f32_16x16x32_bf16 v[8:11], v[188:191], v[220:223], v[8:11]
	v_mfma_f32_16x16x32_bf16 v[12:15], v[176:179], v[216:219], v[12:15]
	v_mfma_f32_16x16x32_bf16 v[12:15], v[180:183], v[220:223], v[12:15]
	v_mfma_f32_16x16x32_bf16 v[16:19], v[168:171], v[216:219], v[16:19]
	v_mfma_f32_16x16x32_bf16 v[16:19], v[172:175], v[220:223], v[16:19]
	v_mfma_f32_16x16x32_bf16 v[20:23], v[132:135], v[216:219], v[20:23]
	v_mfma_f32_16x16x32_bf16 v[20:23], v[164:167], v[220:223], v[20:23]
	s_setprio 0
	s_barrier
	s_add_i32 s0, 0, 0x18000
	s_add_i32 s76, 0, 0x1c000
	v_add_u32_e32 v172, s0, v156
	v_add_u32_e32 v188, s76, v156
	ds_read_b128 v[132:135], v172
	ds_read_b128 v[164:167], v172 offset:1024
	ds_read_b128 v[168:171], v172 offset:2048
	ds_read_b128 v[172:175], v172 offset:3072
	ds_read_b128 v[176:179], v188
	ds_read_b128 v[180:183], v188 offset:1024
	ds_read_b128 v[184:187], v188 offset:2048
	ds_read_b128 v[188:191], v188 offset:3072
	s_add_u32 s98, s58, 0x100000
	s_addc_u32 s99, s59, 0
	s_mov_b32 m0, s51
	ds_read_b128 v[192:195], v161 offset:32768
	ds_read_b128 v[196:199], v161 offset:33792
	ds_read_b128 v[200:203], v161 offset:34816
	ds_read_b128 v[204:207], v161 offset:35840
	ds_read_b128 v[208:211], v161 offset:36864
	ds_read_b128 v[212:215], v161 offset:37888
	ds_read_b128 v[216:219], v161 offset:38912
	ds_read_b128 v[220:223], v161 offset:39936
	global_load_lds_dwordx4 v140, s[98:99]
	s_mov_b32 m0, s53
	s_nop 0
	global_load_lds_dwordx4 v144, s[98:99]
	s_waitcnt vmcnt(8) lgkmcnt(0)
	s_setprio 1
	s_barrier
	v_mfma_f32_16x16x32_bf16 v[136:139], v[132:135], v[192:195], v[136:139]
	v_mfma_f32_16x16x32_bf16 v[136:139], v[164:167], v[196:199], v[136:139]
	v_mfma_f32_16x16x32_bf16 v[128:131], v[168:171], v[192:195], v[128:131]
	v_mfma_f32_16x16x32_bf16 v[128:131], v[172:175], v[196:199], v[128:131]
	v_mfma_f32_16x16x32_bf16 v[124:127], v[176:179], v[192:195], v[124:127]
	v_mfma_f32_16x16x32_bf16 v[124:127], v[180:183], v[196:199], v[124:127]
	v_mfma_f32_16x16x32_bf16 v[120:123], v[184:187], v[192:195], v[120:123]
	v_mfma_f32_16x16x32_bf16 v[120:123], v[188:191], v[196:199], v[120:123]
	v_mfma_f32_16x16x32_bf16 v[104:107], v[184:187], v[200:203], v[104:107]
	v_mfma_f32_16x16x32_bf16 v[104:107], v[188:191], v[204:207], v[104:107]
	v_mfma_f32_16x16x32_bf16 v[108:111], v[176:179], v[200:203], v[108:111]
	v_mfma_f32_16x16x32_bf16 v[108:111], v[180:183], v[204:207], v[108:111]
	v_mfma_f32_16x16x32_bf16 v[112:115], v[168:171], v[200:203], v[112:115]
	v_mfma_f32_16x16x32_bf16 v[112:115], v[172:175], v[204:207], v[112:115]
	v_mfma_f32_16x16x32_bf16 v[116:119], v[132:135], v[200:203], v[116:119]
	v_mfma_f32_16x16x32_bf16 v[116:119], v[164:167], v[204:207], v[116:119]
	v_mfma_f32_16x16x32_bf16 v[100:103], v[132:135], v[208:211], v[100:103]
	v_mfma_f32_16x16x32_bf16 v[100:103], v[164:167], v[212:215], v[100:103]
	v_mfma_f32_16x16x32_bf16 v[96:99], v[168:171], v[208:211], v[96:99]
	v_mfma_f32_16x16x32_bf16 v[96:99], v[172:175], v[212:215], v[96:99]
	v_mfma_f32_16x16x32_bf16 v[92:95], v[176:179], v[208:211], v[92:95]
	v_mfma_f32_16x16x32_bf16 v[92:95], v[180:183], v[212:215], v[92:95]
	v_mfma_f32_16x16x32_bf16 v[88:91], v[184:187], v[208:211], v[88:91]
	v_mfma_f32_16x16x32_bf16 v[88:91], v[188:191], v[212:215], v[88:91]
	v_mfma_f32_16x16x32_bf16 v[72:75], v[184:187], v[216:219], v[72:75]
	v_mfma_f32_16x16x32_bf16 v[72:75], v[188:191], v[220:223], v[72:75]
	v_mfma_f32_16x16x32_bf16 v[76:79], v[176:179], v[216:219], v[76:79]
	v_mfma_f32_16x16x32_bf16 v[76:79], v[180:183], v[220:223], v[76:79]
	v_mfma_f32_16x16x32_bf16 v[80:83], v[168:171], v[216:219], v[80:83]
	v_mfma_f32_16x16x32_bf16 v[80:83], v[172:175], v[220:223], v[80:83]
	v_mfma_f32_16x16x32_bf16 v[84:87], v[132:135], v[216:219], v[84:87]
	v_mfma_f32_16x16x32_bf16 v[84:87], v[164:167], v[220:223], v[84:87]
	s_setprio 0
	s_barrier
	s_add_i32 s0, s0, s47
	s_add_i32 m0, s0, 0xffffff80
	ds_read_b128 v[192:195], v161 offset:49152
	ds_read_b128 v[196:199], v161 offset:50176
	ds_read_b128 v[200:203], v161 offset:51200
	ds_read_b128 v[204:207], v161 offset:52224
	ds_read_b128 v[208:211], v161 offset:53248
	ds_read_b128 v[212:215], v161 offset:54272
	ds_read_b128 v[216:219], v161 offset:55296
	ds_read_b128 v[220:223], v161 offset:56320
	global_load_lds_dwordx4 v142, s[56:57] offset:128
	s_add_i32 m0, s0, 0x1f80
	s_add_i32 s0, s76, s47
	global_load_lds_dwordx4 v146, s[56:57] offset:128
	s_add_u32 s56, s56, 0x100080
	s_addc_u32 s57, s57, 0
	s_mov_b32 m0, s0
	s_nop 0
	global_load_lds_dwordx4 v142, s[56:57]
	s_add_i32 m0, s0, 0x2000
	s_nop 0
	global_load_lds_dwordx4 v146, s[56:57]
	s_add_i32 m0, s62, 0xffffff80
	s_nop 0
	global_load_lds_dwordx4 v140, s[58:59] offset:128
	s_add_i32 m0, s63, 0xffffff80
	s_nop 0
	global_load_lds_dwordx4 v144, s[58:59] offset:128
	s_waitcnt vmcnt(8) lgkmcnt(0)
	s_setprio 1
	s_barrier
	v_mfma_f32_16x16x32_bf16 v[68:71], v[132:135], v[192:195], v[68:71]
	v_mfma_f32_16x16x32_bf16 v[68:71], v[164:167], v[196:199], v[68:71]
	v_mfma_f32_16x16x32_bf16 v[64:67], v[168:171], v[192:195], v[64:67]
	v_mfma_f32_16x16x32_bf16 v[64:67], v[172:175], v[196:199], v[64:67]
	v_mfma_f32_16x16x32_bf16 v[60:63], v[176:179], v[192:195], v[60:63]
	v_mfma_f32_16x16x32_bf16 v[60:63], v[180:183], v[196:199], v[60:63]
	v_mfma_f32_16x16x32_bf16 v[56:59], v[184:187], v[192:195], v[56:59]
	v_mfma_f32_16x16x32_bf16 v[56:59], v[188:191], v[196:199], v[56:59]
	v_mfma_f32_16x16x32_bf16 v[40:43], v[184:187], v[200:203], v[40:43]
	v_mfma_f32_16x16x32_bf16 v[40:43], v[188:191], v[204:207], v[40:43]
	v_mfma_f32_16x16x32_bf16 v[44:47], v[176:179], v[200:203], v[44:47]
	v_mfma_f32_16x16x32_bf16 v[44:47], v[180:183], v[204:207], v[44:47]
	v_mfma_f32_16x16x32_bf16 v[48:51], v[168:171], v[200:203], v[48:51]
	v_mfma_f32_16x16x32_bf16 v[48:51], v[172:175], v[204:207], v[48:51]
	v_mfma_f32_16x16x32_bf16 v[52:55], v[132:135], v[200:203], v[52:55]
	v_mfma_f32_16x16x32_bf16 v[52:55], v[164:167], v[204:207], v[52:55]
	v_mfma_f32_16x16x32_bf16 v[36:39], v[132:135], v[208:211], v[36:39]
	v_mfma_f32_16x16x32_bf16 v[36:39], v[164:167], v[212:215], v[36:39]
	v_mfma_f32_16x16x32_bf16 v[32:35], v[168:171], v[208:211], v[32:35]
	v_mfma_f32_16x16x32_bf16 v[32:35], v[172:175], v[212:215], v[32:35]
	v_mfma_f32_16x16x32_bf16 v[28:31], v[176:179], v[208:211], v[28:31]
	v_mfma_f32_16x16x32_bf16 v[28:31], v[180:183], v[212:215], v[28:31]
	v_mfma_f32_16x16x32_bf16 v[24:27], v[184:187], v[208:211], v[24:27]
	v_mfma_f32_16x16x32_bf16 v[24:27], v[188:191], v[212:215], v[24:27]
	v_mfma_f32_16x16x32_bf16 v[8:11], v[184:187], v[216:219], v[8:11]
	v_mfma_f32_16x16x32_bf16 v[8:11], v[188:191], v[220:223], v[8:11]
	v_mfma_f32_16x16x32_bf16 v[12:15], v[176:179], v[216:219], v[12:15]
	v_mfma_f32_16x16x32_bf16 v[12:15], v[180:183], v[220:223], v[12:15]
	v_mfma_f32_16x16x32_bf16 v[16:19], v[168:171], v[216:219], v[16:19]
	v_mfma_f32_16x16x32_bf16 v[16:19], v[172:175], v[220:223], v[16:19]
	v_mfma_f32_16x16x32_bf16 v[20:23], v[132:135], v[216:219], v[20:23]
	v_mfma_f32_16x16x32_bf16 v[20:23], v[164:167], v[220:223], v[20:23]
	s_setprio 0
	s_barrier
	s_add_i32 s75, s75, 2
	s_add_u32 s54, s54, 0x100
	s_addc_u32 s55, s55, 0
	s_add_u32 s73, s73, 0x100
	s_addc_u32 s74, s74, 0
	s_cmp_gt_u32 s75, 61
	s_cbranch_scc0 .LBB0_1503
	s_and_b64 vcc, exec, s[26:27]
	s_cbranch_vccz .LBB0_1506
	s_barrier

.LBB0_1672:
	ds_read_b128 v[132:135], v193
	ds_read_b128 v[136:139], v193 offset:1024
	ds_read_b128 v[140:143], v193 offset:2048
	ds_read_b128 v[144:147], v193 offset:3072
	ds_read_b128 v[148:151], v194
	ds_read_b128 v[152:155], v194 offset:1024
	ds_read_b128 v[172:175], v194 offset:2048
	ds_read_b128 v[176:179], v194 offset:3072
	s_add_u32 s0, s30, 0xffd50080
	s_addc_u32 s42, s31, -1
	s_cmpk_eq_i32 s66, 0xa8
	s_cselect_b32 s51, s7, s42
	s_cselect_b32 s50, s6, s0
	s_cselect_b32 s43, s29, s65
	s_cselect_b32 s42, s28, s64
	s_add_i32 m0, s46, 0xc000
	ds_read_b128 v[180:183], v195
	ds_read_b128 v[198:201], v195 offset:1024
	ds_read_b128 v[202:205], v195 offset:2048
	ds_read_b128 v[206:209], v195 offset:3072
	ds_read_b128 v[210:213], v195 offset:4096
	ds_read_b128 v[214:217], v195 offset:5120
	ds_read_b128 v[218:221], v195 offset:6144
	ds_read_b128 v[222:225], v195 offset:7168
	global_load_lds_dwordx4 v164, s[30:31]
	s_add_i32 m0, s46, 0xe000
	s_nop 0
	global_load_lds_dwordx4 v166, s[30:31]
	s_waitcnt vmcnt(8) lgkmcnt(0)
	s_setprio 1
	s_barrier
	v_mfma_f32_16x16x32_bf16 v[128:131], v[132:135], v[180:183], v[128:131]
	v_mfma_f32_16x16x32_bf16 v[128:131], v[136:139], v[198:201], v[128:131]
	v_mfma_f32_16x16x32_bf16 v[124:127], v[140:143], v[180:183], v[124:127]
	v_mfma_f32_16x16x32_bf16 v[124:127], v[144:147], v[198:201], v[124:127]
	v_mfma_f32_16x16x32_bf16 v[120:123], v[148:151], v[180:183], v[120:123]
	v_mfma_f32_16x16x32_bf16 v[120:123], v[152:155], v[198:201], v[120:123]
	v_mfma_f32_16x16x32_bf16 v[116:119], v[172:175], v[180:183], v[116:119]
	v_mfma_f32_16x16x32_bf16 v[116:119], v[176:179], v[198:201], v[116:119]
	v_mfma_f32_16x16x32_bf16 v[100:103], v[172:175], v[202:205], v[100:103]
	v_mfma_f32_16x16x32_bf16 v[100:103], v[176:179], v[206:209], v[100:103]
	v_mfma_f32_16x16x32_bf16 v[104:107], v[148:151], v[202:205], v[104:107]
	v_mfma_f32_16x16x32_bf16 v[104:107], v[152:155], v[206:209], v[104:107]
	v_mfma_f32_16x16x32_bf16 v[108:111], v[140:143], v[202:205], v[108:111]
	v_mfma_f32_16x16x32_bf16 v[108:111], v[144:147], v[206:209], v[108:111]
	v_mfma_f32_16x16x32_bf16 v[112:115], v[132:135], v[202:205], v[112:115]
	v_mfma_f32_16x16x32_bf16 v[112:115], v[136:139], v[206:209], v[112:115]
	v_mfma_f32_16x16x32_bf16 v[96:99], v[132:135], v[210:213], v[96:99]
	v_mfma_f32_16x16x32_bf16 v[96:99], v[136:139], v[214:217], v[96:99]
	v_mfma_f32_16x16x32_bf16 v[92:95], v[140:143], v[210:213], v[92:95]
	v_mfma_f32_16x16x32_bf16 v[92:95], v[144:147], v[214:217], v[92:95]
	v_mfma_f32_16x16x32_bf16 v[88:91], v[148:151], v[210:213], v[88:91]
	v_mfma_f32_16x16x32_bf16 v[88:91], v[152:155], v[214:217], v[88:91]
	v_mfma_f32_16x16x32_bf16 v[84:87], v[172:175], v[210:213], v[84:87]
	v_mfma_f32_16x16x32_bf16 v[84:87], v[176:179], v[214:217], v[84:87]
	v_mfma_f32_16x16x32_bf16 v[68:71], v[172:175], v[218:221], v[68:71]
	v_mfma_f32_16x16x32_bf16 v[68:71], v[176:179], v[222:225], v[68:71]
	v_mfma_f32_16x16x32_bf16 v[72:75], v[148:151], v[218:221], v[72:75]
	v_mfma_f32_16x16x32_bf16 v[72:75], v[152:155], v[222:225], v[72:75]
	v_mfma_f32_16x16x32_bf16 v[76:79], v[140:143], v[218:221], v[76:79]
	v_mfma_f32_16x16x32_bf16 v[76:79], v[144:147], v[222:225], v[76:79]
	v_mfma_f32_16x16x32_bf16 v[80:83], v[132:135], v[218:221], v[80:83]
	v_mfma_f32_16x16x32_bf16 v[80:83], v[136:139], v[222:225], v[80:83]
	s_setprio 0
	s_barrier
	s_add_i32 s0, s57, s45
	s_mov_b32 m0, s0
	ds_read_b128 v[180:183], v195 offset:16384
	ds_read_b128 v[198:201], v195 offset:17408
	ds_read_b128 v[202:205], v195 offset:18432
	ds_read_b128 v[206:209], v195 offset:19456
	ds_read_b128 v[210:213], v195 offset:20480
	ds_read_b128 v[214:217], v195 offset:21504
	ds_read_b128 v[218:221], v195 offset:22528
	ds_read_b128 v[222:225], v195 offset:23552
	global_load_lds_dwordx4 v158, s[42:43]
	s_add_i32 m0, s0, 0x2000
	s_add_u32 s70, s42, 0x2b0000
	s_addc_u32 s71, s43, 0
	s_add_i32 s0, s58, s45
	global_load_lds_dwordx4 v162, s[42:43]
	s_mov_b32 m0, s0
	s_nop 0
	global_load_lds_dwordx4 v158, s[70:71]
	s_add_i32 m0, s0, 0x2000
	s_nop 0
	global_load_lds_dwordx4 v162, s[70:71]
	s_mov_b32 m0, s46
	s_nop 0
	global_load_lds_dwordx4 v156, s[50:51]
	s_mov_b32 m0, s47
	s_nop 0
	global_load_lds_dwordx4 v160, s[50:51]
	s_waitcnt vmcnt(8) lgkmcnt(0)
	s_setprio 1
	s_barrier
	v_mfma_f32_16x16x32_bf16 v[64:67], v[132:135], v[180:183], v[64:67]
	v_mfma_f32_16x16x32_bf16 v[64:67], v[136:139], v[198:201], v[64:67]
	v_mfma_f32_16x16x32_bf16 v[60:63], v[140:143], v[180:183], v[60:63]
	v_mfma_f32_16x16x32_bf16 v[60:63], v[144:147], v[198:201], v[60:63]
	v_mfma_f32_16x16x32_bf16 v[56:59], v[148:151], v[180:183], v[56:59]
	v_mfma_f32_16x16x32_bf16 v[56:59], v[152:155], v[198:201], v[56:59]
	v_mfma_f32_16x16x32_bf16 v[52:55], v[172:175], v[180:183], v[52:55]
	v_mfma_f32_16x16x32_bf16 v[52:55], v[176:179], v[198:201], v[52:55]
	v_mfma_f32_16x16x32_bf16 v[36:39], v[172:175], v[202:205], v[36:39]
	v_mfma_f32_16x16x32_bf16 v[36:39], v[176:179], v[206:209], v[36:39]
	v_mfma_f32_16x16x32_bf16 v[40:43], v[148:151], v[202:205], v[40:43]
	v_mfma_f32_16x16x32_bf16 v[40:43], v[152:155], v[206:209], v[40:43]
	v_mfma_f32_16x16x32_bf16 v[44:47], v[140:143], v[202:205], v[44:47]
	v_mfma_f32_16x16x32_bf16 v[44:47], v[144:147], v[206:209], v[44:47]
	v_mfma_f32_16x16x32_bf16 v[48:51], v[132:135], v[202:205], v[48:51]
	v_mfma_f32_16x16x32_bf16 v[48:51], v[136:139], v[206:209], v[48:51]
	v_mfma_f32_16x16x32_bf16 v[32:35], v[132:135], v[210:213], v[32:35]
	v_mfma_f32_16x16x32_bf16 v[32:35], v[136:139], v[214:217], v[32:35]
	v_mfma_f32_16x16x32_bf16 v[28:31], v[140:143], v[210:213], v[28:31]
	v_mfma_f32_16x16x32_bf16 v[28:31], v[144:147], v[214:217], v[28:31]
	v_mfma_f32_16x16x32_bf16 v[24:27], v[148:151], v[210:213], v[24:27]
	v_mfma_f32_16x16x32_bf16 v[24:27], v[152:155], v[214:217], v[24:27]
	v_mfma_f32_16x16x32_bf16 v[20:23], v[172:175], v[210:213], v[20:23]
	v_mfma_f32_16x16x32_bf16 v[20:23], v[176:179], v[214:217], v[20:23]
	v_mfma_f32_16x16x32_bf16 v[4:7], v[172:175], v[218:221], v[4:7]
	v_mfma_f32_16x16x32_bf16 v[4:7], v[176:179], v[222:225], v[4:7]
	v_mfma_f32_16x16x32_bf16 v[8:11], v[148:151], v[218:221], v[8:11]
	v_mfma_f32_16x16x32_bf16 v[8:11], v[152:155], v[222:225], v[8:11]
	v_mfma_f32_16x16x32_bf16 v[12:15], v[140:143], v[218:221], v[12:15]
	v_mfma_f32_16x16x32_bf16 v[12:15], v[144:147], v[222:225], v[12:15]
	v_mfma_f32_16x16x32_bf16 v[16:19], v[132:135], v[218:221], v[16:19]
	v_mfma_f32_16x16x32_bf16 v[16:19], v[136:139], v[222:225], v[16:19]
	s_setprio 0
	s_barrier
	s_add_i32 s0, 0, 0x18000
	s_add_i32 s67, 0, 0x1c000
	v_add_u32_e32 v144, s0, v191
	v_add_u32_e32 v176, s67, v191
	ds_read_b128 v[132:135], v144
	ds_read_b128 v[136:139], v144 offset:1024
	ds_read_b128 v[140:143], v144 offset:2048
	ds_read_b128 v[144:147], v144 offset:3072
	ds_read_b128 v[148:151], v176
	ds_read_b128 v[152:155], v176 offset:1024
	ds_read_b128 v[172:175], v176 offset:2048
	ds_read_b128 v[176:179], v176 offset:3072
	s_add_u32 s98, s50, 0x2b0000
	s_addc_u32 s99, s51, 0
	s_mov_b32 m0, s48
	ds_read_b128 v[180:183], v195 offset:32768
	ds_read_b128 v[198:201], v195 offset:33792
	ds_read_b128 v[202:205], v195 offset:34816
	ds_read_b128 v[206:209], v195 offset:35840
	ds_read_b128 v[210:213], v195 offset:36864
	ds_read_b128 v[214:217], v195 offset:37888
	ds_read_b128 v[218:221], v195 offset:38912
	ds_read_b128 v[222:225], v195 offset:39936
	global_load_lds_dwordx4 v156, s[98:99]
	s_mov_b32 m0, s49
	s_nop 0
	global_load_lds_dwordx4 v160, s[98:99]
	s_waitcnt vmcnt(8) lgkmcnt(0)
	s_setprio 1
	s_barrier
	v_mfma_f32_16x16x32_bf16 v[128:131], v[132:135], v[180:183], v[128:131]
	v_mfma_f32_16x16x32_bf16 v[128:131], v[136:139], v[198:201], v[128:131]
	v_mfma_f32_16x16x32_bf16 v[124:127], v[140:143], v[180:183], v[124:127]
	v_mfma_f32_16x16x32_bf16 v[124:127], v[144:147], v[198:201], v[124:127]
	v_mfma_f32_16x16x32_bf16 v[120:123], v[148:151], v[180:183], v[120:123]
	v_mfma_f32_16x16x32_bf16 v[120:123], v[152:155], v[198:201], v[120:123]
	v_mfma_f32_16x16x32_bf16 v[116:119], v[172:175], v[180:183], v[116:119]
	v_mfma_f32_16x16x32_bf16 v[116:119], v[176:179], v[198:201], v[116:119]
	v_mfma_f32_16x16x32_bf16 v[100:103], v[172:175], v[202:205], v[100:103]
	v_mfma_f32_16x16x32_bf16 v[100:103], v[176:179], v[206:209], v[100:103]
	v_mfma_f32_16x16x32_bf16 v[104:107], v[148:151], v[202:205], v[104:107]
	v_mfma_f32_16x16x32_bf16 v[104:107], v[152:155], v[206:209], v[104:107]
	v_mfma_f32_16x16x32_bf16 v[108:111], v[140:143], v[202:205], v[108:111]
	v_mfma_f32_16x16x32_bf16 v[108:111], v[144:147], v[206:209], v[108:111]
	v_mfma_f32_16x16x32_bf16 v[112:115], v[132:135], v[202:205], v[112:115]
	v_mfma_f32_16x16x32_bf16 v[112:115], v[136:139], v[206:209], v[112:115]
	v_mfma_f32_16x16x32_bf16 v[96:99], v[132:135], v[210:213], v[96:99]
	v_mfma_f32_16x16x32_bf16 v[96:99], v[136:139], v[214:217], v[96:99]
	v_mfma_f32_16x16x32_bf16 v[92:95], v[140:143], v[210:213], v[92:95]
	v_mfma_f32_16x16x32_bf16 v[92:95], v[144:147], v[214:217], v[92:95]
	v_mfma_f32_16x16x32_bf16 v[88:91], v[148:151], v[210:213], v[88:91]
	v_mfma_f32_16x16x32_bf16 v[88:91], v[152:155], v[214:217], v[88:91]
	v_mfma_f32_16x16x32_bf16 v[84:87], v[172:175], v[210:213], v[84:87]
	v_mfma_f32_16x16x32_bf16 v[84:87], v[176:179], v[214:217], v[84:87]
	v_mfma_f32_16x16x32_bf16 v[68:71], v[172:175], v[218:221], v[68:71]
	v_mfma_f32_16x16x32_bf16 v[68:71], v[176:179], v[222:225], v[68:71]
	v_mfma_f32_16x16x32_bf16 v[72:75], v[148:151], v[218:221], v[72:75]
	v_mfma_f32_16x16x32_bf16 v[72:75], v[152:155], v[222:225], v[72:75]
	v_mfma_f32_16x16x32_bf16 v[76:79], v[140:143], v[218:221], v[76:79]
	v_mfma_f32_16x16x32_bf16 v[76:79], v[144:147], v[222:225], v[76:79]
	v_mfma_f32_16x16x32_bf16 v[80:83], v[132:135], v[218:221], v[80:83]
	v_mfma_f32_16x16x32_bf16 v[80:83], v[136:139], v[222:225], v[80:83]
	s_setprio 0
	s_barrier
	s_add_i32 s0, s0, s45
	s_add_i32 m0, s0, 0xffffff80
	ds_read_b128 v[180:183], v195 offset:49152
	ds_read_b128 v[198:201], v195 offset:50176
	ds_read_b128 v[202:205], v195 offset:51200
	ds_read_b128 v[206:209], v195 offset:52224
	ds_read_b128 v[210:213], v195 offset:53248
	ds_read_b128 v[214:217], v195 offset:54272
	ds_read_b128 v[218:221], v195 offset:55296
	ds_read_b128 v[222:225], v195 offset:56320
	global_load_lds_dwordx4 v158, s[42:43] offset:128
	s_add_i32 m0, s0, 0x1f80
	s_add_i32 s0, s67, s45
	global_load_lds_dwordx4 v162, s[42:43] offset:128
	s_add_u32 s42, s42, 0x2b0080
	s_addc_u32 s43, s43, 0
	s_mov_b32 m0, s0
	s_nop 0
	global_load_lds_dwordx4 v158, s[42:43]
	s_add_i32 m0, s0, 0x2000
	s_nop 0
	global_load_lds_dwordx4 v162, s[42:43]
	s_add_i32 m0, s55, 0xffffff80
	s_nop 0
	global_load_lds_dwordx4 v156, s[50:51] offset:128
	s_add_i32 m0, s56, 0xffffff80
	s_nop 0
	global_load_lds_dwordx4 v160, s[50:51] offset:128
	s_waitcnt vmcnt(8) lgkmcnt(0)
	s_setprio 1
	s_barrier
	v_mfma_f32_16x16x32_bf16 v[64:67], v[132:135], v[180:183], v[64:67]
	v_mfma_f32_16x16x32_bf16 v[64:67], v[136:139], v[198:201], v[64:67]
	v_mfma_f32_16x16x32_bf16 v[60:63], v[140:143], v[180:183], v[60:63]
	v_mfma_f32_16x16x32_bf16 v[60:63], v[144:147], v[198:201], v[60:63]
	v_mfma_f32_16x16x32_bf16 v[56:59], v[148:151], v[180:183], v[56:59]
	v_mfma_f32_16x16x32_bf16 v[56:59], v[152:155], v[198:201], v[56:59]
	v_mfma_f32_16x16x32_bf16 v[52:55], v[172:175], v[180:183], v[52:55]
	v_mfma_f32_16x16x32_bf16 v[52:55], v[176:179], v[198:201], v[52:55]
	v_mfma_f32_16x16x32_bf16 v[36:39], v[172:175], v[202:205], v[36:39]
	v_mfma_f32_16x16x32_bf16 v[36:39], v[176:179], v[206:209], v[36:39]
	v_mfma_f32_16x16x32_bf16 v[40:43], v[148:151], v[202:205], v[40:43]
	v_mfma_f32_16x16x32_bf16 v[40:43], v[152:155], v[206:209], v[40:43]
	v_mfma_f32_16x16x32_bf16 v[44:47], v[140:143], v[202:205], v[44:47]
	v_mfma_f32_16x16x32_bf16 v[44:47], v[144:147], v[206:209], v[44:47]
	v_mfma_f32_16x16x32_bf16 v[48:51], v[132:135], v[202:205], v[48:51]
	v_mfma_f32_16x16x32_bf16 v[48:51], v[136:139], v[206:209], v[48:51]
	v_mfma_f32_16x16x32_bf16 v[32:35], v[132:135], v[210:213], v[32:35]
	v_mfma_f32_16x16x32_bf16 v[32:35], v[136:139], v[214:217], v[32:35]
	v_mfma_f32_16x16x32_bf16 v[28:31], v[140:143], v[210:213], v[28:31]
	v_mfma_f32_16x16x32_bf16 v[28:31], v[144:147], v[214:217], v[28:31]
	v_mfma_f32_16x16x32_bf16 v[24:27], v[148:151], v[210:213], v[24:27]
	v_mfma_f32_16x16x32_bf16 v[24:27], v[152:155], v[214:217], v[24:27]
	v_mfma_f32_16x16x32_bf16 v[20:23], v[172:175], v[210:213], v[20:23]
	v_mfma_f32_16x16x32_bf16 v[20:23], v[176:179], v[214:217], v[20:23]
	v_mfma_f32_16x16x32_bf16 v[4:7], v[172:175], v[218:221], v[4:7]
	v_mfma_f32_16x16x32_bf16 v[4:7], v[176:179], v[222:225], v[4:7]
	v_mfma_f32_16x16x32_bf16 v[8:11], v[148:151], v[218:221], v[8:11]
	v_mfma_f32_16x16x32_bf16 v[8:11], v[152:155], v[222:225], v[8:11]
	v_mfma_f32_16x16x32_bf16 v[12:15], v[140:143], v[218:221], v[12:15]
	v_mfma_f32_16x16x32_bf16 v[12:15], v[144:147], v[222:225], v[12:15]
	v_mfma_f32_16x16x32_bf16 v[16:19], v[132:135], v[218:221], v[16:19]
	v_mfma_f32_16x16x32_bf16 v[16:19], v[136:139], v[222:225], v[16:19]
	s_setprio 0
	s_barrier
	s_add_i32 s66, s66, 2
	s_add_u32 s30, s30, 0x100
	s_addc_u32 s31, s31, 0
	s_add_u32 s64, s64, 0x100
	s_addc_u32 s65, s65, 0
	s_cmpk_gt_u32 s66, 0xa9
	s_cbranch_scc0 .LBB0_1672
	s_and_b64 vcc, exec, s[24:25]
	s_cbranch_vccz .LBB0_1675
	s_barrier

.LBB0_1703:
	ds_read_b128 v[136:139], v196
	ds_read_b128 v[140:143], v196 offset:1024
	ds_read_b128 v[144:147], v196 offset:2048
	ds_read_b128 v[148:151], v196 offset:3072
	ds_read_b128 v[152:155], v197
	ds_read_b128 v[176:179], v197 offset:1024
	ds_read_b128 v[180:183], v197 offset:2048
	ds_read_b128 v[184:187], v197 offset:3072
	s_add_u32 s8, s6, 0x100
	s_addc_u32 s9, s7, 0
	s_add_u32 s0, s65, s6
	s_addc_u32 s40, s66, s7
	s_cmpk_eq_i32 s67, 0xa8
	s_cselect_b32 s43, s50, s40
	s_cselect_b32 s40, 0, s8
	s_cselect_b32 s42, s51, s0
	s_cselect_b32 s0, 0, s9
	s_add_u32 s40, s16, s40
	s_addc_u32 s41, s17, s0
	s_mov_b32 m0, s58
	v_lshl_add_u64 v[226:227], v[132:133], 0, s[6:7]
	ds_read_b128 v[188:191], v198
	ds_read_b128 v[192:195], v198 offset:1024
	ds_read_b128 v[202:205], v198 offset:2048
	ds_read_b128 v[206:209], v198 offset:3072
	ds_read_b128 v[210:213], v198 offset:4096
	ds_read_b128 v[214:217], v198 offset:5120
	ds_read_b128 v[218:221], v198 offset:6144
	ds_read_b128 v[222:225], v198 offset:7168
	global_load_lds_dwordx4 v[226:227], off
	v_lshl_add_u64 v[226:227], v[134:135], 0, s[6:7]
	s_mov_b32 m0, s59
	s_nop 0
	global_load_lds_dwordx4 v[226:227], off
	s_waitcnt vmcnt(8) lgkmcnt(0)
	s_setprio 1
	s_barrier
	v_mfma_f32_16x16x32_bf16 v[128:131], v[136:139], v[188:191], v[128:131]
	v_mfma_f32_16x16x32_bf16 v[128:131], v[140:143], v[192:195], v[128:131]
	v_mfma_f32_16x16x32_bf16 v[124:127], v[144:147], v[188:191], v[124:127]
	v_mfma_f32_16x16x32_bf16 v[124:127], v[148:151], v[192:195], v[124:127]
	v_mfma_f32_16x16x32_bf16 v[120:123], v[152:155], v[188:191], v[120:123]
	v_mfma_f32_16x16x32_bf16 v[120:123], v[176:179], v[192:195], v[120:123]
	v_mfma_f32_16x16x32_bf16 v[116:119], v[180:183], v[188:191], v[116:119]
	v_mfma_f32_16x16x32_bf16 v[116:119], v[184:187], v[192:195], v[116:119]
	v_mfma_f32_16x16x32_bf16 v[100:103], v[180:183], v[202:205], v[100:103]
	v_mfma_f32_16x16x32_bf16 v[100:103], v[184:187], v[206:209], v[100:103]
	v_mfma_f32_16x16x32_bf16 v[104:107], v[152:155], v[202:205], v[104:107]
	v_mfma_f32_16x16x32_bf16 v[104:107], v[176:179], v[206:209], v[104:107]
	v_mfma_f32_16x16x32_bf16 v[108:111], v[144:147], v[202:205], v[108:111]
	v_mfma_f32_16x16x32_bf16 v[108:111], v[148:151], v[206:209], v[108:111]
	v_mfma_f32_16x16x32_bf16 v[112:115], v[136:139], v[202:205], v[112:115]
	v_mfma_f32_16x16x32_bf16 v[112:115], v[140:143], v[206:209], v[112:115]
	v_mfma_f32_16x16x32_bf16 v[96:99], v[136:139], v[210:213], v[96:99]
	v_mfma_f32_16x16x32_bf16 v[96:99], v[140:143], v[214:217], v[96:99]
	v_mfma_f32_16x16x32_bf16 v[92:95], v[144:147], v[210:213], v[92:95]
	v_mfma_f32_16x16x32_bf16 v[92:95], v[148:151], v[214:217], v[92:95]
	v_mfma_f32_16x16x32_bf16 v[88:91], v[152:155], v[210:213], v[88:91]
	v_mfma_f32_16x16x32_bf16 v[88:91], v[176:179], v[214:217], v[88:91]
	v_mfma_f32_16x16x32_bf16 v[84:87], v[180:183], v[210:213], v[84:87]
	v_mfma_f32_16x16x32_bf16 v[84:87], v[184:187], v[214:217], v[84:87]
	v_mfma_f32_16x16x32_bf16 v[68:71], v[180:183], v[218:221], v[68:71]
	v_mfma_f32_16x16x32_bf16 v[68:71], v[184:187], v[222:225], v[68:71]
	v_mfma_f32_16x16x32_bf16 v[72:75], v[152:155], v[218:221], v[72:75]
	v_mfma_f32_16x16x32_bf16 v[72:75], v[176:179], v[222:225], v[72:75]
	v_mfma_f32_16x16x32_bf16 v[76:79], v[144:147], v[218:221], v[76:79]
	v_mfma_f32_16x16x32_bf16 v[76:79], v[148:151], v[222:225], v[76:79]
	v_mfma_f32_16x16x32_bf16 v[80:83], v[136:139], v[218:221], v[80:83]
	v_mfma_f32_16x16x32_bf16 v[80:83], v[140:143], v[222:225], v[80:83]
	s_setprio 0
	s_barrier
	s_mov_b32 m0, s60
	v_lshl_add_u64 v[226:227], s[40:41], 0, v[158:159]
	s_add_u32 s6, s40, 0x2b0000
	ds_read_b128 v[188:191], v198 offset:16384
	ds_read_b128 v[192:195], v198 offset:17408
	ds_read_b128 v[202:205], v198 offset:18432
	ds_read_b128 v[206:209], v198 offset:19456
	ds_read_b128 v[210:213], v198 offset:20480
	ds_read_b128 v[214:217], v198 offset:21504
	ds_read_b128 v[218:221], v198 offset:22528
	ds_read_b128 v[222:225], v198 offset:23552
	global_load_lds_dwordx4 v[226:227], off
	v_lshl_add_u64 v[228:229], s[40:41], 0, v[162:163]
	s_mov_b32 m0, s61
	s_addc_u32 s7, s41, 0
	global_load_lds_dwordx4 v[228:229], off
	v_lshl_add_u64 v[230:231], s[6:7], 0, v[158:159]
	s_mov_b32 m0, s62
	v_lshl_add_u64 v[232:233], s[42:43], 0, v[160:161]
	global_load_lds_dwordx4 v[230:231], off
	v_lshl_add_u64 v[230:231], s[6:7], 0, v[162:163]
	s_mov_b32 m0, s63
	s_nop 0
	global_load_lds_dwordx4 v[230:231], off
	v_lshl_add_u64 v[230:231], s[42:43], 0, v[156:157]
	s_mov_b32 m0, s46
	s_nop 0
	global_load_lds_dwordx4 v[230:231], off
	s_mov_b32 m0, s47
	s_nop 0
	global_load_lds_dwordx4 v[232:233], off
	s_waitcnt vmcnt(8) lgkmcnt(0)
	s_setprio 1
	s_barrier
	v_mfma_f32_16x16x32_bf16 v[64:67], v[136:139], v[188:191], v[64:67]
	v_mfma_f32_16x16x32_bf16 v[64:67], v[140:143], v[192:195], v[64:67]
	v_mfma_f32_16x16x32_bf16 v[60:63], v[144:147], v[188:191], v[60:63]
	v_mfma_f32_16x16x32_bf16 v[60:63], v[148:151], v[192:195], v[60:63]
	v_mfma_f32_16x16x32_bf16 v[56:59], v[152:155], v[188:191], v[56:59]
	v_mfma_f32_16x16x32_bf16 v[56:59], v[176:179], v[192:195], v[56:59]
	v_mfma_f32_16x16x32_bf16 v[52:55], v[180:183], v[188:191], v[52:55]
	v_mfma_f32_16x16x32_bf16 v[52:55], v[184:187], v[192:195], v[52:55]
	v_mfma_f32_16x16x32_bf16 v[36:39], v[180:183], v[202:205], v[36:39]
	v_mfma_f32_16x16x32_bf16 v[36:39], v[184:187], v[206:209], v[36:39]
	v_mfma_f32_16x16x32_bf16 v[40:43], v[152:155], v[202:205], v[40:43]
	v_mfma_f32_16x16x32_bf16 v[40:43], v[176:179], v[206:209], v[40:43]
	v_mfma_f32_16x16x32_bf16 v[44:47], v[144:147], v[202:205], v[44:47]
	v_mfma_f32_16x16x32_bf16 v[44:47], v[148:151], v[206:209], v[44:47]
	v_mfma_f32_16x16x32_bf16 v[48:51], v[136:139], v[202:205], v[48:51]
	v_mfma_f32_16x16x32_bf16 v[48:51], v[140:143], v[206:209], v[48:51]
	v_mfma_f32_16x16x32_bf16 v[32:35], v[136:139], v[210:213], v[32:35]
	v_mfma_f32_16x16x32_bf16 v[32:35], v[140:143], v[214:217], v[32:35]
	v_mfma_f32_16x16x32_bf16 v[28:31], v[144:147], v[210:213], v[28:31]
	v_mfma_f32_16x16x32_bf16 v[28:31], v[148:151], v[214:217], v[28:31]
	v_mfma_f32_16x16x32_bf16 v[24:27], v[152:155], v[210:213], v[24:27]
	v_mfma_f32_16x16x32_bf16 v[24:27], v[176:179], v[214:217], v[24:27]
	v_mfma_f32_16x16x32_bf16 v[20:23], v[180:183], v[210:213], v[20:23]
	v_mfma_f32_16x16x32_bf16 v[20:23], v[184:187], v[214:217], v[20:23]
	v_mfma_f32_16x16x32_bf16 v[4:7], v[180:183], v[218:221], v[4:7]
	v_mfma_f32_16x16x32_bf16 v[4:7], v[184:187], v[222:225], v[4:7]
	v_mfma_f32_16x16x32_bf16 v[8:11], v[152:155], v[218:221], v[8:11]
	v_mfma_f32_16x16x32_bf16 v[8:11], v[176:179], v[222:225], v[8:11]
	v_mfma_f32_16x16x32_bf16 v[12:15], v[144:147], v[218:221], v[12:15]
	v_mfma_f32_16x16x32_bf16 v[12:15], v[148:151], v[222:225], v[12:15]
	v_mfma_f32_16x16x32_bf16 v[16:19], v[136:139], v[218:221], v[16:19]
	v_mfma_f32_16x16x32_bf16 v[16:19], v[140:143], v[222:225], v[16:19]
	s_setprio 0
	s_barrier
	s_add_i32 s0, 0, 0x18000
	s_add_i32 s68, 0, 0x1c000
	v_add_u32_e32 v148, s0, v3
	v_add_u32_e32 v170, s68, v3
	ds_read_b128 v[136:139], v148
	ds_read_b128 v[140:143], v148 offset:1024
	ds_read_b128 v[144:147], v148 offset:2048
	ds_read_b128 v[148:151], v148 offset:3072
	ds_read_b128 v[152:155], v170
	ds_read_b128 v[176:179], v170 offset:1024
	ds_read_b128 v[180:183], v170 offset:2048
	ds_read_b128 v[184:187], v170 offset:3072
	s_add_u32 s6, s42, 0x2b0000
	s_addc_u32 s7, s43, 0
	s_mov_b32 m0, s48
	v_lshl_add_u64 v[234:235], s[6:7], 0, v[156:157]
	ds_read_b128 v[188:191], v198 offset:32768
	ds_read_b128 v[192:195], v198 offset:33792
	ds_read_b128 v[202:205], v198 offset:34816
	ds_read_b128 v[206:209], v198 offset:35840
	ds_read_b128 v[210:213], v198 offset:36864
	ds_read_b128 v[214:217], v198 offset:37888
	ds_read_b128 v[218:221], v198 offset:38912
	ds_read_b128 v[222:225], v198 offset:39936
	global_load_lds_dwordx4 v[234:235], off
	v_lshl_add_u64 v[234:235], s[6:7], 0, v[160:161]
	s_mov_b32 m0, s49
	s_nop 0
	global_load_lds_dwordx4 v[234:235], off
	s_waitcnt vmcnt(8) lgkmcnt(0)
	s_setprio 1
	s_barrier
	v_mfma_f32_16x16x32_bf16 v[128:131], v[136:139], v[188:191], v[128:131]
	v_mfma_f32_16x16x32_bf16 v[128:131], v[140:143], v[192:195], v[128:131]
	v_mfma_f32_16x16x32_bf16 v[124:127], v[144:147], v[188:191], v[124:127]
	v_mfma_f32_16x16x32_bf16 v[124:127], v[148:151], v[192:195], v[124:127]
	v_mfma_f32_16x16x32_bf16 v[120:123], v[152:155], v[188:191], v[120:123]
	v_mfma_f32_16x16x32_bf16 v[120:123], v[176:179], v[192:195], v[120:123]
	v_mfma_f32_16x16x32_bf16 v[116:119], v[180:183], v[188:191], v[116:119]
	v_mfma_f32_16x16x32_bf16 v[116:119], v[184:187], v[192:195], v[116:119]
	v_mfma_f32_16x16x32_bf16 v[100:103], v[180:183], v[202:205], v[100:103]
	v_mfma_f32_16x16x32_bf16 v[100:103], v[184:187], v[206:209], v[100:103]
	v_mfma_f32_16x16x32_bf16 v[104:107], v[152:155], v[202:205], v[104:107]
	v_mfma_f32_16x16x32_bf16 v[104:107], v[176:179], v[206:209], v[104:107]
	v_mfma_f32_16x16x32_bf16 v[108:111], v[144:147], v[202:205], v[108:111]
	v_mfma_f32_16x16x32_bf16 v[108:111], v[148:151], v[206:209], v[108:111]
	v_mfma_f32_16x16x32_bf16 v[112:115], v[136:139], v[202:205], v[112:115]
	v_mfma_f32_16x16x32_bf16 v[112:115], v[140:143], v[206:209], v[112:115]
	v_mfma_f32_16x16x32_bf16 v[96:99], v[136:139], v[210:213], v[96:99]
	v_mfma_f32_16x16x32_bf16 v[96:99], v[140:143], v[214:217], v[96:99]
	v_mfma_f32_16x16x32_bf16 v[92:95], v[144:147], v[210:213], v[92:95]
	v_mfma_f32_16x16x32_bf16 v[92:95], v[148:151], v[214:217], v[92:95]
	v_mfma_f32_16x16x32_bf16 v[88:91], v[152:155], v[210:213], v[88:91]
	v_mfma_f32_16x16x32_bf16 v[88:91], v[176:179], v[214:217], v[88:91]
	v_mfma_f32_16x16x32_bf16 v[84:87], v[180:183], v[210:213], v[84:87]
	v_mfma_f32_16x16x32_bf16 v[84:87], v[184:187], v[214:217], v[84:87]
	v_mfma_f32_16x16x32_bf16 v[68:71], v[180:183], v[218:221], v[68:71]
	v_mfma_f32_16x16x32_bf16 v[68:71], v[184:187], v[222:225], v[68:71]
	v_mfma_f32_16x16x32_bf16 v[72:75], v[152:155], v[218:221], v[72:75]
	v_mfma_f32_16x16x32_bf16 v[72:75], v[176:179], v[222:225], v[72:75]
	v_mfma_f32_16x16x32_bf16 v[76:79], v[144:147], v[218:221], v[76:79]
	v_mfma_f32_16x16x32_bf16 v[76:79], v[148:151], v[222:225], v[76:79]
	v_mfma_f32_16x16x32_bf16 v[80:83], v[136:139], v[218:221], v[80:83]
	v_mfma_f32_16x16x32_bf16 v[80:83], v[140:143], v[222:225], v[80:83]
	s_setprio 0
	s_barrier
	s_add_i32 s0, s0, s45
	v_lshl_add_u64 v[226:227], v[226:227], 0, s[28:29]
	s_mov_b32 m0, s0
	ds_read_b128 v[188:191], v198 offset:49152
	ds_read_b128 v[192:195], v198 offset:50176
	ds_read_b128 v[202:205], v198 offset:51200
	ds_read_b128 v[206:209], v198 offset:52224
	ds_read_b128 v[210:213], v198 offset:53248
	ds_read_b128 v[214:217], v198 offset:54272
	ds_read_b128 v[218:221], v198 offset:55296
	ds_read_b128 v[222:225], v198 offset:56320
	global_load_lds_dwordx4 v[226:227], off
	s_add_i32 m0, s0, 0x2000
	s_add_u32 s6, s40, 0x2b0080
	v_lshl_add_u64 v[226:227], v[228:229], 0, s[28:29]
	s_addc_u32 s7, s41, 0
	s_add_i32 s0, s68, s45
	global_load_lds_dwordx4 v[226:227], off
	v_lshl_add_u64 v[226:227], s[6:7], 0, v[158:159]
	s_mov_b32 m0, s0
	s_nop 0
	global_load_lds_dwordx4 v[226:227], off
	v_lshl_add_u64 v[226:227], s[6:7], 0, v[162:163]
	s_add_i32 m0, s0, 0x2000
	s_nop 0
	global_load_lds_dwordx4 v[226:227], off
	v_lshl_add_u64 v[226:227], v[230:231], 0, s[28:29]
	s_mov_b32 m0, s54
	s_nop 0
	global_load_lds_dwordx4 v[226:227], off
	v_lshl_add_u64 v[226:227], v[232:233], 0, s[28:29]
	s_mov_b32 m0, s55
	s_nop 0
	global_load_lds_dwordx4 v[226:227], off
	s_waitcnt vmcnt(8) lgkmcnt(0)
	s_setprio 1
	s_barrier
	v_mfma_f32_16x16x32_bf16 v[64:67], v[136:139], v[188:191], v[64:67]
	v_mfma_f32_16x16x32_bf16 v[64:67], v[140:143], v[192:195], v[64:67]
	v_mfma_f32_16x16x32_bf16 v[60:63], v[144:147], v[188:191], v[60:63]
	v_mfma_f32_16x16x32_bf16 v[60:63], v[148:151], v[192:195], v[60:63]
	v_mfma_f32_16x16x32_bf16 v[56:59], v[152:155], v[188:191], v[56:59]
	v_mfma_f32_16x16x32_bf16 v[56:59], v[176:179], v[192:195], v[56:59]
	v_mfma_f32_16x16x32_bf16 v[52:55], v[180:183], v[188:191], v[52:55]
	v_mfma_f32_16x16x32_bf16 v[52:55], v[184:187], v[192:195], v[52:55]
	v_mfma_f32_16x16x32_bf16 v[36:39], v[180:183], v[202:205], v[36:39]
	v_mfma_f32_16x16x32_bf16 v[36:39], v[184:187], v[206:209], v[36:39]
	v_mfma_f32_16x16x32_bf16 v[40:43], v[152:155], v[202:205], v[40:43]
	v_mfma_f32_16x16x32_bf16 v[40:43], v[176:179], v[206:209], v[40:43]
	v_mfma_f32_16x16x32_bf16 v[44:47], v[144:147], v[202:205], v[44:47]
	v_mfma_f32_16x16x32_bf16 v[44:47], v[148:151], v[206:209], v[44:47]
	v_mfma_f32_16x16x32_bf16 v[48:51], v[136:139], v[202:205], v[48:51]
	v_mfma_f32_16x16x32_bf16 v[48:51], v[140:143], v[206:209], v[48:51]
	v_mfma_f32_16x16x32_bf16 v[32:35], v[136:139], v[210:213], v[32:35]
	v_mfma_f32_16x16x32_bf16 v[32:35], v[140:143], v[214:217], v[32:35]
	v_mfma_f32_16x16x32_bf16 v[28:31], v[144:147], v[210:213], v[28:31]
	v_mfma_f32_16x16x32_bf16 v[28:31], v[148:151], v[214:217], v[28:31]
	v_mfma_f32_16x16x32_bf16 v[24:27], v[152:155], v[210:213], v[24:27]
	v_mfma_f32_16x16x32_bf16 v[24:27], v[176:179], v[214:217], v[24:27]
	v_mfma_f32_16x16x32_bf16 v[20:23], v[180:183], v[210:213], v[20:23]
	v_mfma_f32_16x16x32_bf16 v[20:23], v[184:187], v[214:217], v[20:23]
	v_mfma_f32_16x16x32_bf16 v[4:7], v[180:183], v[218:221], v[4:7]
	v_mfma_f32_16x16x32_bf16 v[4:7], v[184:187], v[222:225], v[4:7]
	v_mfma_f32_16x16x32_bf16 v[8:11], v[152:155], v[218:221], v[8:11]
	v_mfma_f32_16x16x32_bf16 v[8:11], v[176:179], v[222:225], v[8:11]
	v_mfma_f32_16x16x32_bf16 v[12:15], v[144:147], v[218:221], v[12:15]
	v_mfma_f32_16x16x32_bf16 v[12:15], v[148:151], v[222:225], v[12:15]
	v_mfma_f32_16x16x32_bf16 v[16:19], v[136:139], v[218:221], v[16:19]
	v_mfma_f32_16x16x32_bf16 v[16:19], v[140:143], v[222:225], v[16:19]
	s_setprio 0
	s_barrier
	s_add_i32 s67, s67, 2
	s_cmpk_gt_u32 s67, 0xa9
	s_mov_b64 s[6:7], s[8:9]
	s_cbranch_scc0 .LBB0_1703
	s_and_b64 vcc, exec, s[30:31]
	s_cbranch_vccz .LBB0_1706
	s_barrier
